# all per-phase s_setprio removed from the GEMM loops
# baseline (speedup 1.0000x reference)
; #define PG8_STAGE(bufoff, gbase, voff) do { _Pragma("unroll") for (int _i = 0; _i < 2; ++_i) \
;         __builtin_amdgcn_global_load_lds((const unsigned*)((const char*)(gbase) + (voff)[_i]), (PG8_LAS unsigned*)(lds + (bufoff) + ldsw + _i * 8192), 16, 0, 0); } while (0)
; #define PG8_LDA(dst, b, h) do { _Pragma("unroll") for (int m = 0; m < 4; ++m) _Pragma("unroll") for (int k = 0; k < 2; ++k) dst[m][k] = *(const PG8_LAS bf16x8*)(lds + PG8_SA(b, h) + aoff + m * 2048 + k * 1024); } while (0)
; #define PG8_LDB(dst, b, h) do { _Pragma("unroll") for (int n = 0; n < 2; ++n) _Pragma("unroll") for (int k = 0; k < 2; ++k) dst[n][k] = *(const PG8_LAS bf16x8*)(lds + PG8_SB(b, h) + boff + n * 2048 + k * 1024); } while (0)
; #define PG8_MMA(ai, bj, At, Bt) do { __builtin_amdgcn_s_setprio(1); _Pragma("unroll") for (int m = 0; m < 4; ++m) _Pragma("unroll") for (int n = 0; n < 2; ++n) _Pragma("unroll") for (int k = 0; k < 2; ++k) \
;         acc[ai][bj][m][n] = __builtin_amdgcn_mfma_f32_16x16x32_bf16(Bt[n][k], At[m][k], acc[ai][bj][m][n], 0, 0, 0); __builtin_amdgcn_s_setprio(0); } while (0)
; #define PG8_WAIT_V(n) asm volatile("s_waitcnt vmcnt(" #n ")" ::: "memory")
; #define PG8_WAIT_L(n) asm volatile("s_waitcnt lgkmcnt(" #n ")" ::: "memory")
; #define PG8_BAR __builtin_amdgcn_s_barrier()
; #define PG8_SCHED __builtin_amdgcn_sched_barrier(0)
; template <class Epi, class Sched, bool ALIGN_EPI = false, bool SP2 = false>
; __device__ __forceinline__ void gemm_phase(PG8_LAS unsigned char* lds, const Gemm g, const Sched& S, const Epi& E) {
;     ...
;             const bool last = (t == nt - 2);
;             const char* a1 = cA + (size_t)(t + 1) * kstep;
;             const char* a2 = last ? nA : cA + (size_t)(t + 2) * kstep; const char* b2 = last ? nB : cB + (size_t)(t + 2) * kstep;
;             const char* a3 = a2 + kstep; const char* b3 = b2 + kstep;
;             if (last && has_next) S.a_ready(nxt);
;             if constexpr (SP2) {
;             PG8_LDB(B0, 0, 0); PG8_LDB(B1, 0, 1); PG8_SCHED; PG8_LDA(At, 0, 0); PG8_STAGE(PG8_SA(1, 1), a1 + hstep, voffA);
;             PG8_WAIT_V(8); PG8_WAIT_L(0); PG8_BAR; PG8_MMA(0, 0, At, B0); PG8_MMA(0, 1, At, B1); PG8_BAR; PG8_SCHED;
;             PG8_LDA(At, 0, 1); PG8_STAGE(PG8_SB(0, 0), b2, voffB); PG8_STAGE(PG8_SB(0, 1), b2 + hstep, voffB); PG8_STAGE(PG8_SA(0, 0), a2, voffA);
.LBB0_148:
	s_add_u32 s8, s6, 0xfff80080
	s_addc_u32 s9, s7, -1
	s_add_i32 s39, 0, 0x10000
	s_cmp_eq_u32 s38, 28
	s_cselect_b32 s31, s25, s9
	s_cselect_b32 s30, s34, s8
	s_cselect_b32 s9, s23, s37
	s_cselect_b32 s8, s35, s36
	s_add_i32 s58, 0, 0x14000
	v_add_u32_e32 v140, s39, v181
	v_add_u32_e32 v178, s58, v181
	ds_read_b128 v[128:131], v140
	ds_read_b128 v[132:135], v140 offset:1024
	ds_read_b128 v[136:139], v140 offset:2048
	ds_read_b128 v[140:143], v140 offset:3072
	ds_read_b128 v[174:177], v178
	ds_read_b128 v[184:187], v178 offset:1024
	ds_read_b128 v[198:201], v178 offset:2048
	ds_read_b128 v[202:205], v178 offset:3072
	v_lshl_add_u64 v[246:247], s[6:7], 0, v[154:155]
	s_add_i32 m0, s63, 0xc000
	ds_read_b128 v[206:209], v183
	ds_read_b128 v[210:213], v183 offset:1024
	ds_read_b128 v[214:217], v183 offset:2048
	ds_read_b128 v[218:221], v183 offset:3072
	ds_read_b128 v[222:225], v183 offset:4096
	ds_read_b128 v[226:229], v183 offset:5120
	ds_read_b128 v[238:241], v183 offset:6144
	ds_read_b128 v[242:245], v183 offset:7168
	global_load_lds_dwordx4 v[246:247], off
	v_lshl_add_u64 v[246:247], s[6:7], 0, v[156:157]
	s_add_i32 m0, s63, 0xe000
	s_nop 0
	global_load_lds_dwordx4 v[246:247], off
	s_waitcnt vmcnt(8)
	s_waitcnt lgkmcnt(0)
	s_barrier
	v_mfma_f32_16x16x32_bf16 v[124:127], v[128:131], v[206:209], v[124:127]
	v_mfma_f32_16x16x32_bf16 v[120:123], v[136:139], v[206:209], v[120:123]
	v_mfma_f32_16x16x32_bf16 v[108:111], v[128:131], v[214:217], v[108:111]
	v_mfma_f32_16x16x32_bf16 v[104:107], v[136:139], v[214:217], v[104:107]
	v_mfma_f32_16x16x32_bf16 v[92:95], v[128:131], v[222:225], v[92:95]
	v_mfma_f32_16x16x32_bf16 v[88:91], v[136:139], v[222:225], v[88:91]
	v_mfma_f32_16x16x32_bf16 v[76:79], v[128:131], v[238:241], v[76:79]
	v_mfma_f32_16x16x32_bf16 v[72:75], v[136:139], v[238:241], v[72:75]
	v_mfma_f32_16x16x32_bf16 v[124:127], v[132:135], v[210:213], v[124:127]
	v_mfma_f32_16x16x32_bf16 v[120:123], v[140:143], v[210:213], v[120:123]
	v_mfma_f32_16x16x32_bf16 v[108:111], v[132:135], v[218:221], v[108:111]
	v_mfma_f32_16x16x32_bf16 v[104:107], v[140:143], v[218:221], v[104:107]
	v_mfma_f32_16x16x32_bf16 v[92:95], v[132:135], v[226:229], v[92:95]
	v_mfma_f32_16x16x32_bf16 v[88:91], v[140:143], v[226:229], v[88:91]
	v_mfma_f32_16x16x32_bf16 v[76:79], v[132:135], v[242:245], v[76:79]
	v_mfma_f32_16x16x32_bf16 v[72:75], v[140:143], v[242:245], v[72:75]
	v_mfma_f32_16x16x32_bf16 v[116:119], v[174:177], v[206:209], v[116:119]
	v_mfma_f32_16x16x32_bf16 v[112:115], v[198:201], v[206:209], v[112:115]
	v_mfma_f32_16x16x32_bf16 v[100:103], v[174:177], v[214:217], v[100:103]
	v_mfma_f32_16x16x32_bf16 v[96:99], v[198:201], v[214:217], v[96:99]
	v_mfma_f32_16x16x32_bf16 v[84:87], v[174:177], v[222:225], v[84:87]
	v_mfma_f32_16x16x32_bf16 v[80:83], v[198:201], v[222:225], v[80:83]
	v_mfma_f32_16x16x32_bf16 v[68:71], v[174:177], v[238:241], v[68:71]
	v_mfma_f32_16x16x32_bf16 v[64:67], v[198:201], v[238:241], v[64:67]
	v_mfma_f32_16x16x32_bf16 v[116:119], v[184:187], v[210:213], v[116:119]
	v_mfma_f32_16x16x32_bf16 v[112:115], v[202:205], v[210:213], v[112:115]
	v_mfma_f32_16x16x32_bf16 v[100:103], v[184:187], v[218:221], v[100:103]
	v_mfma_f32_16x16x32_bf16 v[96:99], v[202:205], v[218:221], v[96:99]
	v_mfma_f32_16x16x32_bf16 v[84:87], v[184:187], v[226:229], v[84:87]
	v_mfma_f32_16x16x32_bf16 v[80:83], v[202:205], v[226:229], v[80:83]
	v_mfma_f32_16x16x32_bf16 v[68:71], v[184:187], v[242:245], v[68:71]
	v_mfma_f32_16x16x32_bf16 v[64:67], v[202:205], v[242:245], v[64:67]
	s_barrier
	s_add_i32 s39, s39, s45
	v_lshl_add_u64 v[246:247], s[8:9], 0, v[148:149]
	s_mov_b32 m0, s39
	ds_read_b128 v[206:209], v183 offset:16384
	ds_read_b128 v[210:213], v183 offset:17408
	ds_read_b128 v[214:217], v183 offset:18432
	ds_read_b128 v[218:221], v183 offset:19456
	ds_read_b128 v[222:225], v183 offset:20480
	ds_read_b128 v[226:229], v183 offset:21504
	ds_read_b128 v[238:241], v183 offset:22528
	ds_read_b128 v[242:245], v183 offset:23552
	global_load_lds_dwordx4 v[246:247], off
	s_add_i32 m0, s39, 0x2000
	s_add_u32 s88, s8, 0x80000
	v_lshl_add_u64 v[248:249], s[8:9], 0, v[144:145]
	s_addc_u32 s89, s9, 0
	s_add_i32 s39, s58, s45
	global_load_lds_dwordx4 v[248:249], off
	v_lshl_add_u64 v[250:251], s[88:89], 0, v[148:149]
	s_mov_b32 m0, s39
	v_lshl_add_u64 v[252:253], s[30:31], 0, v[146:147]
	global_load_lds_dwordx4 v[250:251], off
	v_lshl_add_u64 v[250:251], s[88:89], 0, v[144:145]
	s_add_i32 m0, s39, 0x2000
	s_nop 0
	global_load_lds_dwordx4 v[250:251], off
	v_lshl_add_u64 v[250:251], s[30:31], 0, v[150:151]
	s_mov_b32 m0, s63
	s_nop 0
	global_load_lds_dwordx4 v[250:251], off
	s_mov_b32 m0, s66
	s_nop 0
	global_load_lds_dwordx4 v[252:253], off
	s_waitcnt vmcnt(8)
	s_waitcnt lgkmcnt(0)
	s_barrier
; #define PG8_STAGE(bufoff, gbase, voff) do { _Pragma("unroll") for (int _i = 0; _i < 2; ++_i) \
;         __builtin_amdgcn_global_load_lds((const unsigned*)((const char*)(gbase) + (voff)[_i]), (PG8_LAS unsigned*)(lds + (bufoff) + ldsw + _i * 8192), 16, 0, 0); } while (0)
; #define PG8_LDA(dst, b, h) do { _Pragma("unroll") for (int m = 0; m < 4; ++m) _Pragma("unroll") for (int k = 0; k < 2; ++k) dst[m][k] = *(const PG8_LAS bf16x8*)(lds + PG8_SA(b, h) + aoff + m * 2048 + k * 1024); } while (0)
; #define PG8_LDB(dst, b, h) do { _Pragma("unroll") for (int n = 0; n < 2; ++n) _Pragma("unroll") for (int k = 0; k < 2; ++k) dst[n][k] = *(const PG8_LAS bf16x8*)(lds + PG8_SB(b, h) + boff + n * 2048 + k * 1024); } while (0)
; #define PG8_MMA(ai, bj, At, Bt) do { __builtin_amdgcn_s_setprio(1); _Pragma("unroll") for (int m = 0; m < 4; ++m) _Pragma("unroll") for (int n = 0; n < 2; ++n) _Pragma("unroll") for (int k = 0; k < 2; ++k) \
;         acc[ai][bj][m][n] = __builtin_amdgcn_mfma_f32_16x16x32_bf16(Bt[n][k], At[m][k], acc[ai][bj][m][n], 0, 0, 0); __builtin_amdgcn_s_setprio(0); } while (0)
; #define PG8_WAIT_V(n) asm volatile("s_waitcnt vmcnt(" #n ")" ::: "memory")
; #define PG8_WAIT_L(n) asm volatile("s_waitcnt lgkmcnt(" #n ")" ::: "memory")
; #define PG8_BAR __builtin_amdgcn_s_barrier()
; #define PG8_SCHED __builtin_amdgcn_sched_barrier(0)
; template <class Epi, class Sched, bool ALIGN_EPI = false, bool SP2 = false>
; __device__ __forceinline__ void gemm_phase(PG8_LAS unsigned char* lds, const Gemm g, const Sched& S, const Epi& E) {
;     ...
;             PG8_WAIT_V(8); PG8_WAIT_L(0); PG8_BAR; PG8_MMA(1, 0, At, B0); PG8_MMA(1, 1, At, B1); PG8_BAR; PG8_SCHED;
;             PG8_LDB(B0, 1, 0); PG8_LDB(B1, 1, 1); PG8_SCHED; PG8_LDA(At, 1, 0); PG8_STAGE(PG8_SA(0, 1), a2 + hstep, voffA);
;             PG8_WAIT_V(8); PG8_WAIT_L(0); PG8_BAR; PG8_MMA(0, 0, At, B0); PG8_MMA(0, 1, At, B1); PG8_BAR; PG8_SCHED;
	v_mfma_f32_16x16x32_bf16 v[60:63], v[128:131], v[206:209], v[60:63]
	v_mfma_f32_16x16x32_bf16 v[56:59], v[136:139], v[206:209], v[56:59]
	v_mfma_f32_16x16x32_bf16 v[44:47], v[128:131], v[214:217], v[44:47]
	v_mfma_f32_16x16x32_bf16 v[40:43], v[136:139], v[214:217], v[40:43]
	v_mfma_f32_16x16x32_bf16 v[28:31], v[128:131], v[222:225], v[28:31]
	v_mfma_f32_16x16x32_bf16 v[24:27], v[136:139], v[222:225], v[24:27]
	v_mfma_f32_16x16x32_bf16 v[12:15], v[128:131], v[238:241], v[12:15]
	v_mfma_f32_16x16x32_bf16 v[8:11], v[136:139], v[238:241], v[8:11]
	v_mfma_f32_16x16x32_bf16 v[60:63], v[132:135], v[210:213], v[60:63]
	v_mfma_f32_16x16x32_bf16 v[56:59], v[140:143], v[210:213], v[56:59]
	v_mfma_f32_16x16x32_bf16 v[44:47], v[132:135], v[218:221], v[44:47]
	v_mfma_f32_16x16x32_bf16 v[40:43], v[140:143], v[218:221], v[40:43]
	v_mfma_f32_16x16x32_bf16 v[28:31], v[132:135], v[226:229], v[28:31]
	v_mfma_f32_16x16x32_bf16 v[24:27], v[140:143], v[226:229], v[24:27]
	v_mfma_f32_16x16x32_bf16 v[12:15], v[132:135], v[242:245], v[12:15]
	v_mfma_f32_16x16x32_bf16 v[8:11], v[140:143], v[242:245], v[8:11]
	v_mfma_f32_16x16x32_bf16 v[52:55], v[174:177], v[206:209], v[52:55]
	v_mfma_f32_16x16x32_bf16 v[48:51], v[198:201], v[206:209], v[48:51]
	v_mfma_f32_16x16x32_bf16 v[36:39], v[174:177], v[214:217], v[36:39]
	v_mfma_f32_16x16x32_bf16 v[32:35], v[198:201], v[214:217], v[32:35]
	v_mfma_f32_16x16x32_bf16 v[20:23], v[174:177], v[222:225], v[20:23]
	v_mfma_f32_16x16x32_bf16 v[16:19], v[198:201], v[222:225], v[16:19]
	v_mfma_f32_16x16x32_bf16 v[4:7], v[174:177], v[238:241], v[4:7]
	v_mfma_f32_16x16x32_bf16 v[0:3], v[198:201], v[238:241], v[0:3]
	v_mfma_f32_16x16x32_bf16 v[52:55], v[184:187], v[210:213], v[52:55]
	v_mfma_f32_16x16x32_bf16 v[48:51], v[202:205], v[210:213], v[48:51]
	v_mfma_f32_16x16x32_bf16 v[36:39], v[184:187], v[218:221], v[36:39]
	v_mfma_f32_16x16x32_bf16 v[32:35], v[202:205], v[218:221], v[32:35]
	v_mfma_f32_16x16x32_bf16 v[20:23], v[184:187], v[226:229], v[20:23]
	v_mfma_f32_16x16x32_bf16 v[16:19], v[202:205], v[226:229], v[16:19]
	v_mfma_f32_16x16x32_bf16 v[4:7], v[184:187], v[242:245], v[4:7]
	v_mfma_f32_16x16x32_bf16 v[0:3], v[202:205], v[242:245], v[0:3]
	s_barrier
	s_add_i32 s39, 0, 0x18000
	s_add_i32 s58, 0, 0x1c000
	v_add_u32_e32 v140, s39, v181
	v_add_u32_e32 v178, s58, v181
	ds_read_b128 v[128:131], v140
	ds_read_b128 v[132:135], v140 offset:1024
	ds_read_b128 v[136:139], v140 offset:2048
	ds_read_b128 v[140:143], v140 offset:3072
	ds_read_b128 v[174:177], v178
	ds_read_b128 v[184:187], v178 offset:1024
	ds_read_b128 v[198:201], v178 offset:2048
	ds_read_b128 v[202:205], v178 offset:3072
	s_add_u32 s30, s30, 0x80000
	s_addc_u32 s31, s31, 0
	s_mov_b32 m0, s67
	v_lshl_add_u64 v[232:233], s[30:31], 0, v[150:151]
	ds_read_b128 v[206:209], v183 offset:32768
	ds_read_b128 v[210:213], v183 offset:33792
	ds_read_b128 v[214:217], v183 offset:34816
	ds_read_b128 v[218:221], v183 offset:35840
	ds_read_b128 v[222:225], v183 offset:36864
	ds_read_b128 v[226:229], v183 offset:37888
	ds_read_b128 v[238:241], v183 offset:38912
	ds_read_b128 v[242:245], v183 offset:39936
	global_load_lds_dwordx4 v[232:233], off
	v_lshl_add_u64 v[232:233], s[30:31], 0, v[146:147]
	s_mov_b32 m0, s72
	s_nop 0
	global_load_lds_dwordx4 v[232:233], off
	s_waitcnt vmcnt(8)
	s_waitcnt lgkmcnt(0)
	s_barrier
	v_mfma_f32_16x16x32_bf16 v[124:127], v[128:131], v[206:209], v[124:127]
	v_mfma_f32_16x16x32_bf16 v[120:123], v[136:139], v[206:209], v[120:123]
	v_mfma_f32_16x16x32_bf16 v[108:111], v[128:131], v[214:217], v[108:111]
	v_mfma_f32_16x16x32_bf16 v[104:107], v[136:139], v[214:217], v[104:107]
	v_mfma_f32_16x16x32_bf16 v[92:95], v[128:131], v[222:225], v[92:95]
	v_mfma_f32_16x16x32_bf16 v[88:91], v[136:139], v[222:225], v[88:91]
	v_mfma_f32_16x16x32_bf16 v[76:79], v[128:131], v[238:241], v[76:79]
	v_mfma_f32_16x16x32_bf16 v[72:75], v[136:139], v[238:241], v[72:75]
	v_mfma_f32_16x16x32_bf16 v[124:127], v[132:135], v[210:213], v[124:127]
	v_mfma_f32_16x16x32_bf16 v[120:123], v[140:143], v[210:213], v[120:123]
	v_mfma_f32_16x16x32_bf16 v[108:111], v[132:135], v[218:221], v[108:111]
	v_mfma_f32_16x16x32_bf16 v[104:107], v[140:143], v[218:221], v[104:107]
	v_mfma_f32_16x16x32_bf16 v[92:95], v[132:135], v[226:229], v[92:95]
	v_mfma_f32_16x16x32_bf16 v[88:91], v[140:143], v[226:229], v[88:91]
	v_mfma_f32_16x16x32_bf16 v[76:79], v[132:135], v[242:245], v[76:79]
	v_mfma_f32_16x16x32_bf16 v[72:75], v[140:143], v[242:245], v[72:75]
	v_mfma_f32_16x16x32_bf16 v[116:119], v[174:177], v[206:209], v[116:119]
	v_mfma_f32_16x16x32_bf16 v[112:115], v[198:201], v[206:209], v[112:115]
	v_mfma_f32_16x16x32_bf16 v[100:103], v[174:177], v[214:217], v[100:103]
	v_mfma_f32_16x16x32_bf16 v[96:99], v[198:201], v[214:217], v[96:99]
	v_mfma_f32_16x16x32_bf16 v[84:87], v[174:177], v[222:225], v[84:87]
	v_mfma_f32_16x16x32_bf16 v[80:83], v[198:201], v[222:225], v[80:83]
	v_mfma_f32_16x16x32_bf16 v[68:71], v[174:177], v[238:241], v[68:71]
	v_mfma_f32_16x16x32_bf16 v[64:67], v[198:201], v[238:241], v[64:67]
	v_mfma_f32_16x16x32_bf16 v[116:119], v[184:187], v[210:213], v[116:119]
	v_mfma_f32_16x16x32_bf16 v[112:115], v[202:205], v[210:213], v[112:115]
	v_mfma_f32_16x16x32_bf16 v[100:103], v[184:187], v[218:221], v[100:103]
	v_mfma_f32_16x16x32_bf16 v[96:99], v[202:205], v[218:221], v[96:99]
	v_mfma_f32_16x16x32_bf16 v[84:87], v[184:187], v[226:229], v[84:87]
	v_mfma_f32_16x16x32_bf16 v[80:83], v[202:205], v[226:229], v[80:83]
	v_mfma_f32_16x16x32_bf16 v[68:71], v[184:187], v[242:245], v[68:71]
	v_mfma_f32_16x16x32_bf16 v[64:67], v[202:205], v[242:245], v[64:67]
	s_barrier
; #define PG8_STAGE(bufoff, gbase, voff) do { _Pragma("unroll") for (int _i = 0; _i < 2; ++_i) \
;         __builtin_amdgcn_global_load_lds((const unsigned*)((const char*)(gbase) + (voff)[_i]), (PG8_LAS unsigned*)(lds + (bufoff) + ldsw + _i * 8192), 16, 0, 0); } while (0)
; #define PG8_LDA(dst, b, h) do { _Pragma("unroll") for (int m = 0; m < 4; ++m) _Pragma("unroll") for (int k = 0; k < 2; ++k) dst[m][k] = *(const PG8_LAS bf16x8*)(lds + PG8_SA(b, h) + aoff + m * 2048 + k * 1024); } while (0)
; #define PG8_MMA(ai, bj, At, Bt) do { __builtin_amdgcn_s_setprio(1); _Pragma("unroll") for (int m = 0; m < 4; ++m) _Pragma("unroll") for (int n = 0; n < 2; ++n) _Pragma("unroll") for (int k = 0; k < 2; ++k) \
;         acc[ai][bj][m][n] = __builtin_amdgcn_mfma_f32_16x16x32_bf16(Bt[n][k], At[m][k], acc[ai][bj][m][n], 0, 0, 0); __builtin_amdgcn_s_setprio(0); } while (0)
; #define PG8_WAIT_V(n) asm volatile("s_waitcnt vmcnt(" #n ")" ::: "memory")
; #define PG8_WAIT_L(n) asm volatile("s_waitcnt lgkmcnt(" #n ")" ::: "memory")
; #define PG8_BAR __builtin_amdgcn_s_barrier()
; #define PG8_SCHED __builtin_amdgcn_sched_barrier(0)
; template <class Epi, class Sched, bool ALIGN_EPI = false, bool SP2 = false>
; __device__ __forceinline__ void gemm_phase(PG8_LAS unsigned char* lds, const Gemm g, const Sched& S, const Epi& E) {
;     ...
;             PG8_LDA(At, 1, 1); PG8_STAGE(PG8_SB(1, 0), b3, voffB); PG8_STAGE(PG8_SB(1, 1), b3 + hstep, voffB); PG8_STAGE(PG8_SA(1, 0), a3, voffA);
;             PG8_WAIT_V(8); PG8_WAIT_L(0); PG8_BAR; PG8_MMA(1, 0, At, B0); PG8_MMA(1, 1, At, B1); PG8_BAR; PG8_SCHED;
	s_add_i32 s30, s39, s45
	v_lshl_add_u64 v[232:233], v[246:247], 0, s[78:79]
	s_mov_b32 m0, s30
	ds_read_b128 v[206:209], v183 offset:49152
	ds_read_b128 v[210:213], v183 offset:50176
	ds_read_b128 v[214:217], v183 offset:51200
	ds_read_b128 v[218:221], v183 offset:52224
	ds_read_b128 v[222:225], v183 offset:53248
	ds_read_b128 v[226:229], v183 offset:54272
	ds_read_b128 v[238:241], v183 offset:55296
	ds_read_b128 v[242:245], v183 offset:56320
	global_load_lds_dwordx4 v[232:233], off
	s_add_i32 m0, s30, 0x2000
	s_add_u32 s8, s8, 0x80080
	v_lshl_add_u64 v[232:233], v[248:249], 0, s[78:79]
	s_addc_u32 s9, s9, 0
	s_add_i32 s30, s58, s45
	global_load_lds_dwordx4 v[232:233], off
	v_lshl_add_u64 v[232:233], s[8:9], 0, v[148:149]
	s_mov_b32 m0, s30
	s_nop 0
	global_load_lds_dwordx4 v[232:233], off
	v_lshl_add_u64 v[232:233], s[8:9], 0, v[144:145]
	s_add_i32 m0, s30, 0x2000
	s_nop 0
	global_load_lds_dwordx4 v[232:233], off
	v_lshl_add_u64 v[232:233], v[250:251], 0, s[78:79]
	s_mov_b32 m0, s73
	s_nop 0
	global_load_lds_dwordx4 v[232:233], off
	v_lshl_add_u64 v[232:233], v[252:253], 0, s[78:79]
	s_mov_b32 m0, s74
	s_nop 0
	global_load_lds_dwordx4 v[232:233], off
	s_waitcnt vmcnt(8)
	s_waitcnt lgkmcnt(0)
	s_barrier
	v_mfma_f32_16x16x32_bf16 v[60:63], v[128:131], v[206:209], v[60:63]
	v_mfma_f32_16x16x32_bf16 v[56:59], v[136:139], v[206:209], v[56:59]
	v_mfma_f32_16x16x32_bf16 v[44:47], v[128:131], v[214:217], v[44:47]
	v_mfma_f32_16x16x32_bf16 v[40:43], v[136:139], v[214:217], v[40:43]
	v_mfma_f32_16x16x32_bf16 v[28:31], v[128:131], v[222:225], v[28:31]
	v_mfma_f32_16x16x32_bf16 v[24:27], v[136:139], v[222:225], v[24:27]
	v_mfma_f32_16x16x32_bf16 v[12:15], v[128:131], v[238:241], v[12:15]
	v_mfma_f32_16x16x32_bf16 v[8:11], v[136:139], v[238:241], v[8:11]
	v_mfma_f32_16x16x32_bf16 v[60:63], v[132:135], v[210:213], v[60:63]
	v_mfma_f32_16x16x32_bf16 v[56:59], v[140:143], v[210:213], v[56:59]
	v_mfma_f32_16x16x32_bf16 v[44:47], v[132:135], v[218:221], v[44:47]
	v_mfma_f32_16x16x32_bf16 v[40:43], v[140:143], v[218:221], v[40:43]
	v_mfma_f32_16x16x32_bf16 v[28:31], v[132:135], v[226:229], v[28:31]
	v_mfma_f32_16x16x32_bf16 v[24:27], v[140:143], v[226:229], v[24:27]
	v_mfma_f32_16x16x32_bf16 v[12:15], v[132:135], v[242:245], v[12:15]
	v_mfma_f32_16x16x32_bf16 v[8:11], v[140:143], v[242:245], v[8:11]
	v_mfma_f32_16x16x32_bf16 v[52:55], v[174:177], v[206:209], v[52:55]
	v_mfma_f32_16x16x32_bf16 v[48:51], v[198:201], v[206:209], v[48:51]
	v_mfma_f32_16x16x32_bf16 v[36:39], v[174:177], v[214:217], v[36:39]
	v_mfma_f32_16x16x32_bf16 v[32:35], v[198:201], v[214:217], v[32:35]
	v_mfma_f32_16x16x32_bf16 v[20:23], v[174:177], v[222:225], v[20:23]
	v_mfma_f32_16x16x32_bf16 v[16:19], v[198:201], v[222:225], v[16:19]
	v_mfma_f32_16x16x32_bf16 v[4:7], v[174:177], v[238:241], v[4:7]
	v_mfma_f32_16x16x32_bf16 v[0:3], v[198:201], v[238:241], v[0:3]
	v_mfma_f32_16x16x32_bf16 v[52:55], v[184:187], v[210:213], v[52:55]
	v_mfma_f32_16x16x32_bf16 v[48:51], v[202:205], v[210:213], v[48:51]
	v_mfma_f32_16x16x32_bf16 v[36:39], v[184:187], v[218:221], v[36:39]
	v_mfma_f32_16x16x32_bf16 v[32:35], v[202:205], v[218:221], v[32:35]
	v_mfma_f32_16x16x32_bf16 v[20:23], v[184:187], v[226:229], v[20:23]
	v_mfma_f32_16x16x32_bf16 v[16:19], v[202:205], v[226:229], v[16:19]
	v_mfma_f32_16x16x32_bf16 v[4:7], v[184:187], v[242:245], v[4:7]
	v_mfma_f32_16x16x32_bf16 v[0:3], v[202:205], v[242:245], v[0:3]
	s_barrier
	s_add_i32 s38, s38, 2
	s_add_u32 s6, s6, 0x100
	s_addc_u32 s7, s7, 0
	s_add_u32 s36, s36, 0x100
	s_addc_u32 s37, s37, 0
	s_cmp_gt_u32 s38, 29
	s_cbranch_scc0 .LBB0_148
	s_and_b64 vcc, exec, s[20:21]
	s_cbranch_vccz .LBB0_151
	s_barrier

; #define PG8_STAGE(bufoff, gbase, voff) do { _Pragma("unroll") for (int _i = 0; _i < 2; ++_i) \
;         __builtin_amdgcn_global_load_lds((const unsigned*)((const char*)(gbase) + (voff)[_i]), (PG8_LAS unsigned*)(lds + (bufoff) + ldsw + _i * 8192), 16, 0, 0); } while (0)
; #define PG8_LDA(dst, b, h) do { _Pragma("unroll") for (int m = 0; m < 4; ++m) _Pragma("unroll") for (int k = 0; k < 2; ++k) dst[m][k] = *(const PG8_LAS bf16x8*)(lds + PG8_SA(b, h) + aoff + m * 2048 + k * 1024); } while (0)
; #define PG8_LDB(dst, b, h) do { _Pragma("unroll") for (int n = 0; n < 2; ++n) _Pragma("unroll") for (int k = 0; k < 2; ++k) dst[n][k] = *(const PG8_LAS bf16x8*)(lds + PG8_SB(b, h) + boff + n * 2048 + k * 1024); } while (0)
; #define PG8_MMA(ai, bj, At, Bt) do { __builtin_amdgcn_s_setprio(1); _Pragma("unroll") for (int m = 0; m < 4; ++m) _Pragma("unroll") for (int n = 0; n < 2; ++n) _Pragma("unroll") for (int k = 0; k < 2; ++k) \
;         acc[ai][bj][m][n] = __builtin_amdgcn_mfma_f32_16x16x32_bf16(Bt[n][k], At[m][k], acc[ai][bj][m][n], 0, 0, 0); __builtin_amdgcn_s_setprio(0); } while (0)
; #define PG8_WAIT_V(n) asm volatile("s_waitcnt vmcnt(" #n ")" ::: "memory")
; #define PG8_WAIT_L(n) asm volatile("s_waitcnt lgkmcnt(" #n ")" ::: "memory")
; template <class Epi, class Sched, bool ALIGN_EPI = false, bool SP2 = false>
; __device__ __forceinline__ void gemm_phase(PG8_LAS unsigned char* lds, const Gemm g, const Sched& S, const Epi& E) {
;     ...
;             const bool last = (t == nt - 2);
;             const char* a1 = cA + (size_t)(t + 1) * kstep;
;             const char* a2 = last ? nA : cA + (size_t)(t + 2) * kstep; const char* b2 = last ? nB : cB + (size_t)(t + 2) * kstep;
;             const char* a3 = a2 + kstep; const char* b3 = b2 + kstep;
;             if (last && has_next) S.a_ready(nxt);
;             if constexpr (SP2) {
;             PG8_LDB(B0, 0, 0); PG8_LDB(B1, 0, 1); PG8_SCHED; PG8_LDA(At, 0, 0); PG8_STAGE(PG8_SA(1, 1), a1 + hstep, voffA);
;             PG8_WAIT_V(8); PG8_WAIT_L(0); PG8_BAR; PG8_MMA(0, 0, At, B0); PG8_MMA(0, 1, At, B1); PG8_BAR; PG8_SCHED;
;             PG8_LDA(At, 0, 1); PG8_STAGE(PG8_SB(0, 0), b2, voffB); PG8_STAGE(PG8_SB(0, 1), b2 + hstep, voffB); PG8_STAGE(PG8_SA(0, 0), a2, voffA);
;             PG8_WAIT_V(8); PG8_WAIT_L(0); PG8_BAR; PG8_MMA(1, 0, At, B0); PG8_MMA(1, 1, At, B1); PG8_BAR; PG8_SCHED;
.LBB0_424:
	s_add_u32 s8, s6, 0xfffc0080
	s_addc_u32 s9, s7, -1
	s_add_i32 s60, 0, 0x10000
	s_cmp_eq_u32 s58, 12
	s_cselect_b32 s25, s17, s9
	s_cselect_b32 s24, s38, s8
	s_cselect_b32 s9, s19, s52
	s_cselect_b32 s8, s39, s45
	s_add_i32 s62, 0, 0x14000
	v_add_u32_e32 v140, s60, v201
	v_add_u32_e32 v156, s62, v201
	ds_read_b128 v[128:131], v140
	ds_read_b128 v[132:135], v140 offset:1024
	ds_read_b128 v[136:139], v140 offset:2048
	ds_read_b128 v[140:143], v140 offset:3072
	ds_read_b128 v[144:147], v156
	ds_read_b128 v[148:151], v156 offset:1024
	ds_read_b128 v[152:155], v156 offset:2048
	ds_read_b128 v[156:159], v156 offset:3072
	v_lshl_add_u64 v[198:199], s[6:7], 0, v[168:169]
	s_add_i32 m0, s31, 0xc000
	ds_read_b128 v[172:175], v203
	ds_read_b128 v[176:179], v203 offset:1024
	ds_read_b128 v[180:183], v203 offset:2048
	ds_read_b128 v[184:187], v203 offset:3072
	ds_read_b128 v[204:207], v203 offset:4096
	ds_read_b128 v[208:211], v203 offset:5120
	ds_read_b128 v[212:215], v203 offset:6144
	ds_read_b128 v[216:219], v203 offset:7168
	global_load_lds_dwordx4 v[198:199], off
	v_lshl_add_u64 v[198:199], s[6:7], 0, v[170:171]
	s_add_i32 m0, s31, 0xe000
	s_nop 0
	global_load_lds_dwordx4 v[198:199], off
	s_waitcnt vmcnt(8)
	s_waitcnt lgkmcnt(0)
	s_barrier
	v_mfma_f32_16x16x32_bf16 v[124:127], v[128:131], v[172:175], v[124:127]
	v_mfma_f32_16x16x32_bf16 v[120:123], v[136:139], v[172:175], v[120:123]
	v_mfma_f32_16x16x32_bf16 v[116:119], v[128:131], v[180:183], v[116:119]
	v_mfma_f32_16x16x32_bf16 v[112:115], v[136:139], v[180:183], v[112:115]
	v_mfma_f32_16x16x32_bf16 v[108:111], v[128:131], v[204:207], v[108:111]
	v_mfma_f32_16x16x32_bf16 v[104:107], v[136:139], v[204:207], v[104:107]
	v_mfma_f32_16x16x32_bf16 v[100:103], v[128:131], v[212:215], v[100:103]
	v_mfma_f32_16x16x32_bf16 v[96:99], v[136:139], v[212:215], v[96:99]
	v_mfma_f32_16x16x32_bf16 v[124:127], v[132:135], v[176:179], v[124:127]
	v_mfma_f32_16x16x32_bf16 v[120:123], v[140:143], v[176:179], v[120:123]
	v_mfma_f32_16x16x32_bf16 v[116:119], v[132:135], v[184:187], v[116:119]
	v_mfma_f32_16x16x32_bf16 v[112:115], v[140:143], v[184:187], v[112:115]
	v_mfma_f32_16x16x32_bf16 v[108:111], v[132:135], v[208:211], v[108:111]
	v_mfma_f32_16x16x32_bf16 v[104:107], v[140:143], v[208:211], v[104:107]
	v_mfma_f32_16x16x32_bf16 v[100:103], v[132:135], v[216:219], v[100:103]
	v_mfma_f32_16x16x32_bf16 v[96:99], v[140:143], v[216:219], v[96:99]
	v_mfma_f32_16x16x32_bf16 v[92:95], v[144:147], v[172:175], v[92:95]
	v_mfma_f32_16x16x32_bf16 v[88:91], v[152:155], v[172:175], v[88:91]
	v_mfma_f32_16x16x32_bf16 v[84:87], v[144:147], v[180:183], v[84:87]
	v_mfma_f32_16x16x32_bf16 v[80:83], v[152:155], v[180:183], v[80:83]
	v_mfma_f32_16x16x32_bf16 v[76:79], v[144:147], v[204:207], v[76:79]
	v_mfma_f32_16x16x32_bf16 v[72:75], v[152:155], v[204:207], v[72:75]
	v_mfma_f32_16x16x32_bf16 v[68:71], v[144:147], v[212:215], v[68:71]
	v_mfma_f32_16x16x32_bf16 v[64:67], v[152:155], v[212:215], v[64:67]
	v_mfma_f32_16x16x32_bf16 v[92:95], v[148:151], v[176:179], v[92:95]
	v_mfma_f32_16x16x32_bf16 v[88:91], v[156:159], v[176:179], v[88:91]
	v_mfma_f32_16x16x32_bf16 v[84:87], v[148:151], v[184:187], v[84:87]
	v_mfma_f32_16x16x32_bf16 v[80:83], v[156:159], v[184:187], v[80:83]
	v_mfma_f32_16x16x32_bf16 v[76:79], v[148:151], v[208:211], v[76:79]
	v_mfma_f32_16x16x32_bf16 v[72:75], v[156:159], v[208:211], v[72:75]
	v_mfma_f32_16x16x32_bf16 v[68:71], v[148:151], v[216:219], v[68:71]
	v_mfma_f32_16x16x32_bf16 v[64:67], v[156:159], v[216:219], v[64:67]
	s_barrier
	s_add_i32 s60, s60, s30
	v_lshl_add_u64 v[198:199], s[8:9], 0, v[164:165]
	s_mov_b32 m0, s60
	ds_read_b128 v[172:175], v203 offset:16384
	ds_read_b128 v[176:179], v203 offset:17408
	ds_read_b128 v[180:183], v203 offset:18432
	ds_read_b128 v[184:187], v203 offset:19456
	ds_read_b128 v[204:207], v203 offset:20480
	ds_read_b128 v[208:211], v203 offset:21504
	ds_read_b128 v[212:215], v203 offset:22528
	ds_read_b128 v[216:219], v203 offset:23552
	global_load_lds_dwordx4 v[198:199], off
	s_add_i32 m0, s60, 0x2000
	s_add_u32 s60, s8, 0x40000
	v_lshl_add_u64 v[220:221], s[8:9], 0, v[160:161]
	s_addc_u32 s61, s9, 0
	s_add_i32 s62, s62, s30
	global_load_lds_dwordx4 v[220:221], off
	v_lshl_add_u64 v[222:223], s[60:61], 0, v[164:165]
	s_mov_b32 m0, s62
	v_lshl_add_u64 v[224:225], s[24:25], 0, v[162:163]
	global_load_lds_dwordx4 v[222:223], off
	v_lshl_add_u64 v[222:223], s[60:61], 0, v[160:161]
	s_add_i32 m0, s62, 0x2000
	s_nop 0
	global_load_lds_dwordx4 v[222:223], off
	v_lshl_add_u64 v[222:223], s[24:25], 0, v[166:167]
	s_mov_b32 m0, s31
	s_nop 0
	global_load_lds_dwordx4 v[222:223], off
	s_mov_b32 m0, s34
	s_nop 0
	global_load_lds_dwordx4 v[224:225], off
	s_waitcnt vmcnt(8)
	s_waitcnt lgkmcnt(0)
	s_barrier
; #define PG8_STAGE(bufoff, gbase, voff) do { _Pragma("unroll") for (int _i = 0; _i < 2; ++_i) \
;         __builtin_amdgcn_global_load_lds((const unsigned*)((const char*)(gbase) + (voff)[_i]), (PG8_LAS unsigned*)(lds + (bufoff) + ldsw + _i * 8192), 16, 0, 0); } while (0)
; #define PG8_LDA(dst, b, h) do { _Pragma("unroll") for (int m = 0; m < 4; ++m) _Pragma("unroll") for (int k = 0; k < 2; ++k) dst[m][k] = *(const PG8_LAS bf16x8*)(lds + PG8_SA(b, h) + aoff + m * 2048 + k * 1024); } while (0)
; #define PG8_LDB(dst, b, h) do { _Pragma("unroll") for (int n = 0; n < 2; ++n) _Pragma("unroll") for (int k = 0; k < 2; ++k) dst[n][k] = *(const PG8_LAS bf16x8*)(lds + PG8_SB(b, h) + boff + n * 2048 + k * 1024); } while (0)
; #define PG8_MMA(ai, bj, At, Bt) do { __builtin_amdgcn_s_setprio(1); _Pragma("unroll") for (int m = 0; m < 4; ++m) _Pragma("unroll") for (int n = 0; n < 2; ++n) _Pragma("unroll") for (int k = 0; k < 2; ++k) \
;         acc[ai][bj][m][n] = __builtin_amdgcn_mfma_f32_16x16x32_bf16(Bt[n][k], At[m][k], acc[ai][bj][m][n], 0, 0, 0); __builtin_amdgcn_s_setprio(0); } while (0)
; #define PG8_WAIT_V(n) asm volatile("s_waitcnt vmcnt(" #n ")" ::: "memory")
; #define PG8_WAIT_L(n) asm volatile("s_waitcnt lgkmcnt(" #n ")" ::: "memory")
; #define PG8_BAR __builtin_amdgcn_s_barrier()
; #define PG8_SCHED __builtin_amdgcn_sched_barrier(0)
; template <class Epi, class Sched, bool ALIGN_EPI = false, bool SP2 = false>
; __device__ __forceinline__ void gemm_phase(PG8_LAS unsigned char* lds, const Gemm g, const Sched& S, const Epi& E) {
;     ...
;             PG8_WAIT_V(8); PG8_WAIT_L(0); PG8_BAR; PG8_MMA(1, 0, At, B0); PG8_MMA(1, 1, At, B1); PG8_BAR; PG8_SCHED;
;             PG8_LDB(B0, 1, 0); PG8_LDB(B1, 1, 1); PG8_SCHED; PG8_LDA(At, 1, 0); PG8_STAGE(PG8_SA(0, 1), a2 + hstep, voffA);
;             PG8_WAIT_V(8); PG8_WAIT_L(0); PG8_BAR; PG8_MMA(0, 0, At, B0); PG8_MMA(0, 1, At, B1); PG8_BAR; PG8_SCHED;
	v_mfma_f32_16x16x32_bf16 v[60:63], v[128:131], v[172:175], v[60:63]
	v_mfma_f32_16x16x32_bf16 v[56:59], v[136:139], v[172:175], v[56:59]
	v_mfma_f32_16x16x32_bf16 v[52:55], v[128:131], v[180:183], v[52:55]
	v_mfma_f32_16x16x32_bf16 v[48:51], v[136:139], v[180:183], v[48:51]
	v_mfma_f32_16x16x32_bf16 v[44:47], v[128:131], v[204:207], v[44:47]
	v_mfma_f32_16x16x32_bf16 v[40:43], v[136:139], v[204:207], v[40:43]
	v_mfma_f32_16x16x32_bf16 v[36:39], v[128:131], v[212:215], v[36:39]
	v_mfma_f32_16x16x32_bf16 v[32:35], v[136:139], v[212:215], v[32:35]
	v_mfma_f32_16x16x32_bf16 v[60:63], v[132:135], v[176:179], v[60:63]
	v_mfma_f32_16x16x32_bf16 v[56:59], v[140:143], v[176:179], v[56:59]
	v_mfma_f32_16x16x32_bf16 v[52:55], v[132:135], v[184:187], v[52:55]
	v_mfma_f32_16x16x32_bf16 v[48:51], v[140:143], v[184:187], v[48:51]
	v_mfma_f32_16x16x32_bf16 v[44:47], v[132:135], v[208:211], v[44:47]
	v_mfma_f32_16x16x32_bf16 v[40:43], v[140:143], v[208:211], v[40:43]
	v_mfma_f32_16x16x32_bf16 v[36:39], v[132:135], v[216:219], v[36:39]
	v_mfma_f32_16x16x32_bf16 v[32:35], v[140:143], v[216:219], v[32:35]
	v_mfma_f32_16x16x32_bf16 v[28:31], v[144:147], v[172:175], v[28:31]
	v_mfma_f32_16x16x32_bf16 v[24:27], v[152:155], v[172:175], v[24:27]
	v_mfma_f32_16x16x32_bf16 v[20:23], v[144:147], v[180:183], v[20:23]
	v_mfma_f32_16x16x32_bf16 v[16:19], v[152:155], v[180:183], v[16:19]
	v_mfma_f32_16x16x32_bf16 v[12:15], v[144:147], v[204:207], v[12:15]
	v_mfma_f32_16x16x32_bf16 v[8:11], v[152:155], v[204:207], v[8:11]
	v_mfma_f32_16x16x32_bf16 v[4:7], v[144:147], v[212:215], v[4:7]
	v_mfma_f32_16x16x32_bf16 v[0:3], v[152:155], v[212:215], v[0:3]
	v_mfma_f32_16x16x32_bf16 v[28:31], v[148:151], v[176:179], v[28:31]
	v_mfma_f32_16x16x32_bf16 v[24:27], v[156:159], v[176:179], v[24:27]
	v_mfma_f32_16x16x32_bf16 v[20:23], v[148:151], v[184:187], v[20:23]
	v_mfma_f32_16x16x32_bf16 v[16:19], v[156:159], v[184:187], v[16:19]
	v_mfma_f32_16x16x32_bf16 v[12:15], v[148:151], v[208:211], v[12:15]
	v_mfma_f32_16x16x32_bf16 v[8:11], v[156:159], v[208:211], v[8:11]
	v_mfma_f32_16x16x32_bf16 v[4:7], v[148:151], v[216:219], v[4:7]
	v_mfma_f32_16x16x32_bf16 v[0:3], v[156:159], v[216:219], v[0:3]
	s_barrier
	s_add_i32 s60, 0, 0x18000
	s_add_i32 s61, 0, 0x1c000
	v_add_u32_e32 v140, s60, v201
	v_add_u32_e32 v156, s61, v201
	ds_read_b128 v[128:131], v140
	ds_read_b128 v[132:135], v140 offset:1024
	ds_read_b128 v[136:139], v140 offset:2048
	ds_read_b128 v[140:143], v140 offset:3072
	ds_read_b128 v[144:147], v156
	ds_read_b128 v[148:151], v156 offset:1024
	ds_read_b128 v[152:155], v156 offset:2048
	ds_read_b128 v[156:159], v156 offset:3072
	s_add_u32 s24, s24, 0x40000
	s_addc_u32 s25, s25, 0
	s_mov_b32 m0, s35
	v_lshl_add_u64 v[226:227], s[24:25], 0, v[166:167]
	ds_read_b128 v[172:175], v203 offset:32768
	ds_read_b128 v[176:179], v203 offset:33792
	ds_read_b128 v[180:183], v203 offset:34816
	ds_read_b128 v[184:187], v203 offset:35840
	ds_read_b128 v[204:207], v203 offset:36864
	ds_read_b128 v[208:211], v203 offset:37888
	ds_read_b128 v[212:215], v203 offset:38912
	ds_read_b128 v[216:219], v203 offset:39936
	global_load_lds_dwordx4 v[226:227], off
	v_lshl_add_u64 v[226:227], s[24:25], 0, v[162:163]
	s_mov_b32 m0, s36
	s_nop 0
	global_load_lds_dwordx4 v[226:227], off
	s_waitcnt vmcnt(8)
	s_waitcnt lgkmcnt(0)
	s_barrier
	v_mfma_f32_16x16x32_bf16 v[124:127], v[128:131], v[172:175], v[124:127]
	v_mfma_f32_16x16x32_bf16 v[120:123], v[136:139], v[172:175], v[120:123]
	v_mfma_f32_16x16x32_bf16 v[116:119], v[128:131], v[180:183], v[116:119]
	v_mfma_f32_16x16x32_bf16 v[112:115], v[136:139], v[180:183], v[112:115]
	v_mfma_f32_16x16x32_bf16 v[108:111], v[128:131], v[204:207], v[108:111]
	v_mfma_f32_16x16x32_bf16 v[104:107], v[136:139], v[204:207], v[104:107]
	v_mfma_f32_16x16x32_bf16 v[100:103], v[128:131], v[212:215], v[100:103]
	v_mfma_f32_16x16x32_bf16 v[96:99], v[136:139], v[212:215], v[96:99]
	v_mfma_f32_16x16x32_bf16 v[124:127], v[132:135], v[176:179], v[124:127]
	v_mfma_f32_16x16x32_bf16 v[120:123], v[140:143], v[176:179], v[120:123]
	v_mfma_f32_16x16x32_bf16 v[116:119], v[132:135], v[184:187], v[116:119]
	v_mfma_f32_16x16x32_bf16 v[112:115], v[140:143], v[184:187], v[112:115]
	v_mfma_f32_16x16x32_bf16 v[108:111], v[132:135], v[208:211], v[108:111]
	v_mfma_f32_16x16x32_bf16 v[104:107], v[140:143], v[208:211], v[104:107]
	v_mfma_f32_16x16x32_bf16 v[100:103], v[132:135], v[216:219], v[100:103]
	v_mfma_f32_16x16x32_bf16 v[96:99], v[140:143], v[216:219], v[96:99]
	v_mfma_f32_16x16x32_bf16 v[92:95], v[144:147], v[172:175], v[92:95]
	v_mfma_f32_16x16x32_bf16 v[88:91], v[152:155], v[172:175], v[88:91]
	v_mfma_f32_16x16x32_bf16 v[84:87], v[144:147], v[180:183], v[84:87]
	v_mfma_f32_16x16x32_bf16 v[80:83], v[152:155], v[180:183], v[80:83]
	v_mfma_f32_16x16x32_bf16 v[76:79], v[144:147], v[204:207], v[76:79]
	v_mfma_f32_16x16x32_bf16 v[72:75], v[152:155], v[204:207], v[72:75]
	v_mfma_f32_16x16x32_bf16 v[68:71], v[144:147], v[212:215], v[68:71]
	v_mfma_f32_16x16x32_bf16 v[64:67], v[152:155], v[212:215], v[64:67]
	v_mfma_f32_16x16x32_bf16 v[92:95], v[148:151], v[176:179], v[92:95]
	v_mfma_f32_16x16x32_bf16 v[88:91], v[156:159], v[176:179], v[88:91]
	v_mfma_f32_16x16x32_bf16 v[84:87], v[148:151], v[184:187], v[84:87]
	v_mfma_f32_16x16x32_bf16 v[80:83], v[156:159], v[184:187], v[80:83]
	v_mfma_f32_16x16x32_bf16 v[76:79], v[148:151], v[208:211], v[76:79]
	v_mfma_f32_16x16x32_bf16 v[72:75], v[156:159], v[208:211], v[72:75]
	v_mfma_f32_16x16x32_bf16 v[68:71], v[148:151], v[216:219], v[68:71]
	v_mfma_f32_16x16x32_bf16 v[64:67], v[156:159], v[216:219], v[64:67]
	s_barrier
; #define PG8_STAGE(bufoff, gbase, voff) do { _Pragma("unroll") for (int _i = 0; _i < 2; ++_i) \
;         __builtin_amdgcn_global_load_lds((const unsigned*)((const char*)(gbase) + (voff)[_i]), (PG8_LAS unsigned*)(lds + (bufoff) + ldsw + _i * 8192), 16, 0, 0); } while (0)
; #define PG8_LDA(dst, b, h) do { _Pragma("unroll") for (int m = 0; m < 4; ++m) _Pragma("unroll") for (int k = 0; k < 2; ++k) dst[m][k] = *(const PG8_LAS bf16x8*)(lds + PG8_SA(b, h) + aoff + m * 2048 + k * 1024); } while (0)
; #define PG8_MMA(ai, bj, At, Bt) do { __builtin_amdgcn_s_setprio(1); _Pragma("unroll") for (int m = 0; m < 4; ++m) _Pragma("unroll") for (int n = 0; n < 2; ++n) _Pragma("unroll") for (int k = 0; k < 2; ++k) \
;         acc[ai][bj][m][n] = __builtin_amdgcn_mfma_f32_16x16x32_bf16(Bt[n][k], At[m][k], acc[ai][bj][m][n], 0, 0, 0); __builtin_amdgcn_s_setprio(0); } while (0)
; #define PG8_WAIT_V(n) asm volatile("s_waitcnt vmcnt(" #n ")" ::: "memory")
; #define PG8_WAIT_L(n) asm volatile("s_waitcnt lgkmcnt(" #n ")" ::: "memory")
; #define PG8_BAR __builtin_amdgcn_s_barrier()
; #define PG8_SCHED __builtin_amdgcn_sched_barrier(0)
; template <class Epi, class Sched, bool ALIGN_EPI = false, bool SP2 = false>
; __device__ __forceinline__ void gemm_phase(PG8_LAS unsigned char* lds, const Gemm g, const Sched& S, const Epi& E) {
;     ...
;             PG8_LDA(At, 1, 1); PG8_STAGE(PG8_SB(1, 0), b3, voffB); PG8_STAGE(PG8_SB(1, 1), b3 + hstep, voffB); PG8_STAGE(PG8_SA(1, 0), a3, voffA);
;             PG8_WAIT_V(8); PG8_WAIT_L(0); PG8_BAR; PG8_MMA(1, 0, At, B0); PG8_MMA(1, 1, At, B1); PG8_BAR; PG8_SCHED;
;     ...
;         if constexpr (ALIGN_EPI) { if (wr == 0) PG8_BAR; }
	s_add_i32 s24, s60, s30
	v_lshl_add_u64 v[198:199], v[198:199], 0, s[78:79]
	s_mov_b32 m0, s24
	ds_read_b128 v[172:175], v203 offset:49152
	ds_read_b128 v[176:179], v203 offset:50176
	ds_read_b128 v[180:183], v203 offset:51200
	ds_read_b128 v[184:187], v203 offset:52224
	ds_read_b128 v[204:207], v203 offset:53248
	ds_read_b128 v[208:211], v203 offset:54272
	ds_read_b128 v[212:215], v203 offset:55296
	ds_read_b128 v[216:219], v203 offset:56320
	global_load_lds_dwordx4 v[198:199], off
	s_add_i32 m0, s24, 0x2000
	s_add_u32 s8, s8, 0x40080
	v_lshl_add_u64 v[198:199], v[220:221], 0, s[78:79]
	s_addc_u32 s9, s9, 0
	s_add_i32 s24, s61, s30
	global_load_lds_dwordx4 v[198:199], off
	v_lshl_add_u64 v[198:199], s[8:9], 0, v[164:165]
	s_mov_b32 m0, s24
	s_nop 0
	global_load_lds_dwordx4 v[198:199], off
	v_lshl_add_u64 v[198:199], s[8:9], 0, v[160:161]
	s_add_i32 m0, s24, 0x2000
	s_nop 0
	global_load_lds_dwordx4 v[198:199], off
	v_lshl_add_u64 v[198:199], v[222:223], 0, s[78:79]
	s_mov_b32 m0, s37
	s_nop 0
	global_load_lds_dwordx4 v[198:199], off
	v_lshl_add_u64 v[198:199], v[224:225], 0, s[78:79]
	s_mov_b32 m0, s40
	s_nop 0
	global_load_lds_dwordx4 v[198:199], off
	s_waitcnt vmcnt(8)
	s_waitcnt lgkmcnt(0)
	s_barrier
	v_mfma_f32_16x16x32_bf16 v[60:63], v[128:131], v[172:175], v[60:63]
	v_mfma_f32_16x16x32_bf16 v[56:59], v[136:139], v[172:175], v[56:59]
	v_mfma_f32_16x16x32_bf16 v[52:55], v[128:131], v[180:183], v[52:55]
	v_mfma_f32_16x16x32_bf16 v[48:51], v[136:139], v[180:183], v[48:51]
	v_mfma_f32_16x16x32_bf16 v[44:47], v[128:131], v[204:207], v[44:47]
	v_mfma_f32_16x16x32_bf16 v[40:43], v[136:139], v[204:207], v[40:43]
	v_mfma_f32_16x16x32_bf16 v[36:39], v[128:131], v[212:215], v[36:39]
	v_mfma_f32_16x16x32_bf16 v[32:35], v[136:139], v[212:215], v[32:35]
	v_mfma_f32_16x16x32_bf16 v[60:63], v[132:135], v[176:179], v[60:63]
	v_mfma_f32_16x16x32_bf16 v[56:59], v[140:143], v[176:179], v[56:59]
	v_mfma_f32_16x16x32_bf16 v[52:55], v[132:135], v[184:187], v[52:55]
	v_mfma_f32_16x16x32_bf16 v[48:51], v[140:143], v[184:187], v[48:51]
	v_mfma_f32_16x16x32_bf16 v[44:47], v[132:135], v[208:211], v[44:47]
	v_mfma_f32_16x16x32_bf16 v[40:43], v[140:143], v[208:211], v[40:43]
	v_mfma_f32_16x16x32_bf16 v[36:39], v[132:135], v[216:219], v[36:39]
	v_mfma_f32_16x16x32_bf16 v[32:35], v[140:143], v[216:219], v[32:35]
	v_mfma_f32_16x16x32_bf16 v[28:31], v[144:147], v[172:175], v[28:31]
	v_mfma_f32_16x16x32_bf16 v[24:27], v[152:155], v[172:175], v[24:27]
	v_mfma_f32_16x16x32_bf16 v[20:23], v[144:147], v[180:183], v[20:23]
	v_mfma_f32_16x16x32_bf16 v[16:19], v[152:155], v[180:183], v[16:19]
	v_mfma_f32_16x16x32_bf16 v[12:15], v[144:147], v[204:207], v[12:15]
	v_mfma_f32_16x16x32_bf16 v[8:11], v[152:155], v[204:207], v[8:11]
	v_mfma_f32_16x16x32_bf16 v[4:7], v[144:147], v[212:215], v[4:7]
	v_mfma_f32_16x16x32_bf16 v[0:3], v[152:155], v[212:215], v[0:3]
	v_mfma_f32_16x16x32_bf16 v[28:31], v[148:151], v[176:179], v[28:31]
	v_mfma_f32_16x16x32_bf16 v[24:27], v[156:159], v[176:179], v[24:27]
	v_mfma_f32_16x16x32_bf16 v[20:23], v[148:151], v[184:187], v[20:23]
	v_mfma_f32_16x16x32_bf16 v[16:19], v[156:159], v[184:187], v[16:19]
	v_mfma_f32_16x16x32_bf16 v[12:15], v[148:151], v[208:211], v[12:15]
	v_mfma_f32_16x16x32_bf16 v[8:11], v[156:159], v[208:211], v[8:11]
	v_mfma_f32_16x16x32_bf16 v[4:7], v[148:151], v[216:219], v[4:7]
	v_mfma_f32_16x16x32_bf16 v[0:3], v[156:159], v[216:219], v[0:3]
	s_barrier
	s_add_i32 s58, s58, 2
	s_add_u32 s6, s6, 0x100
	s_addc_u32 s7, s7, 0
	s_add_u32 s45, s45, 0x100
	s_addc_u32 s52, s52, 0
	s_cmp_gt_u32 s58, 13
	s_cbranch_scc0 .LBB0_424
	s_and_b64 vcc, exec, s[14:15]
	s_cbranch_vccz .LBB0_427
	s_barrier

; #define PG8_STAGE(bufoff, gbase, voff) do { _Pragma("unroll") for (int _i = 0; _i < 2; ++_i) \
;         __builtin_amdgcn_global_load_lds((const unsigned*)((const char*)(gbase) + (voff)[_i]), (PG8_LAS unsigned*)(lds + (bufoff) + ldsw + _i * 8192), 16, 0, 0); } while (0)
; #define PG8_LDA(dst, b, h) do { _Pragma("unroll") for (int m = 0; m < 4; ++m) _Pragma("unroll") for (int k = 0; k < 2; ++k) dst[m][k] = *(const PG8_LAS bf16x8*)(lds + PG8_SA(b, h) + aoff + m * 2048 + k * 1024); } while (0)
; #define PG8_LDB(dst, b, h) do { _Pragma("unroll") for (int n = 0; n < 2; ++n) _Pragma("unroll") for (int k = 0; k < 2; ++k) dst[n][k] = *(const PG8_LAS bf16x8*)(lds + PG8_SB(b, h) + boff + n * 2048 + k * 1024); } while (0)
; #define PG8_MMA(ai, bj, At, Bt) do { __builtin_amdgcn_s_setprio(1); _Pragma("unroll") for (int m = 0; m < 4; ++m) _Pragma("unroll") for (int n = 0; n < 2; ++n) _Pragma("unroll") for (int k = 0; k < 2; ++k) \
;         acc[ai][bj][m][n] = __builtin_amdgcn_mfma_f32_16x16x32_bf16(Bt[n][k], At[m][k], acc[ai][bj][m][n], 0, 0, 0); __builtin_amdgcn_s_setprio(0); } while (0)
; #define PG8_WAIT_V(n) asm volatile("s_waitcnt vmcnt(" #n ")" ::: "memory")
; #define PG8_WAIT_L(n) asm volatile("s_waitcnt lgkmcnt(" #n ")" ::: "memory")
; template <class Epi, class Sched, bool ALIGN_EPI = false, bool SP2 = false>
; __device__ __forceinline__ void gemm_phase(PG8_LAS unsigned char* lds, const Gemm g, const Sched& S, const Epi& E) {
;     ...
;             const bool last = (t == nt - 2);
;             const char* a1 = cA + (size_t)(t + 1) * kstep;
;             const char* a2 = last ? nA : cA + (size_t)(t + 2) * kstep; const char* b2 = last ? nB : cB + (size_t)(t + 2) * kstep;
;             const char* a3 = a2 + kstep; const char* b3 = b2 + kstep;
;             if (last && has_next) S.a_ready(nxt);
;             if constexpr (SP2) {
;             PG8_LDB(B0, 0, 0); PG8_LDB(B1, 0, 1); PG8_SCHED; PG8_LDA(At, 0, 0); PG8_STAGE(PG8_SA(1, 1), a1 + hstep, voffA);
;             PG8_WAIT_V(8); PG8_WAIT_L(0); PG8_BAR; PG8_MMA(0, 0, At, B0); PG8_MMA(0, 1, At, B1); PG8_BAR; PG8_SCHED;
;             PG8_LDA(At, 0, 1); PG8_STAGE(PG8_SB(0, 0), b2, voffB); PG8_STAGE(PG8_SB(0, 1), b2 + hstep, voffB); PG8_STAGE(PG8_SA(0, 0), a2, voffA);
;             PG8_WAIT_V(8); PG8_WAIT_L(0); PG8_BAR; PG8_MMA(1, 0, At, B0); PG8_MMA(1, 1, At, B1); PG8_BAR; PG8_SCHED;
.LBB0_596:
	s_add_u32 s26, s24, 0xfff80080
	s_addc_u32 s27, s25, -1
	s_add_i32 s60, 0, 0x10000
	s_cmp_eq_u32 s67, 28
	s_cselect_b32 s29, s19, s27
	s_cselect_b32 s28, s58, s26
	s_cselect_b32 s27, s17, s66
	s_cselect_b32 s26, s62, s63
	s_add_i32 s68, 0, 0x14000
	v_add_u32_e32 v124, s60, v239
	v_add_u32_e32 v148, s68, v239
	ds_read_b128 v[112:115], v124
	ds_read_b128 v[116:119], v124 offset:1024
	ds_read_b128 v[120:123], v124 offset:2048
	ds_read_b128 v[124:127], v124 offset:3072
	ds_read_b128 v[132:135], v148
	ds_read_b128 v[140:143], v148 offset:1024
	ds_read_b128 v[144:147], v148 offset:2048
	ds_read_b128 v[148:151], v148 offset:3072
	v_lshl_add_u64 v[212:213], s[24:25], 0, v[204:205]
	s_add_i32 m0, s36, 0xc000
	ds_read_b128 v[156:159], v241
	ds_read_b128 v[164:167], v241 offset:1024
	ds_read_b128 v[168:171], v241 offset:2048
	ds_read_b128 v[172:175], v241 offset:3072
	ds_read_b128 v[176:179], v241 offset:4096
	ds_read_b128 v[180:183], v241 offset:5120
	ds_read_b128 v[184:187], v241 offset:6144
	ds_read_b128 v[208:211], v241 offset:7168
	global_load_lds_dwordx4 v[212:213], off
	v_lshl_add_u64 v[212:213], s[24:25], 0, v[206:207]
	s_add_i32 m0, s36, 0xe000
	s_nop 0
	global_load_lds_dwordx4 v[212:213], off
	s_waitcnt vmcnt(8)
	s_waitcnt lgkmcnt(0)
	s_barrier
	v_mfma_f32_16x16x32_bf16 v[160:163], v[112:115], v[156:159], v[160:163]
	v_mfma_f32_16x16x32_bf16 v[152:155], v[120:123], v[156:159], v[152:155]
	v_mfma_f32_16x16x32_bf16 v[108:111], v[112:115], v[168:171], v[108:111]
	v_mfma_f32_16x16x32_bf16 v[104:107], v[120:123], v[168:171], v[104:107]
	v_mfma_f32_16x16x32_bf16 v[92:95], v[112:115], v[176:179], v[92:95]
	v_mfma_f32_16x16x32_bf16 v[88:91], v[120:123], v[176:179], v[88:91]
	v_mfma_f32_16x16x32_bf16 v[76:79], v[112:115], v[184:187], v[76:79]
	v_mfma_f32_16x16x32_bf16 v[72:75], v[120:123], v[184:187], v[72:75]
	v_mfma_f32_16x16x32_bf16 v[160:163], v[116:119], v[164:167], v[160:163]
	v_mfma_f32_16x16x32_bf16 v[152:155], v[124:127], v[164:167], v[152:155]
	v_mfma_f32_16x16x32_bf16 v[108:111], v[116:119], v[172:175], v[108:111]
	v_mfma_f32_16x16x32_bf16 v[104:107], v[124:127], v[172:175], v[104:107]
	v_mfma_f32_16x16x32_bf16 v[92:95], v[116:119], v[180:183], v[92:95]
	v_mfma_f32_16x16x32_bf16 v[88:91], v[124:127], v[180:183], v[88:91]
	v_mfma_f32_16x16x32_bf16 v[76:79], v[116:119], v[208:211], v[76:79]
	v_mfma_f32_16x16x32_bf16 v[72:75], v[124:127], v[208:211], v[72:75]
	v_mfma_f32_16x16x32_bf16 v[136:139], v[132:135], v[156:159], v[136:139]
	v_mfma_f32_16x16x32_bf16 v[128:131], v[144:147], v[156:159], v[128:131]
	v_mfma_f32_16x16x32_bf16 v[100:103], v[132:135], v[168:171], v[100:103]
	v_mfma_f32_16x16x32_bf16 v[96:99], v[144:147], v[168:171], v[96:99]
	v_mfma_f32_16x16x32_bf16 v[84:87], v[132:135], v[176:179], v[84:87]
	v_mfma_f32_16x16x32_bf16 v[80:83], v[144:147], v[176:179], v[80:83]
	v_mfma_f32_16x16x32_bf16 v[68:71], v[132:135], v[184:187], v[68:71]
	v_mfma_f32_16x16x32_bf16 v[64:67], v[144:147], v[184:187], v[64:67]
	v_mfma_f32_16x16x32_bf16 v[136:139], v[140:143], v[164:167], v[136:139]
	v_mfma_f32_16x16x32_bf16 v[128:131], v[148:151], v[164:167], v[128:131]
	v_mfma_f32_16x16x32_bf16 v[100:103], v[140:143], v[172:175], v[100:103]
	v_mfma_f32_16x16x32_bf16 v[96:99], v[148:151], v[172:175], v[96:99]
	v_mfma_f32_16x16x32_bf16 v[84:87], v[140:143], v[180:183], v[84:87]
	v_mfma_f32_16x16x32_bf16 v[80:83], v[148:151], v[180:183], v[80:83]
	v_mfma_f32_16x16x32_bf16 v[68:71], v[140:143], v[208:211], v[68:71]
	v_mfma_f32_16x16x32_bf16 v[64:67], v[148:151], v[208:211], v[64:67]
	s_barrier
	s_add_i32 s60, s60, s35
	v_lshl_add_u64 v[212:213], s[26:27], 0, v[188:189]
	s_mov_b32 m0, s60
	ds_read_b128 v[156:159], v241 offset:16384
	ds_read_b128 v[164:167], v241 offset:17408
	ds_read_b128 v[168:171], v241 offset:18432
	ds_read_b128 v[172:175], v241 offset:19456
	ds_read_b128 v[176:179], v241 offset:20480
	ds_read_b128 v[180:183], v241 offset:21504
	ds_read_b128 v[184:187], v241 offset:22528
	ds_read_b128 v[208:211], v241 offset:23552
	global_load_lds_dwordx4 v[212:213], off
	s_add_i32 m0, s60, 0x2000
	s_add_u32 s60, s26, 0x80000
	v_lshl_add_u64 v[214:215], s[26:27], 0, v[198:199]
	s_addc_u32 s61, s27, 0
	s_add_i32 s68, s68, s35
	global_load_lds_dwordx4 v[214:215], off
	v_lshl_add_u64 v[216:217], s[60:61], 0, v[188:189]
	s_mov_b32 m0, s68
	v_lshl_add_u64 v[218:219], s[28:29], 0, v[200:201]
	global_load_lds_dwordx4 v[216:217], off
	v_lshl_add_u64 v[216:217], s[60:61], 0, v[198:199]
	s_add_i32 m0, s68, 0x2000
	s_nop 0
	global_load_lds_dwordx4 v[216:217], off
	v_lshl_add_u64 v[216:217], s[28:29], 0, v[202:203]
	s_mov_b32 m0, s36
	s_nop 0
	global_load_lds_dwordx4 v[216:217], off
	s_mov_b32 m0, s37
	s_nop 0
	global_load_lds_dwordx4 v[218:219], off
	s_waitcnt vmcnt(8)
	s_waitcnt lgkmcnt(0)
	s_barrier
; #define PG8_STAGE(bufoff, gbase, voff) do { _Pragma("unroll") for (int _i = 0; _i < 2; ++_i) \
;         __builtin_amdgcn_global_load_lds((const unsigned*)((const char*)(gbase) + (voff)[_i]), (PG8_LAS unsigned*)(lds + (bufoff) + ldsw + _i * 8192), 16, 0, 0); } while (0)
; #define PG8_LDA(dst, b, h) do { _Pragma("unroll") for (int m = 0; m < 4; ++m) _Pragma("unroll") for (int k = 0; k < 2; ++k) dst[m][k] = *(const PG8_LAS bf16x8*)(lds + PG8_SA(b, h) + aoff + m * 2048 + k * 1024); } while (0)
; #define PG8_LDB(dst, b, h) do { _Pragma("unroll") for (int n = 0; n < 2; ++n) _Pragma("unroll") for (int k = 0; k < 2; ++k) dst[n][k] = *(const PG8_LAS bf16x8*)(lds + PG8_SB(b, h) + boff + n * 2048 + k * 1024); } while (0)
; #define PG8_MMA(ai, bj, At, Bt) do { __builtin_amdgcn_s_setprio(1); _Pragma("unroll") for (int m = 0; m < 4; ++m) _Pragma("unroll") for (int n = 0; n < 2; ++n) _Pragma("unroll") for (int k = 0; k < 2; ++k) \
;         acc[ai][bj][m][n] = __builtin_amdgcn_mfma_f32_16x16x32_bf16(Bt[n][k], At[m][k], acc[ai][bj][m][n], 0, 0, 0); __builtin_amdgcn_s_setprio(0); } while (0)
; #define PG8_WAIT_V(n) asm volatile("s_waitcnt vmcnt(" #n ")" ::: "memory")
; #define PG8_WAIT_L(n) asm volatile("s_waitcnt lgkmcnt(" #n ")" ::: "memory")
; #define PG8_BAR __builtin_amdgcn_s_barrier()
; #define PG8_SCHED __builtin_amdgcn_sched_barrier(0)
; template <class Epi, class Sched, bool ALIGN_EPI = false, bool SP2 = false>
; __device__ __forceinline__ void gemm_phase(PG8_LAS unsigned char* lds, const Gemm g, const Sched& S, const Epi& E) {
;     ...
;             PG8_WAIT_V(8); PG8_WAIT_L(0); PG8_BAR; PG8_MMA(1, 0, At, B0); PG8_MMA(1, 1, At, B1); PG8_BAR; PG8_SCHED;
;             PG8_LDB(B0, 1, 0); PG8_LDB(B1, 1, 1); PG8_SCHED; PG8_LDA(At, 1, 0); PG8_STAGE(PG8_SA(0, 1), a2 + hstep, voffA);
;             PG8_WAIT_V(8); PG8_WAIT_L(0); PG8_BAR; PG8_MMA(0, 0, At, B0); PG8_MMA(0, 1, At, B1); PG8_BAR; PG8_SCHED;
	v_mfma_f32_16x16x32_bf16 v[60:63], v[112:115], v[156:159], v[60:63]
	v_mfma_f32_16x16x32_bf16 v[56:59], v[120:123], v[156:159], v[56:59]
	v_mfma_f32_16x16x32_bf16 v[44:47], v[112:115], v[168:171], v[44:47]
	v_mfma_f32_16x16x32_bf16 v[40:43], v[120:123], v[168:171], v[40:43]
	v_mfma_f32_16x16x32_bf16 v[28:31], v[112:115], v[176:179], v[28:31]
	v_mfma_f32_16x16x32_bf16 v[24:27], v[120:123], v[176:179], v[24:27]
	v_mfma_f32_16x16x32_bf16 v[12:15], v[112:115], v[184:187], v[12:15]
	v_mfma_f32_16x16x32_bf16 v[8:11], v[120:123], v[184:187], v[8:11]
	v_mfma_f32_16x16x32_bf16 v[60:63], v[116:119], v[164:167], v[60:63]
	v_mfma_f32_16x16x32_bf16 v[56:59], v[124:127], v[164:167], v[56:59]
	v_mfma_f32_16x16x32_bf16 v[44:47], v[116:119], v[172:175], v[44:47]
	v_mfma_f32_16x16x32_bf16 v[40:43], v[124:127], v[172:175], v[40:43]
	v_mfma_f32_16x16x32_bf16 v[28:31], v[116:119], v[180:183], v[28:31]
	v_mfma_f32_16x16x32_bf16 v[24:27], v[124:127], v[180:183], v[24:27]
	v_mfma_f32_16x16x32_bf16 v[12:15], v[116:119], v[208:211], v[12:15]
	v_mfma_f32_16x16x32_bf16 v[8:11], v[124:127], v[208:211], v[8:11]
	v_mfma_f32_16x16x32_bf16 v[52:55], v[132:135], v[156:159], v[52:55]
	v_mfma_f32_16x16x32_bf16 v[48:51], v[144:147], v[156:159], v[48:51]
	v_mfma_f32_16x16x32_bf16 v[36:39], v[132:135], v[168:171], v[36:39]
	v_mfma_f32_16x16x32_bf16 v[32:35], v[144:147], v[168:171], v[32:35]
	v_mfma_f32_16x16x32_bf16 v[20:23], v[132:135], v[176:179], v[20:23]
	v_mfma_f32_16x16x32_bf16 v[16:19], v[144:147], v[176:179], v[16:19]
	v_mfma_f32_16x16x32_bf16 v[4:7], v[132:135], v[184:187], v[4:7]
	v_mfma_f32_16x16x32_bf16 v[0:3], v[144:147], v[184:187], v[0:3]
	v_mfma_f32_16x16x32_bf16 v[52:55], v[140:143], v[164:167], v[52:55]
	v_mfma_f32_16x16x32_bf16 v[48:51], v[148:151], v[164:167], v[48:51]
	v_mfma_f32_16x16x32_bf16 v[36:39], v[140:143], v[172:175], v[36:39]
	v_mfma_f32_16x16x32_bf16 v[32:35], v[148:151], v[172:175], v[32:35]
	v_mfma_f32_16x16x32_bf16 v[20:23], v[140:143], v[180:183], v[20:23]
	v_mfma_f32_16x16x32_bf16 v[16:19], v[148:151], v[180:183], v[16:19]
	v_mfma_f32_16x16x32_bf16 v[4:7], v[140:143], v[208:211], v[4:7]
	v_mfma_f32_16x16x32_bf16 v[0:3], v[148:151], v[208:211], v[0:3]
	s_barrier
	s_add_i32 s60, 0, 0x18000
	s_add_i32 s61, 0, 0x1c000
	v_add_u32_e32 v124, s60, v239
	v_add_u32_e32 v148, s61, v239
	ds_read_b128 v[112:115], v124
	ds_read_b128 v[116:119], v124 offset:1024
	ds_read_b128 v[120:123], v124 offset:2048
	ds_read_b128 v[124:127], v124 offset:3072
	ds_read_b128 v[132:135], v148
	ds_read_b128 v[140:143], v148 offset:1024
	ds_read_b128 v[144:147], v148 offset:2048
	ds_read_b128 v[148:151], v148 offset:3072
	s_add_u32 s28, s28, 0x80000
	s_addc_u32 s29, s29, 0
	s_mov_b32 m0, s38
	v_lshl_add_u64 v[220:221], s[28:29], 0, v[202:203]
	ds_read_b128 v[156:159], v241 offset:32768
	ds_read_b128 v[164:167], v241 offset:33792
	ds_read_b128 v[168:171], v241 offset:34816
	ds_read_b128 v[172:175], v241 offset:35840
	ds_read_b128 v[176:179], v241 offset:36864
	ds_read_b128 v[180:183], v241 offset:37888
	ds_read_b128 v[184:187], v241 offset:38912
	ds_read_b128 v[208:211], v241 offset:39936
	global_load_lds_dwordx4 v[220:221], off
	v_lshl_add_u64 v[220:221], s[28:29], 0, v[200:201]
	s_mov_b32 m0, s39
	s_nop 0
	global_load_lds_dwordx4 v[220:221], off
	s_waitcnt vmcnt(8)
	s_waitcnt lgkmcnt(0)
	s_barrier
	v_mfma_f32_16x16x32_bf16 v[160:163], v[112:115], v[156:159], v[160:163]
	v_mfma_f32_16x16x32_bf16 v[152:155], v[120:123], v[156:159], v[152:155]
	v_mfma_f32_16x16x32_bf16 v[108:111], v[112:115], v[168:171], v[108:111]
	v_mfma_f32_16x16x32_bf16 v[104:107], v[120:123], v[168:171], v[104:107]
	v_mfma_f32_16x16x32_bf16 v[92:95], v[112:115], v[176:179], v[92:95]
	v_mfma_f32_16x16x32_bf16 v[88:91], v[120:123], v[176:179], v[88:91]
	v_mfma_f32_16x16x32_bf16 v[76:79], v[112:115], v[184:187], v[76:79]
	v_mfma_f32_16x16x32_bf16 v[72:75], v[120:123], v[184:187], v[72:75]
	v_mfma_f32_16x16x32_bf16 v[160:163], v[116:119], v[164:167], v[160:163]
	v_mfma_f32_16x16x32_bf16 v[152:155], v[124:127], v[164:167], v[152:155]
	v_mfma_f32_16x16x32_bf16 v[108:111], v[116:119], v[172:175], v[108:111]
	v_mfma_f32_16x16x32_bf16 v[104:107], v[124:127], v[172:175], v[104:107]
	v_mfma_f32_16x16x32_bf16 v[92:95], v[116:119], v[180:183], v[92:95]
	v_mfma_f32_16x16x32_bf16 v[88:91], v[124:127], v[180:183], v[88:91]
	v_mfma_f32_16x16x32_bf16 v[76:79], v[116:119], v[208:211], v[76:79]
	v_mfma_f32_16x16x32_bf16 v[72:75], v[124:127], v[208:211], v[72:75]
	v_mfma_f32_16x16x32_bf16 v[136:139], v[132:135], v[156:159], v[136:139]
	v_mfma_f32_16x16x32_bf16 v[128:131], v[144:147], v[156:159], v[128:131]
	v_mfma_f32_16x16x32_bf16 v[100:103], v[132:135], v[168:171], v[100:103]
	v_mfma_f32_16x16x32_bf16 v[96:99], v[144:147], v[168:171], v[96:99]
	v_mfma_f32_16x16x32_bf16 v[84:87], v[132:135], v[176:179], v[84:87]
	v_mfma_f32_16x16x32_bf16 v[80:83], v[144:147], v[176:179], v[80:83]
	v_mfma_f32_16x16x32_bf16 v[68:71], v[132:135], v[184:187], v[68:71]
	v_mfma_f32_16x16x32_bf16 v[64:67], v[144:147], v[184:187], v[64:67]
	v_mfma_f32_16x16x32_bf16 v[136:139], v[140:143], v[164:167], v[136:139]
	v_mfma_f32_16x16x32_bf16 v[128:131], v[148:151], v[164:167], v[128:131]
	v_mfma_f32_16x16x32_bf16 v[100:103], v[140:143], v[172:175], v[100:103]
	v_mfma_f32_16x16x32_bf16 v[96:99], v[148:151], v[172:175], v[96:99]
	v_mfma_f32_16x16x32_bf16 v[84:87], v[140:143], v[180:183], v[84:87]
	v_mfma_f32_16x16x32_bf16 v[80:83], v[148:151], v[180:183], v[80:83]
	v_mfma_f32_16x16x32_bf16 v[68:71], v[140:143], v[208:211], v[68:71]
	v_mfma_f32_16x16x32_bf16 v[64:67], v[148:151], v[208:211], v[64:67]
	s_barrier
; #define PG8_STAGE(bufoff, gbase, voff) do { _Pragma("unroll") for (int _i = 0; _i < 2; ++_i) \
;         __builtin_amdgcn_global_load_lds((const unsigned*)((const char*)(gbase) + (voff)[_i]), (PG8_LAS unsigned*)(lds + (bufoff) + ldsw + _i * 8192), 16, 0, 0); } while (0)
; #define PG8_LDA(dst, b, h) do { _Pragma("unroll") for (int m = 0; m < 4; ++m) _Pragma("unroll") for (int k = 0; k < 2; ++k) dst[m][k] = *(const PG8_LAS bf16x8*)(lds + PG8_SA(b, h) + aoff + m * 2048 + k * 1024); } while (0)
; #define PG8_MMA(ai, bj, At, Bt) do { __builtin_amdgcn_s_setprio(1); _Pragma("unroll") for (int m = 0; m < 4; ++m) _Pragma("unroll") for (int n = 0; n < 2; ++n) _Pragma("unroll") for (int k = 0; k < 2; ++k) \
;         acc[ai][bj][m][n] = __builtin_amdgcn_mfma_f32_16x16x32_bf16(Bt[n][k], At[m][k], acc[ai][bj][m][n], 0, 0, 0); __builtin_amdgcn_s_setprio(0); } while (0)
; #define PG8_WAIT_V(n) asm volatile("s_waitcnt vmcnt(" #n ")" ::: "memory")
; #define PG8_WAIT_L(n) asm volatile("s_waitcnt lgkmcnt(" #n ")" ::: "memory")
; #define PG8_BAR __builtin_amdgcn_s_barrier()
; #define PG8_SCHED __builtin_amdgcn_sched_barrier(0)
; template <class Epi, class Sched, bool ALIGN_EPI = false, bool SP2 = false>
; __device__ __forceinline__ void gemm_phase(PG8_LAS unsigned char* lds, const Gemm g, const Sched& S, const Epi& E) {
;     ...
;             PG8_LDA(At, 1, 1); PG8_STAGE(PG8_SB(1, 0), b3, voffB); PG8_STAGE(PG8_SB(1, 1), b3 + hstep, voffB); PG8_STAGE(PG8_SA(1, 0), a3, voffA);
;             PG8_WAIT_V(8); PG8_WAIT_L(0); PG8_BAR; PG8_MMA(1, 0, At, B0); PG8_MMA(1, 1, At, B1); PG8_BAR; PG8_SCHED;
;     ...
;         if constexpr (ALIGN_EPI) { if (wr == 0) PG8_BAR; }
	s_add_i32 s28, s60, s35
	v_lshl_add_u64 v[212:213], v[212:213], 0, s[78:79]
	s_mov_b32 m0, s28
	ds_read_b128 v[156:159], v241 offset:49152
	ds_read_b128 v[164:167], v241 offset:50176
	ds_read_b128 v[168:171], v241 offset:51200
	ds_read_b128 v[172:175], v241 offset:52224
	ds_read_b128 v[176:179], v241 offset:53248
	ds_read_b128 v[180:183], v241 offset:54272
	ds_read_b128 v[184:187], v241 offset:55296
	ds_read_b128 v[208:211], v241 offset:56320
	global_load_lds_dwordx4 v[212:213], off
	s_add_i32 m0, s28, 0x2000
	s_add_u32 s26, s26, 0x80080
	v_lshl_add_u64 v[212:213], v[214:215], 0, s[78:79]
	s_addc_u32 s27, s27, 0
	s_add_i32 s28, s61, s35
	global_load_lds_dwordx4 v[212:213], off
	v_lshl_add_u64 v[212:213], s[26:27], 0, v[188:189]
	s_mov_b32 m0, s28
	s_nop 0
	global_load_lds_dwordx4 v[212:213], off
	v_lshl_add_u64 v[212:213], s[26:27], 0, v[198:199]
	s_add_i32 m0, s28, 0x2000
	s_nop 0
	global_load_lds_dwordx4 v[212:213], off
	v_lshl_add_u64 v[212:213], v[216:217], 0, s[78:79]
	s_mov_b32 m0, s40
	s_nop 0
	global_load_lds_dwordx4 v[212:213], off
	v_lshl_add_u64 v[212:213], v[218:219], 0, s[78:79]
	s_mov_b32 m0, s41
	s_nop 0
	global_load_lds_dwordx4 v[212:213], off
	s_waitcnt vmcnt(8)
	s_waitcnt lgkmcnt(0)
	s_barrier
	v_mfma_f32_16x16x32_bf16 v[60:63], v[112:115], v[156:159], v[60:63]
	v_mfma_f32_16x16x32_bf16 v[56:59], v[120:123], v[156:159], v[56:59]
	v_mfma_f32_16x16x32_bf16 v[44:47], v[112:115], v[168:171], v[44:47]
	v_mfma_f32_16x16x32_bf16 v[40:43], v[120:123], v[168:171], v[40:43]
	v_mfma_f32_16x16x32_bf16 v[28:31], v[112:115], v[176:179], v[28:31]
	v_mfma_f32_16x16x32_bf16 v[24:27], v[120:123], v[176:179], v[24:27]
	v_mfma_f32_16x16x32_bf16 v[12:15], v[112:115], v[184:187], v[12:15]
	v_mfma_f32_16x16x32_bf16 v[8:11], v[120:123], v[184:187], v[8:11]
	v_mfma_f32_16x16x32_bf16 v[60:63], v[116:119], v[164:167], v[60:63]
	v_mfma_f32_16x16x32_bf16 v[56:59], v[124:127], v[164:167], v[56:59]
	v_mfma_f32_16x16x32_bf16 v[44:47], v[116:119], v[172:175], v[44:47]
	v_mfma_f32_16x16x32_bf16 v[40:43], v[124:127], v[172:175], v[40:43]
	v_mfma_f32_16x16x32_bf16 v[28:31], v[116:119], v[180:183], v[28:31]
	v_mfma_f32_16x16x32_bf16 v[24:27], v[124:127], v[180:183], v[24:27]
	v_mfma_f32_16x16x32_bf16 v[12:15], v[116:119], v[208:211], v[12:15]
	v_mfma_f32_16x16x32_bf16 v[8:11], v[124:127], v[208:211], v[8:11]
	v_mfma_f32_16x16x32_bf16 v[52:55], v[132:135], v[156:159], v[52:55]
	v_mfma_f32_16x16x32_bf16 v[48:51], v[144:147], v[156:159], v[48:51]
	v_mfma_f32_16x16x32_bf16 v[36:39], v[132:135], v[168:171], v[36:39]
	v_mfma_f32_16x16x32_bf16 v[32:35], v[144:147], v[168:171], v[32:35]
	v_mfma_f32_16x16x32_bf16 v[20:23], v[132:135], v[176:179], v[20:23]
	v_mfma_f32_16x16x32_bf16 v[16:19], v[144:147], v[176:179], v[16:19]
	v_mfma_f32_16x16x32_bf16 v[4:7], v[132:135], v[184:187], v[4:7]
	v_mfma_f32_16x16x32_bf16 v[0:3], v[144:147], v[184:187], v[0:3]
	v_mfma_f32_16x16x32_bf16 v[52:55], v[140:143], v[164:167], v[52:55]
	v_mfma_f32_16x16x32_bf16 v[48:51], v[148:151], v[164:167], v[48:51]
	v_mfma_f32_16x16x32_bf16 v[36:39], v[140:143], v[172:175], v[36:39]
	v_mfma_f32_16x16x32_bf16 v[32:35], v[148:151], v[172:175], v[32:35]
	v_mfma_f32_16x16x32_bf16 v[20:23], v[140:143], v[180:183], v[20:23]
	v_mfma_f32_16x16x32_bf16 v[16:19], v[148:151], v[180:183], v[16:19]
	v_mfma_f32_16x16x32_bf16 v[4:7], v[140:143], v[208:211], v[4:7]
	v_mfma_f32_16x16x32_bf16 v[0:3], v[148:151], v[208:211], v[0:3]
	s_barrier
	s_add_i32 s67, s67, 2
	s_add_u32 s24, s24, 0x100
	s_addc_u32 s25, s25, 0
	s_add_u32 s63, s63, 0x100
	s_addc_u32 s66, s66, 0
	s_cmp_gt_u32 s67, 29
	s_cbranch_scc0 .LBB0_596
	s_and_b64 vcc, exec, s[14:15]
	s_cbranch_vccz .LBB0_599
	s_barrier

; #define PG8_STAGE(bufoff, gbase, voff) do { _Pragma("unroll") for (int _i = 0; _i < 2; ++_i) \
;         __builtin_amdgcn_global_load_lds((const unsigned*)((const char*)(gbase) + (voff)[_i]), (PG8_LAS unsigned*)(lds + (bufoff) + ldsw + _i * 8192), 16, 0, 0); } while (0)
; #define PG8_LDA(dst, b, h) do { _Pragma("unroll") for (int m = 0; m < 4; ++m) _Pragma("unroll") for (int k = 0; k < 2; ++k) dst[m][k] = *(const PG8_LAS bf16x8*)(lds + PG8_SA(b, h) + aoff + m * 2048 + k * 1024); } while (0)
; #define PG8_LDB(dst, b, h) do { _Pragma("unroll") for (int n = 0; n < 2; ++n) _Pragma("unroll") for (int k = 0; k < 2; ++k) dst[n][k] = *(const PG8_LAS bf16x8*)(lds + PG8_SB(b, h) + boff + n * 2048 + k * 1024); } while (0)
; #define PG8_MMA(ai, bj, At, Bt) do { __builtin_amdgcn_s_setprio(1); _Pragma("unroll") for (int m = 0; m < 4; ++m) _Pragma("unroll") for (int n = 0; n < 2; ++n) _Pragma("unroll") for (int k = 0; k < 2; ++k) \
;         acc[ai][bj][m][n] = __builtin_amdgcn_mfma_f32_16x16x32_bf16(Bt[n][k], At[m][k], acc[ai][bj][m][n], 0, 0, 0); __builtin_amdgcn_s_setprio(0); } while (0)
; #define PG8_WAIT_V(n) asm volatile("s_waitcnt vmcnt(" #n ")" ::: "memory")
; #define PG8_WAIT_L(n) asm volatile("s_waitcnt lgkmcnt(" #n ")" ::: "memory")
; template <class Epi, class Sched, bool ALIGN_EPI = false, bool SP2 = false>
; __device__ __forceinline__ void gemm_phase(PG8_LAS unsigned char* lds, const Gemm g, const Sched& S, const Epi& E) {
;     ...
;             const bool last = (t == nt - 2);
;             const char* a1 = cA + (size_t)(t + 1) * kstep;
;             const char* a2 = last ? nA : cA + (size_t)(t + 2) * kstep; const char* b2 = last ? nB : cB + (size_t)(t + 2) * kstep;
;             const char* a3 = a2 + kstep; const char* b3 = b2 + kstep;
;             if (last && has_next) S.a_ready(nxt);
;             if constexpr (SP2) {
;             PG8_LDB(B0, 0, 0); PG8_LDB(B1, 0, 1); PG8_SCHED; PG8_LDA(At, 0, 0); PG8_STAGE(PG8_SA(1, 1), a1 + hstep, voffA);
;             PG8_WAIT_V(8); PG8_WAIT_L(0); PG8_BAR; PG8_MMA(0, 0, At, B0); PG8_MMA(0, 1, At, B1); PG8_BAR; PG8_SCHED;
;             PG8_LDA(At, 0, 1); PG8_STAGE(PG8_SB(0, 0), b2, voffB); PG8_STAGE(PG8_SB(0, 1), b2 + hstep, voffB); PG8_STAGE(PG8_SA(0, 0), a2, voffA);
;             PG8_WAIT_V(8); PG8_WAIT_L(0); PG8_BAR; PG8_MMA(1, 0, At, B0); PG8_MMA(1, 1, At, B1); PG8_BAR; PG8_SCHED;
.LBB0_684:
	s_add_u32 s24, s8, 0xfff80080
	s_addc_u32 s25, s9, -1
	s_add_i32 s60, 0, 0x10000
	s_cmp_eq_u32 s63, 28
	s_cselect_b32 s27, s19, s25
	s_cselect_b32 s26, s45, s24
	v_add_u32_e32 v154, s60, v157
	s_cselect_b32 s25, s17, s62
	s_cselect_b32 s24, s52, s58
	s_add_i32 s66, 0, 0x14000
	ds_read_b128 v[160:163], v154
	ds_read_b128 v[164:167], v154 offset:1024
	ds_read_b128 v[168:171], v154 offset:2048
	ds_read_b128 v[172:175], v154 offset:3072
	v_add_u32_e32 v154, s66, v157
	ds_read_b128 v[176:179], v154
	ds_read_b128 v[180:183], v154 offset:1024
	ds_read_b128 v[184:187], v154 offset:2048
	ds_read_b128 v[198:201], v154 offset:3072
	v_lshl_add_u64 v[154:155], s[8:9], 0, v[134:135]
	s_add_i32 m0, s34, 0xc000
	ds_read_b128 v[202:205], v159
	ds_read_b128 v[206:209], v159 offset:1024
	ds_read_b128 v[210:213], v159 offset:2048
	ds_read_b128 v[214:217], v159 offset:3072
	ds_read_b128 v[218:221], v159 offset:4096
	ds_read_b128 v[222:225], v159 offset:5120
	ds_read_b128 v[226:229], v159 offset:6144
	ds_read_b128 v[238:241], v159 offset:7168
	global_load_lds_dwordx4 v[154:155], off
	v_lshl_add_u64 v[154:155], s[8:9], 0, v[136:137]
	s_add_i32 m0, s34, 0xe000
	s_nop 0
	global_load_lds_dwordx4 v[154:155], off
	s_waitcnt vmcnt(8)
	s_waitcnt lgkmcnt(0)
	s_barrier
	v_mfma_f32_16x16x32_bf16 v[124:127], v[160:163], v[202:205], v[124:127]
	v_mfma_f32_16x16x32_bf16 v[120:123], v[168:171], v[202:205], v[120:123]
	v_mfma_f32_16x16x32_bf16 v[108:111], v[160:163], v[210:213], v[108:111]
	v_mfma_f32_16x16x32_bf16 v[104:107], v[168:171], v[210:213], v[104:107]
	v_mfma_f32_16x16x32_bf16 v[92:95], v[160:163], v[218:221], v[92:95]
	v_mfma_f32_16x16x32_bf16 v[88:91], v[168:171], v[218:221], v[88:91]
	v_mfma_f32_16x16x32_bf16 v[76:79], v[160:163], v[226:229], v[76:79]
	v_mfma_f32_16x16x32_bf16 v[72:75], v[168:171], v[226:229], v[72:75]
	v_mfma_f32_16x16x32_bf16 v[124:127], v[164:167], v[206:209], v[124:127]
	v_mfma_f32_16x16x32_bf16 v[120:123], v[172:175], v[206:209], v[120:123]
	v_mfma_f32_16x16x32_bf16 v[108:111], v[164:167], v[214:217], v[108:111]
	v_mfma_f32_16x16x32_bf16 v[104:107], v[172:175], v[214:217], v[104:107]
	v_mfma_f32_16x16x32_bf16 v[92:95], v[164:167], v[222:225], v[92:95]
	v_mfma_f32_16x16x32_bf16 v[88:91], v[172:175], v[222:225], v[88:91]
	v_mfma_f32_16x16x32_bf16 v[76:79], v[164:167], v[238:241], v[76:79]
	v_mfma_f32_16x16x32_bf16 v[72:75], v[172:175], v[238:241], v[72:75]
	v_mfma_f32_16x16x32_bf16 v[116:119], v[176:179], v[202:205], v[116:119]
	v_mfma_f32_16x16x32_bf16 v[112:115], v[184:187], v[202:205], v[112:115]
	v_mfma_f32_16x16x32_bf16 v[100:103], v[176:179], v[210:213], v[100:103]
	v_mfma_f32_16x16x32_bf16 v[96:99], v[184:187], v[210:213], v[96:99]
	v_mfma_f32_16x16x32_bf16 v[84:87], v[176:179], v[218:221], v[84:87]
	v_mfma_f32_16x16x32_bf16 v[80:83], v[184:187], v[218:221], v[80:83]
	v_mfma_f32_16x16x32_bf16 v[68:71], v[176:179], v[226:229], v[68:71]
	v_mfma_f32_16x16x32_bf16 v[64:67], v[184:187], v[226:229], v[64:67]
	v_mfma_f32_16x16x32_bf16 v[116:119], v[180:183], v[206:209], v[116:119]
	v_mfma_f32_16x16x32_bf16 v[112:115], v[198:201], v[206:209], v[112:115]
	v_mfma_f32_16x16x32_bf16 v[100:103], v[180:183], v[214:217], v[100:103]
	v_mfma_f32_16x16x32_bf16 v[96:99], v[198:201], v[214:217], v[96:99]
	v_mfma_f32_16x16x32_bf16 v[84:87], v[180:183], v[222:225], v[84:87]
	v_mfma_f32_16x16x32_bf16 v[80:83], v[198:201], v[222:225], v[80:83]
	v_mfma_f32_16x16x32_bf16 v[68:71], v[180:183], v[238:241], v[68:71]
	v_mfma_f32_16x16x32_bf16 v[64:67], v[198:201], v[238:241], v[64:67]
	s_barrier
	s_add_i32 s60, s60, s31
	v_lshl_add_u64 v[154:155], s[24:25], 0, v[188:189]
	s_mov_b32 m0, s60
	ds_read_b128 v[202:205], v159 offset:16384
	ds_read_b128 v[206:209], v159 offset:17408
	ds_read_b128 v[210:213], v159 offset:18432
	ds_read_b128 v[214:217], v159 offset:19456
	ds_read_b128 v[218:221], v159 offset:20480
	ds_read_b128 v[222:225], v159 offset:21504
	ds_read_b128 v[226:229], v159 offset:22528
	ds_read_b128 v[238:241], v159 offset:23552
	global_load_lds_dwordx4 v[154:155], off
	s_add_i32 m0, s60, 0x2000
	s_add_u32 s60, s24, 0x80000
	v_lshl_add_u64 v[232:233], s[24:25], 0, v[128:129]
	s_addc_u32 s61, s25, 0
	s_add_i32 s66, s66, s31
	global_load_lds_dwordx4 v[232:233], off
	v_lshl_add_u64 v[242:243], s[60:61], 0, v[188:189]
	s_mov_b32 m0, s66
	v_lshl_add_u64 v[244:245], s[26:27], 0, v[130:131]
	global_load_lds_dwordx4 v[242:243], off
	v_lshl_add_u64 v[242:243], s[60:61], 0, v[128:129]
	s_add_i32 m0, s66, 0x2000
	s_nop 0
	global_load_lds_dwordx4 v[242:243], off
	v_lshl_add_u64 v[242:243], s[26:27], 0, v[132:133]
	s_mov_b32 m0, s34
	s_nop 0
	global_load_lds_dwordx4 v[242:243], off
	s_mov_b32 m0, s35
	s_nop 0
	global_load_lds_dwordx4 v[244:245], off
	s_waitcnt vmcnt(8)
	s_waitcnt lgkmcnt(0)
	s_barrier
; #define PG8_STAGE(bufoff, gbase, voff) do { _Pragma("unroll") for (int _i = 0; _i < 2; ++_i) \
;         __builtin_amdgcn_global_load_lds((const unsigned*)((const char*)(gbase) + (voff)[_i]), (PG8_LAS unsigned*)(lds + (bufoff) + ldsw + _i * 8192), 16, 0, 0); } while (0)
; #define PG8_LDA(dst, b, h) do { _Pragma("unroll") for (int m = 0; m < 4; ++m) _Pragma("unroll") for (int k = 0; k < 2; ++k) dst[m][k] = *(const PG8_LAS bf16x8*)(lds + PG8_SA(b, h) + aoff + m * 2048 + k * 1024); } while (0)
; #define PG8_LDB(dst, b, h) do { _Pragma("unroll") for (int n = 0; n < 2; ++n) _Pragma("unroll") for (int k = 0; k < 2; ++k) dst[n][k] = *(const PG8_LAS bf16x8*)(lds + PG8_SB(b, h) + boff + n * 2048 + k * 1024); } while (0)
; #define PG8_MMA(ai, bj, At, Bt) do { __builtin_amdgcn_s_setprio(1); _Pragma("unroll") for (int m = 0; m < 4; ++m) _Pragma("unroll") for (int n = 0; n < 2; ++n) _Pragma("unroll") for (int k = 0; k < 2; ++k) \
;         acc[ai][bj][m][n] = __builtin_amdgcn_mfma_f32_16x16x32_bf16(Bt[n][k], At[m][k], acc[ai][bj][m][n], 0, 0, 0); __builtin_amdgcn_s_setprio(0); } while (0)
; #define PG8_WAIT_V(n) asm volatile("s_waitcnt vmcnt(" #n ")" ::: "memory")
; #define PG8_WAIT_L(n) asm volatile("s_waitcnt lgkmcnt(" #n ")" ::: "memory")
; #define PG8_BAR __builtin_amdgcn_s_barrier()
; #define PG8_SCHED __builtin_amdgcn_sched_barrier(0)
; template <class Epi, class Sched, bool ALIGN_EPI = false, bool SP2 = false>
; __device__ __forceinline__ void gemm_phase(PG8_LAS unsigned char* lds, const Gemm g, const Sched& S, const Epi& E) {
;     ...
;             PG8_WAIT_V(8); PG8_WAIT_L(0); PG8_BAR; PG8_MMA(1, 0, At, B0); PG8_MMA(1, 1, At, B1); PG8_BAR; PG8_SCHED;
;             PG8_LDB(B0, 1, 0); PG8_LDB(B1, 1, 1); PG8_SCHED; PG8_LDA(At, 1, 0); PG8_STAGE(PG8_SA(0, 1), a2 + hstep, voffA);
;             PG8_WAIT_V(8); PG8_WAIT_L(0); PG8_BAR; PG8_MMA(0, 0, At, B0); PG8_MMA(0, 1, At, B1); PG8_BAR; PG8_SCHED;
	v_mfma_f32_16x16x32_bf16 v[60:63], v[160:163], v[202:205], v[60:63]
	v_mfma_f32_16x16x32_bf16 v[56:59], v[168:171], v[202:205], v[56:59]
	v_mfma_f32_16x16x32_bf16 v[44:47], v[160:163], v[210:213], v[44:47]
	v_mfma_f32_16x16x32_bf16 v[40:43], v[168:171], v[210:213], v[40:43]
	v_mfma_f32_16x16x32_bf16 v[28:31], v[160:163], v[218:221], v[28:31]
	v_mfma_f32_16x16x32_bf16 v[24:27], v[168:171], v[218:221], v[24:27]
	v_mfma_f32_16x16x32_bf16 v[12:15], v[160:163], v[226:229], v[12:15]
	v_mfma_f32_16x16x32_bf16 v[8:11], v[168:171], v[226:229], v[8:11]
	v_mfma_f32_16x16x32_bf16 v[60:63], v[164:167], v[206:209], v[60:63]
	v_mfma_f32_16x16x32_bf16 v[56:59], v[172:175], v[206:209], v[56:59]
	v_mfma_f32_16x16x32_bf16 v[44:47], v[164:167], v[214:217], v[44:47]
	v_mfma_f32_16x16x32_bf16 v[40:43], v[172:175], v[214:217], v[40:43]
	v_mfma_f32_16x16x32_bf16 v[28:31], v[164:167], v[222:225], v[28:31]
	v_mfma_f32_16x16x32_bf16 v[24:27], v[172:175], v[222:225], v[24:27]
	v_mfma_f32_16x16x32_bf16 v[12:15], v[164:167], v[238:241], v[12:15]
	v_mfma_f32_16x16x32_bf16 v[8:11], v[172:175], v[238:241], v[8:11]
	v_mfma_f32_16x16x32_bf16 v[52:55], v[176:179], v[202:205], v[52:55]
	v_mfma_f32_16x16x32_bf16 v[48:51], v[184:187], v[202:205], v[48:51]
	v_mfma_f32_16x16x32_bf16 v[36:39], v[176:179], v[210:213], v[36:39]
	v_mfma_f32_16x16x32_bf16 v[32:35], v[184:187], v[210:213], v[32:35]
	v_mfma_f32_16x16x32_bf16 v[20:23], v[176:179], v[218:221], v[20:23]
	v_mfma_f32_16x16x32_bf16 v[16:19], v[184:187], v[218:221], v[16:19]
	v_mfma_f32_16x16x32_bf16 v[4:7], v[176:179], v[226:229], v[4:7]
	v_mfma_f32_16x16x32_bf16 v[0:3], v[184:187], v[226:229], v[0:3]
	v_mfma_f32_16x16x32_bf16 v[52:55], v[180:183], v[206:209], v[52:55]
	v_mfma_f32_16x16x32_bf16 v[48:51], v[198:201], v[206:209], v[48:51]
	v_mfma_f32_16x16x32_bf16 v[36:39], v[180:183], v[214:217], v[36:39]
	v_mfma_f32_16x16x32_bf16 v[32:35], v[198:201], v[214:217], v[32:35]
	v_mfma_f32_16x16x32_bf16 v[20:23], v[180:183], v[222:225], v[20:23]
	v_mfma_f32_16x16x32_bf16 v[16:19], v[198:201], v[222:225], v[16:19]
	v_mfma_f32_16x16x32_bf16 v[4:7], v[180:183], v[238:241], v[4:7]
	v_mfma_f32_16x16x32_bf16 v[0:3], v[198:201], v[238:241], v[0:3]
	s_barrier
	s_add_i32 s60, 0, 0x18000
	s_add_i32 s61, 0, 0x1c000
	v_add_u32_e32 v172, s60, v157
	v_add_u32_e32 v194, s61, v157
	ds_read_b128 v[160:163], v172
	ds_read_b128 v[164:167], v172 offset:1024
	ds_read_b128 v[168:171], v172 offset:2048
	ds_read_b128 v[172:175], v172 offset:3072
	ds_read_b128 v[176:179], v194
	ds_read_b128 v[180:183], v194 offset:1024
	ds_read_b128 v[184:187], v194 offset:2048
	ds_read_b128 v[198:201], v194 offset:3072
	s_add_u32 s26, s26, 0x80000
	s_addc_u32 s27, s27, 0
	s_mov_b32 m0, s36
	v_lshl_add_u64 v[246:247], s[26:27], 0, v[132:133]
	ds_read_b128 v[202:205], v159 offset:32768
	ds_read_b128 v[206:209], v159 offset:33792
	ds_read_b128 v[210:213], v159 offset:34816
	ds_read_b128 v[214:217], v159 offset:35840
	ds_read_b128 v[218:221], v159 offset:36864
	ds_read_b128 v[222:225], v159 offset:37888
	ds_read_b128 v[226:229], v159 offset:38912
	ds_read_b128 v[238:241], v159 offset:39936
	global_load_lds_dwordx4 v[246:247], off
	v_lshl_add_u64 v[246:247], s[26:27], 0, v[130:131]
	s_mov_b32 m0, s37
	s_nop 0
	global_load_lds_dwordx4 v[246:247], off
	s_waitcnt vmcnt(8)
	s_waitcnt lgkmcnt(0)
	s_barrier
	v_mfma_f32_16x16x32_bf16 v[124:127], v[160:163], v[202:205], v[124:127]
	v_mfma_f32_16x16x32_bf16 v[120:123], v[168:171], v[202:205], v[120:123]
	v_mfma_f32_16x16x32_bf16 v[108:111], v[160:163], v[210:213], v[108:111]
	v_mfma_f32_16x16x32_bf16 v[104:107], v[168:171], v[210:213], v[104:107]
	v_mfma_f32_16x16x32_bf16 v[92:95], v[160:163], v[218:221], v[92:95]
	v_mfma_f32_16x16x32_bf16 v[88:91], v[168:171], v[218:221], v[88:91]
	v_mfma_f32_16x16x32_bf16 v[76:79], v[160:163], v[226:229], v[76:79]
	v_mfma_f32_16x16x32_bf16 v[72:75], v[168:171], v[226:229], v[72:75]
	v_mfma_f32_16x16x32_bf16 v[124:127], v[164:167], v[206:209], v[124:127]
	v_mfma_f32_16x16x32_bf16 v[120:123], v[172:175], v[206:209], v[120:123]
	v_mfma_f32_16x16x32_bf16 v[108:111], v[164:167], v[214:217], v[108:111]
	v_mfma_f32_16x16x32_bf16 v[104:107], v[172:175], v[214:217], v[104:107]
	v_mfma_f32_16x16x32_bf16 v[92:95], v[164:167], v[222:225], v[92:95]
	v_mfma_f32_16x16x32_bf16 v[88:91], v[172:175], v[222:225], v[88:91]
	v_mfma_f32_16x16x32_bf16 v[76:79], v[164:167], v[238:241], v[76:79]
	v_mfma_f32_16x16x32_bf16 v[72:75], v[172:175], v[238:241], v[72:75]
	v_mfma_f32_16x16x32_bf16 v[116:119], v[176:179], v[202:205], v[116:119]
	v_mfma_f32_16x16x32_bf16 v[112:115], v[184:187], v[202:205], v[112:115]
	v_mfma_f32_16x16x32_bf16 v[100:103], v[176:179], v[210:213], v[100:103]
	v_mfma_f32_16x16x32_bf16 v[96:99], v[184:187], v[210:213], v[96:99]
	v_mfma_f32_16x16x32_bf16 v[84:87], v[176:179], v[218:221], v[84:87]
	v_mfma_f32_16x16x32_bf16 v[80:83], v[184:187], v[218:221], v[80:83]
	v_mfma_f32_16x16x32_bf16 v[68:71], v[176:179], v[226:229], v[68:71]
	v_mfma_f32_16x16x32_bf16 v[64:67], v[184:187], v[226:229], v[64:67]
	v_mfma_f32_16x16x32_bf16 v[116:119], v[180:183], v[206:209], v[116:119]
	v_mfma_f32_16x16x32_bf16 v[112:115], v[198:201], v[206:209], v[112:115]
	v_mfma_f32_16x16x32_bf16 v[100:103], v[180:183], v[214:217], v[100:103]
	v_mfma_f32_16x16x32_bf16 v[96:99], v[198:201], v[214:217], v[96:99]
	v_mfma_f32_16x16x32_bf16 v[84:87], v[180:183], v[222:225], v[84:87]
	v_mfma_f32_16x16x32_bf16 v[80:83], v[198:201], v[222:225], v[80:83]
	v_mfma_f32_16x16x32_bf16 v[68:71], v[180:183], v[238:241], v[68:71]
	v_mfma_f32_16x16x32_bf16 v[64:67], v[198:201], v[238:241], v[64:67]
	s_barrier
; #define PG8_STAGE(bufoff, gbase, voff) do { _Pragma("unroll") for (int _i = 0; _i < 2; ++_i) \
;         __builtin_amdgcn_global_load_lds((const unsigned*)((const char*)(gbase) + (voff)[_i]), (PG8_LAS unsigned*)(lds + (bufoff) + ldsw + _i * 8192), 16, 0, 0); } while (0)
; #define PG8_LDA(dst, b, h) do { _Pragma("unroll") for (int m = 0; m < 4; ++m) _Pragma("unroll") for (int k = 0; k < 2; ++k) dst[m][k] = *(const PG8_LAS bf16x8*)(lds + PG8_SA(b, h) + aoff + m * 2048 + k * 1024); } while (0)
; #define PG8_MMA(ai, bj, At, Bt) do { __builtin_amdgcn_s_setprio(1); _Pragma("unroll") for (int m = 0; m < 4; ++m) _Pragma("unroll") for (int n = 0; n < 2; ++n) _Pragma("unroll") for (int k = 0; k < 2; ++k) \
;         acc[ai][bj][m][n] = __builtin_amdgcn_mfma_f32_16x16x32_bf16(Bt[n][k], At[m][k], acc[ai][bj][m][n], 0, 0, 0); __builtin_amdgcn_s_setprio(0); } while (0)
; #define PG8_WAIT_V(n) asm volatile("s_waitcnt vmcnt(" #n ")" ::: "memory")
; #define PG8_WAIT_L(n) asm volatile("s_waitcnt lgkmcnt(" #n ")" ::: "memory")
; #define PG8_BAR __builtin_amdgcn_s_barrier()
; #define PG8_SCHED __builtin_amdgcn_sched_barrier(0)
; template <class Epi, class Sched, bool ALIGN_EPI = false, bool SP2 = false>
; __device__ __forceinline__ void gemm_phase(PG8_LAS unsigned char* lds, const Gemm g, const Sched& S, const Epi& E) {
;     ...
;             PG8_LDA(At, 1, 1); PG8_STAGE(PG8_SB(1, 0), b3, voffB); PG8_STAGE(PG8_SB(1, 1), b3 + hstep, voffB); PG8_STAGE(PG8_SA(1, 0), a3, voffA);
;             PG8_WAIT_V(8); PG8_WAIT_L(0); PG8_BAR; PG8_MMA(1, 0, At, B0); PG8_MMA(1, 1, At, B1); PG8_BAR; PG8_SCHED;
;     ...
;         if constexpr (ALIGN_EPI) { if (wr == 0) PG8_BAR; }
	s_add_i32 s26, s60, s31
	v_lshl_add_u64 v[154:155], v[154:155], 0, s[78:79]
	s_mov_b32 m0, s26
	ds_read_b128 v[202:205], v159 offset:49152
	ds_read_b128 v[206:209], v159 offset:50176
	ds_read_b128 v[210:213], v159 offset:51200
	ds_read_b128 v[214:217], v159 offset:52224
	ds_read_b128 v[218:221], v159 offset:53248
	ds_read_b128 v[222:225], v159 offset:54272
	ds_read_b128 v[226:229], v159 offset:55296
	ds_read_b128 v[238:241], v159 offset:56320
	global_load_lds_dwordx4 v[154:155], off
	s_add_i32 m0, s26, 0x2000
	s_add_u32 s24, s24, 0x80080
	v_lshl_add_u64 v[154:155], v[232:233], 0, s[78:79]
	s_addc_u32 s25, s25, 0
	s_add_i32 s26, s61, s31
	global_load_lds_dwordx4 v[154:155], off
	v_lshl_add_u64 v[154:155], s[24:25], 0, v[188:189]
	s_mov_b32 m0, s26
	s_nop 0
	global_load_lds_dwordx4 v[154:155], off
	v_lshl_add_u64 v[154:155], s[24:25], 0, v[128:129]
	s_add_i32 m0, s26, 0x2000
	s_nop 0
	global_load_lds_dwordx4 v[154:155], off
	v_lshl_add_u64 v[154:155], v[242:243], 0, s[78:79]
	s_mov_b32 m0, s38
	s_nop 0
	global_load_lds_dwordx4 v[154:155], off
	v_lshl_add_u64 v[154:155], v[244:245], 0, s[78:79]
	s_mov_b32 m0, s39
	s_nop 0
	global_load_lds_dwordx4 v[154:155], off
	s_waitcnt vmcnt(8)
	s_waitcnt lgkmcnt(0)
	s_barrier
	v_mfma_f32_16x16x32_bf16 v[60:63], v[160:163], v[202:205], v[60:63]
	v_mfma_f32_16x16x32_bf16 v[56:59], v[168:171], v[202:205], v[56:59]
	v_mfma_f32_16x16x32_bf16 v[44:47], v[160:163], v[210:213], v[44:47]
	v_mfma_f32_16x16x32_bf16 v[40:43], v[168:171], v[210:213], v[40:43]
	v_mfma_f32_16x16x32_bf16 v[28:31], v[160:163], v[218:221], v[28:31]
	v_mfma_f32_16x16x32_bf16 v[24:27], v[168:171], v[218:221], v[24:27]
	v_mfma_f32_16x16x32_bf16 v[12:15], v[160:163], v[226:229], v[12:15]
	v_mfma_f32_16x16x32_bf16 v[8:11], v[168:171], v[226:229], v[8:11]
	v_mfma_f32_16x16x32_bf16 v[60:63], v[164:167], v[206:209], v[60:63]
	v_mfma_f32_16x16x32_bf16 v[56:59], v[172:175], v[206:209], v[56:59]
	v_mfma_f32_16x16x32_bf16 v[44:47], v[164:167], v[214:217], v[44:47]
	v_mfma_f32_16x16x32_bf16 v[40:43], v[172:175], v[214:217], v[40:43]
	v_mfma_f32_16x16x32_bf16 v[28:31], v[164:167], v[222:225], v[28:31]
	v_mfma_f32_16x16x32_bf16 v[24:27], v[172:175], v[222:225], v[24:27]
	v_mfma_f32_16x16x32_bf16 v[12:15], v[164:167], v[238:241], v[12:15]
	v_mfma_f32_16x16x32_bf16 v[8:11], v[172:175], v[238:241], v[8:11]
	v_mfma_f32_16x16x32_bf16 v[52:55], v[176:179], v[202:205], v[52:55]
	v_mfma_f32_16x16x32_bf16 v[48:51], v[184:187], v[202:205], v[48:51]
	v_mfma_f32_16x16x32_bf16 v[36:39], v[176:179], v[210:213], v[36:39]
	v_mfma_f32_16x16x32_bf16 v[32:35], v[184:187], v[210:213], v[32:35]
	v_mfma_f32_16x16x32_bf16 v[20:23], v[176:179], v[218:221], v[20:23]
	v_mfma_f32_16x16x32_bf16 v[16:19], v[184:187], v[218:221], v[16:19]
	v_mfma_f32_16x16x32_bf16 v[4:7], v[176:179], v[226:229], v[4:7]
	v_mfma_f32_16x16x32_bf16 v[0:3], v[184:187], v[226:229], v[0:3]
	v_mfma_f32_16x16x32_bf16 v[52:55], v[180:183], v[206:209], v[52:55]
	v_mfma_f32_16x16x32_bf16 v[48:51], v[198:201], v[206:209], v[48:51]
	v_mfma_f32_16x16x32_bf16 v[36:39], v[180:183], v[214:217], v[36:39]
	v_mfma_f32_16x16x32_bf16 v[32:35], v[198:201], v[214:217], v[32:35]
	v_mfma_f32_16x16x32_bf16 v[20:23], v[180:183], v[222:225], v[20:23]
	v_mfma_f32_16x16x32_bf16 v[16:19], v[198:201], v[222:225], v[16:19]
	v_mfma_f32_16x16x32_bf16 v[4:7], v[180:183], v[238:241], v[4:7]
	v_mfma_f32_16x16x32_bf16 v[0:3], v[198:201], v[238:241], v[0:3]
	s_barrier
	s_add_i32 s63, s63, 2
	s_add_u32 s8, s8, 0x100
	s_addc_u32 s9, s9, 0
	s_add_u32 s58, s58, 0x100
	s_addc_u32 s62, s62, 0
	s_cmp_gt_u32 s63, 29
	s_cbranch_scc0 .LBB0_684
	s_and_b64 vcc, exec, s[14:15]
	s_cbranch_vccz .LBB0_687
	s_barrier

; #define PG8_STAGE(bufoff, gbase, voff) do { _Pragma("unroll") for (int _i = 0; _i < 2; ++_i) \
;         __builtin_amdgcn_global_load_lds((const unsigned*)((const char*)(gbase) + (voff)[_i]), (PG8_LAS unsigned*)(lds + (bufoff) + ldsw + _i * 8192), 16, 0, 0); } while (0)
; #define PG8_LDA(dst, b, h) do { _Pragma("unroll") for (int m = 0; m < 4; ++m) _Pragma("unroll") for (int k = 0; k < 2; ++k) dst[m][k] = *(const PG8_LAS bf16x8*)(lds + PG8_SA(b, h) + aoff + m * 2048 + k * 1024); } while (0)
; #define PG8_LDB(dst, b, h) do { _Pragma("unroll") for (int n = 0; n < 2; ++n) _Pragma("unroll") for (int k = 0; k < 2; ++k) dst[n][k] = *(const PG8_LAS bf16x8*)(lds + PG8_SB(b, h) + boff + n * 2048 + k * 1024); } while (0)
; #define PG8_MMA(ai, bj, At, Bt) do { __builtin_amdgcn_s_setprio(1); _Pragma("unroll") for (int m = 0; m < 4; ++m) _Pragma("unroll") for (int n = 0; n < 2; ++n) _Pragma("unroll") for (int k = 0; k < 2; ++k) \
;         acc[ai][bj][m][n] = __builtin_amdgcn_mfma_f32_16x16x32_bf16(Bt[n][k], At[m][k], acc[ai][bj][m][n], 0, 0, 0); __builtin_amdgcn_s_setprio(0); } while (0)
; #define PG8_WAIT_V(n) asm volatile("s_waitcnt vmcnt(" #n ")" ::: "memory")
; #define PG8_WAIT_L(n) asm volatile("s_waitcnt lgkmcnt(" #n ")" ::: "memory")
; template <class Epi, class Sched, bool ALIGN_EPI = false, bool SP2 = false>
; __device__ __forceinline__ void gemm_phase(PG8_LAS unsigned char* lds, const Gemm g, const Sched& S, const Epi& E) {
;     ...
;             const bool last = (t == nt - 2);
;             const char* a1 = cA + (size_t)(t + 1) * kstep;
;             const char* a2 = last ? nA : cA + (size_t)(t + 2) * kstep; const char* b2 = last ? nB : cB + (size_t)(t + 2) * kstep;
;             const char* a3 = a2 + kstep; const char* b3 = b2 + kstep;
;             if (last && has_next) S.a_ready(nxt);
;             if constexpr (SP2) {
;             PG8_LDB(B0, 0, 0); PG8_LDB(B1, 0, 1); PG8_SCHED; PG8_LDA(At, 0, 0); PG8_STAGE(PG8_SA(1, 1), a1 + hstep, voffA);
;             PG8_WAIT_V(8); PG8_WAIT_L(0); PG8_BAR; PG8_MMA(0, 0, At, B0); PG8_MMA(0, 1, At, B1); PG8_BAR; PG8_SCHED;
;             PG8_LDA(At, 0, 1); PG8_STAGE(PG8_SB(0, 0), b2, voffB); PG8_STAGE(PG8_SB(0, 1), b2 + hstep, voffB); PG8_STAGE(PG8_SA(0, 0), a2, voffA);
;             PG8_WAIT_V(8); PG8_WAIT_L(0); PG8_BAR; PG8_MMA(1, 0, At, B0); PG8_MMA(1, 1, At, B1); PG8_BAR; PG8_SCHED;
.LBB0_757:
	s_add_u32 s28, s26, 0xffe00080
	s_addc_u32 s29, s27, -1
	s_add_i32 s60, 0, 0x10000
	s_cmpk_eq_i32 s72, 0x7c
	s_cselect_b32 s31, s21, s29
	s_cselect_b32 s30, s63, s28
	s_cselect_b32 s29, s19, s68
	s_cselect_b32 s28, s66, s67
	s_add_i32 s73, 0, 0x14000
	v_add_u32_e32 v124, s60, v239
	v_add_u32_e32 v148, s73, v239
	ds_read_b128 v[112:115], v124
	ds_read_b128 v[116:119], v124 offset:1024
	ds_read_b128 v[120:123], v124 offset:2048
	ds_read_b128 v[124:127], v124 offset:3072
	ds_read_b128 v[132:135], v148
	ds_read_b128 v[140:143], v148 offset:1024
	ds_read_b128 v[144:147], v148 offset:2048
	ds_read_b128 v[148:151], v148 offset:3072
	v_lshl_add_u64 v[212:213], s[26:27], 0, v[204:205]
	s_add_i32 m0, s38, 0xc000
	ds_read_b128 v[152:155], v241
	ds_read_b128 v[164:167], v241 offset:1024
	ds_read_b128 v[168:171], v241 offset:2048
	ds_read_b128 v[172:175], v241 offset:3072
	ds_read_b128 v[176:179], v241 offset:4096
	ds_read_b128 v[180:183], v241 offset:5120
	ds_read_b128 v[184:187], v241 offset:6144
	ds_read_b128 v[208:211], v241 offset:7168
	global_load_lds_dwordx4 v[212:213], off
	v_lshl_add_u64 v[212:213], s[26:27], 0, v[206:207]
	s_add_i32 m0, s38, 0xe000
	s_nop 0
	global_load_lds_dwordx4 v[212:213], off
	s_waitcnt vmcnt(8)
	s_waitcnt lgkmcnt(0)
	s_barrier
	v_mfma_f32_16x16x32_bf16 v[160:163], v[112:115], v[152:155], v[160:163]
	v_mfma_f32_16x16x32_bf16 v[156:159], v[120:123], v[152:155], v[156:159]
	v_mfma_f32_16x16x32_bf16 v[108:111], v[112:115], v[168:171], v[108:111]
	v_mfma_f32_16x16x32_bf16 v[104:107], v[120:123], v[168:171], v[104:107]
	v_mfma_f32_16x16x32_bf16 v[92:95], v[112:115], v[176:179], v[92:95]
	v_mfma_f32_16x16x32_bf16 v[88:91], v[120:123], v[176:179], v[88:91]
	v_mfma_f32_16x16x32_bf16 v[76:79], v[112:115], v[184:187], v[76:79]
	v_mfma_f32_16x16x32_bf16 v[72:75], v[120:123], v[184:187], v[72:75]
	v_mfma_f32_16x16x32_bf16 v[160:163], v[116:119], v[164:167], v[160:163]
	v_mfma_f32_16x16x32_bf16 v[156:159], v[124:127], v[164:167], v[156:159]
	v_mfma_f32_16x16x32_bf16 v[108:111], v[116:119], v[172:175], v[108:111]
	v_mfma_f32_16x16x32_bf16 v[104:107], v[124:127], v[172:175], v[104:107]
	v_mfma_f32_16x16x32_bf16 v[92:95], v[116:119], v[180:183], v[92:95]
	v_mfma_f32_16x16x32_bf16 v[88:91], v[124:127], v[180:183], v[88:91]
	v_mfma_f32_16x16x32_bf16 v[76:79], v[116:119], v[208:211], v[76:79]
	v_mfma_f32_16x16x32_bf16 v[72:75], v[124:127], v[208:211], v[72:75]
	v_mfma_f32_16x16x32_bf16 v[136:139], v[132:135], v[152:155], v[136:139]
	v_mfma_f32_16x16x32_bf16 v[128:131], v[144:147], v[152:155], v[128:131]
	v_mfma_f32_16x16x32_bf16 v[100:103], v[132:135], v[168:171], v[100:103]
	v_mfma_f32_16x16x32_bf16 v[96:99], v[144:147], v[168:171], v[96:99]
	v_mfma_f32_16x16x32_bf16 v[84:87], v[132:135], v[176:179], v[84:87]
	v_mfma_f32_16x16x32_bf16 v[80:83], v[144:147], v[176:179], v[80:83]
	v_mfma_f32_16x16x32_bf16 v[68:71], v[132:135], v[184:187], v[68:71]
	v_mfma_f32_16x16x32_bf16 v[64:67], v[144:147], v[184:187], v[64:67]
	v_mfma_f32_16x16x32_bf16 v[136:139], v[140:143], v[164:167], v[136:139]
	v_mfma_f32_16x16x32_bf16 v[128:131], v[148:151], v[164:167], v[128:131]
	v_mfma_f32_16x16x32_bf16 v[100:103], v[140:143], v[172:175], v[100:103]
	v_mfma_f32_16x16x32_bf16 v[96:99], v[148:151], v[172:175], v[96:99]
	v_mfma_f32_16x16x32_bf16 v[84:87], v[140:143], v[180:183], v[84:87]
	v_mfma_f32_16x16x32_bf16 v[80:83], v[148:151], v[180:183], v[80:83]
	v_mfma_f32_16x16x32_bf16 v[68:71], v[140:143], v[208:211], v[68:71]
	v_mfma_f32_16x16x32_bf16 v[64:67], v[148:151], v[208:211], v[64:67]
	s_barrier
	s_add_i32 s60, s60, s37
	v_lshl_add_u64 v[212:213], s[28:29], 0, v[188:189]
	s_mov_b32 m0, s60
	ds_read_b128 v[152:155], v241 offset:16384
	ds_read_b128 v[164:167], v241 offset:17408
	ds_read_b128 v[168:171], v241 offset:18432
	ds_read_b128 v[172:175], v241 offset:19456
	ds_read_b128 v[176:179], v241 offset:20480
	ds_read_b128 v[180:183], v241 offset:21504
	ds_read_b128 v[184:187], v241 offset:22528
	ds_read_b128 v[208:211], v241 offset:23552
	global_load_lds_dwordx4 v[212:213], off
	s_add_i32 m0, s60, 0x2000
	s_add_u32 s60, s28, 0x200000
	v_lshl_add_u64 v[214:215], s[28:29], 0, v[198:199]
	s_addc_u32 s61, s29, 0
	s_add_i32 s73, s73, s37
	global_load_lds_dwordx4 v[214:215], off
	v_lshl_add_u64 v[216:217], s[60:61], 0, v[188:189]
	s_mov_b32 m0, s73
	v_lshl_add_u64 v[218:219], s[30:31], 0, v[200:201]
	global_load_lds_dwordx4 v[216:217], off
	v_lshl_add_u64 v[216:217], s[60:61], 0, v[198:199]
	s_add_i32 m0, s73, 0x2000
	s_nop 0
	global_load_lds_dwordx4 v[216:217], off
	v_lshl_add_u64 v[216:217], s[30:31], 0, v[202:203]
	s_mov_b32 m0, s38
	s_nop 0
	global_load_lds_dwordx4 v[216:217], off
	s_mov_b32 m0, s39
	s_nop 0
	global_load_lds_dwordx4 v[218:219], off
	s_waitcnt vmcnt(8)
	s_waitcnt lgkmcnt(0)
	s_barrier
; #define PG8_STAGE(bufoff, gbase, voff) do { _Pragma("unroll") for (int _i = 0; _i < 2; ++_i) \
;         __builtin_amdgcn_global_load_lds((const unsigned*)((const char*)(gbase) + (voff)[_i]), (PG8_LAS unsigned*)(lds + (bufoff) + ldsw + _i * 8192), 16, 0, 0); } while (0)
; #define PG8_LDA(dst, b, h) do { _Pragma("unroll") for (int m = 0; m < 4; ++m) _Pragma("unroll") for (int k = 0; k < 2; ++k) dst[m][k] = *(const PG8_LAS bf16x8*)(lds + PG8_SA(b, h) + aoff + m * 2048 + k * 1024); } while (0)
; #define PG8_LDB(dst, b, h) do { _Pragma("unroll") for (int n = 0; n < 2; ++n) _Pragma("unroll") for (int k = 0; k < 2; ++k) dst[n][k] = *(const PG8_LAS bf16x8*)(lds + PG8_SB(b, h) + boff + n * 2048 + k * 1024); } while (0)
; #define PG8_MMA(ai, bj, At, Bt) do { __builtin_amdgcn_s_setprio(1); _Pragma("unroll") for (int m = 0; m < 4; ++m) _Pragma("unroll") for (int n = 0; n < 2; ++n) _Pragma("unroll") for (int k = 0; k < 2; ++k) \
;         acc[ai][bj][m][n] = __builtin_amdgcn_mfma_f32_16x16x32_bf16(Bt[n][k], At[m][k], acc[ai][bj][m][n], 0, 0, 0); __builtin_amdgcn_s_setprio(0); } while (0)
; #define PG8_WAIT_V(n) asm volatile("s_waitcnt vmcnt(" #n ")" ::: "memory")
; #define PG8_WAIT_L(n) asm volatile("s_waitcnt lgkmcnt(" #n ")" ::: "memory")
; #define PG8_BAR __builtin_amdgcn_s_barrier()
; #define PG8_SCHED __builtin_amdgcn_sched_barrier(0)
; template <class Epi, class Sched, bool ALIGN_EPI = false, bool SP2 = false>
; __device__ __forceinline__ void gemm_phase(PG8_LAS unsigned char* lds, const Gemm g, const Sched& S, const Epi& E) {
;     ...
;             PG8_WAIT_V(8); PG8_WAIT_L(0); PG8_BAR; PG8_MMA(1, 0, At, B0); PG8_MMA(1, 1, At, B1); PG8_BAR; PG8_SCHED;
;             PG8_LDB(B0, 1, 0); PG8_LDB(B1, 1, 1); PG8_SCHED; PG8_LDA(At, 1, 0); PG8_STAGE(PG8_SA(0, 1), a2 + hstep, voffA);
;             PG8_WAIT_V(8); PG8_WAIT_L(0); PG8_BAR; PG8_MMA(0, 0, At, B0); PG8_MMA(0, 1, At, B1); PG8_BAR; PG8_SCHED;
	v_mfma_f32_16x16x32_bf16 v[60:63], v[112:115], v[152:155], v[60:63]
	v_mfma_f32_16x16x32_bf16 v[56:59], v[120:123], v[152:155], v[56:59]
	v_mfma_f32_16x16x32_bf16 v[44:47], v[112:115], v[168:171], v[44:47]
	v_mfma_f32_16x16x32_bf16 v[40:43], v[120:123], v[168:171], v[40:43]
	v_mfma_f32_16x16x32_bf16 v[28:31], v[112:115], v[176:179], v[28:31]
	v_mfma_f32_16x16x32_bf16 v[24:27], v[120:123], v[176:179], v[24:27]
	v_mfma_f32_16x16x32_bf16 v[12:15], v[112:115], v[184:187], v[12:15]
	v_mfma_f32_16x16x32_bf16 v[8:11], v[120:123], v[184:187], v[8:11]
	v_mfma_f32_16x16x32_bf16 v[60:63], v[116:119], v[164:167], v[60:63]
	v_mfma_f32_16x16x32_bf16 v[56:59], v[124:127], v[164:167], v[56:59]
	v_mfma_f32_16x16x32_bf16 v[44:47], v[116:119], v[172:175], v[44:47]
	v_mfma_f32_16x16x32_bf16 v[40:43], v[124:127], v[172:175], v[40:43]
	v_mfma_f32_16x16x32_bf16 v[28:31], v[116:119], v[180:183], v[28:31]
	v_mfma_f32_16x16x32_bf16 v[24:27], v[124:127], v[180:183], v[24:27]
	v_mfma_f32_16x16x32_bf16 v[12:15], v[116:119], v[208:211], v[12:15]
	v_mfma_f32_16x16x32_bf16 v[8:11], v[124:127], v[208:211], v[8:11]
	v_mfma_f32_16x16x32_bf16 v[52:55], v[132:135], v[152:155], v[52:55]
	v_mfma_f32_16x16x32_bf16 v[48:51], v[144:147], v[152:155], v[48:51]
	v_mfma_f32_16x16x32_bf16 v[36:39], v[132:135], v[168:171], v[36:39]
	v_mfma_f32_16x16x32_bf16 v[32:35], v[144:147], v[168:171], v[32:35]
	v_mfma_f32_16x16x32_bf16 v[20:23], v[132:135], v[176:179], v[20:23]
	v_mfma_f32_16x16x32_bf16 v[16:19], v[144:147], v[176:179], v[16:19]
	v_mfma_f32_16x16x32_bf16 v[4:7], v[132:135], v[184:187], v[4:7]
	v_mfma_f32_16x16x32_bf16 v[0:3], v[144:147], v[184:187], v[0:3]
	v_mfma_f32_16x16x32_bf16 v[52:55], v[140:143], v[164:167], v[52:55]
	v_mfma_f32_16x16x32_bf16 v[48:51], v[148:151], v[164:167], v[48:51]
	v_mfma_f32_16x16x32_bf16 v[36:39], v[140:143], v[172:175], v[36:39]
	v_mfma_f32_16x16x32_bf16 v[32:35], v[148:151], v[172:175], v[32:35]
	v_mfma_f32_16x16x32_bf16 v[20:23], v[140:143], v[180:183], v[20:23]
	v_mfma_f32_16x16x32_bf16 v[16:19], v[148:151], v[180:183], v[16:19]
	v_mfma_f32_16x16x32_bf16 v[4:7], v[140:143], v[208:211], v[4:7]
	v_mfma_f32_16x16x32_bf16 v[0:3], v[148:151], v[208:211], v[0:3]
	s_barrier
	s_add_i32 s60, 0, 0x18000
	s_add_i32 s61, 0, 0x1c000
	v_add_u32_e32 v124, s60, v239
	v_add_u32_e32 v148, s61, v239
	ds_read_b128 v[112:115], v124
	ds_read_b128 v[116:119], v124 offset:1024
	ds_read_b128 v[120:123], v124 offset:2048
	ds_read_b128 v[124:127], v124 offset:3072
	ds_read_b128 v[132:135], v148
	ds_read_b128 v[140:143], v148 offset:1024
	ds_read_b128 v[144:147], v148 offset:2048
	ds_read_b128 v[148:151], v148 offset:3072
	s_add_u32 s30, s30, 0x200000
	s_addc_u32 s31, s31, 0
	s_mov_b32 m0, s40
	v_lshl_add_u64 v[220:221], s[30:31], 0, v[202:203]
	ds_read_b128 v[152:155], v241 offset:32768
	ds_read_b128 v[164:167], v241 offset:33792
	ds_read_b128 v[168:171], v241 offset:34816
	ds_read_b128 v[172:175], v241 offset:35840
	ds_read_b128 v[176:179], v241 offset:36864
	ds_read_b128 v[180:183], v241 offset:37888
	ds_read_b128 v[184:187], v241 offset:38912
	ds_read_b128 v[208:211], v241 offset:39936
	global_load_lds_dwordx4 v[220:221], off
	v_lshl_add_u64 v[220:221], s[30:31], 0, v[200:201]
	s_mov_b32 m0, s41
	s_nop 0
	global_load_lds_dwordx4 v[220:221], off
	s_waitcnt vmcnt(8)
	s_waitcnt lgkmcnt(0)
	s_barrier
	v_mfma_f32_16x16x32_bf16 v[160:163], v[112:115], v[152:155], v[160:163]
	v_mfma_f32_16x16x32_bf16 v[156:159], v[120:123], v[152:155], v[156:159]
	v_mfma_f32_16x16x32_bf16 v[108:111], v[112:115], v[168:171], v[108:111]
	v_mfma_f32_16x16x32_bf16 v[104:107], v[120:123], v[168:171], v[104:107]
	v_mfma_f32_16x16x32_bf16 v[92:95], v[112:115], v[176:179], v[92:95]
	v_mfma_f32_16x16x32_bf16 v[88:91], v[120:123], v[176:179], v[88:91]
	v_mfma_f32_16x16x32_bf16 v[76:79], v[112:115], v[184:187], v[76:79]
	v_mfma_f32_16x16x32_bf16 v[72:75], v[120:123], v[184:187], v[72:75]
	v_mfma_f32_16x16x32_bf16 v[160:163], v[116:119], v[164:167], v[160:163]
	v_mfma_f32_16x16x32_bf16 v[156:159], v[124:127], v[164:167], v[156:159]
	v_mfma_f32_16x16x32_bf16 v[108:111], v[116:119], v[172:175], v[108:111]
	v_mfma_f32_16x16x32_bf16 v[104:107], v[124:127], v[172:175], v[104:107]
	v_mfma_f32_16x16x32_bf16 v[92:95], v[116:119], v[180:183], v[92:95]
	v_mfma_f32_16x16x32_bf16 v[88:91], v[124:127], v[180:183], v[88:91]
	v_mfma_f32_16x16x32_bf16 v[76:79], v[116:119], v[208:211], v[76:79]
	v_mfma_f32_16x16x32_bf16 v[72:75], v[124:127], v[208:211], v[72:75]
	v_mfma_f32_16x16x32_bf16 v[136:139], v[132:135], v[152:155], v[136:139]
	v_mfma_f32_16x16x32_bf16 v[128:131], v[144:147], v[152:155], v[128:131]
	v_mfma_f32_16x16x32_bf16 v[100:103], v[132:135], v[168:171], v[100:103]
	v_mfma_f32_16x16x32_bf16 v[96:99], v[144:147], v[168:171], v[96:99]
	v_mfma_f32_16x16x32_bf16 v[84:87], v[132:135], v[176:179], v[84:87]
	v_mfma_f32_16x16x32_bf16 v[80:83], v[144:147], v[176:179], v[80:83]
	v_mfma_f32_16x16x32_bf16 v[68:71], v[132:135], v[184:187], v[68:71]
	v_mfma_f32_16x16x32_bf16 v[64:67], v[144:147], v[184:187], v[64:67]
	v_mfma_f32_16x16x32_bf16 v[136:139], v[140:143], v[164:167], v[136:139]
	v_mfma_f32_16x16x32_bf16 v[128:131], v[148:151], v[164:167], v[128:131]
	v_mfma_f32_16x16x32_bf16 v[100:103], v[140:143], v[172:175], v[100:103]
	v_mfma_f32_16x16x32_bf16 v[96:99], v[148:151], v[172:175], v[96:99]
	v_mfma_f32_16x16x32_bf16 v[84:87], v[140:143], v[180:183], v[84:87]
	v_mfma_f32_16x16x32_bf16 v[80:83], v[148:151], v[180:183], v[80:83]
	v_mfma_f32_16x16x32_bf16 v[68:71], v[140:143], v[208:211], v[68:71]
	v_mfma_f32_16x16x32_bf16 v[64:67], v[148:151], v[208:211], v[64:67]
	s_barrier
; #define PG8_STAGE(bufoff, gbase, voff) do { _Pragma("unroll") for (int _i = 0; _i < 2; ++_i) \
;         __builtin_amdgcn_global_load_lds((const unsigned*)((const char*)(gbase) + (voff)[_i]), (PG8_LAS unsigned*)(lds + (bufoff) + ldsw + _i * 8192), 16, 0, 0); } while (0)
; #define PG8_LDA(dst, b, h) do { _Pragma("unroll") for (int m = 0; m < 4; ++m) _Pragma("unroll") for (int k = 0; k < 2; ++k) dst[m][k] = *(const PG8_LAS bf16x8*)(lds + PG8_SA(b, h) + aoff + m * 2048 + k * 1024); } while (0)
; #define PG8_MMA(ai, bj, At, Bt) do { __builtin_amdgcn_s_setprio(1); _Pragma("unroll") for (int m = 0; m < 4; ++m) _Pragma("unroll") for (int n = 0; n < 2; ++n) _Pragma("unroll") for (int k = 0; k < 2; ++k) \
;         acc[ai][bj][m][n] = __builtin_amdgcn_mfma_f32_16x16x32_bf16(Bt[n][k], At[m][k], acc[ai][bj][m][n], 0, 0, 0); __builtin_amdgcn_s_setprio(0); } while (0)
; #define PG8_WAIT_V(n) asm volatile("s_waitcnt vmcnt(" #n ")" ::: "memory")
; #define PG8_WAIT_L(n) asm volatile("s_waitcnt lgkmcnt(" #n ")" ::: "memory")
; #define PG8_BAR __builtin_amdgcn_s_barrier()
; #define PG8_SCHED __builtin_amdgcn_sched_barrier(0)
; template <class Epi, class Sched, bool ALIGN_EPI = false, bool SP2 = false>
; __device__ __forceinline__ void gemm_phase(PG8_LAS unsigned char* lds, const Gemm g, const Sched& S, const Epi& E) {
;     ...
;             PG8_LDA(At, 1, 1); PG8_STAGE(PG8_SB(1, 0), b3, voffB); PG8_STAGE(PG8_SB(1, 1), b3 + hstep, voffB); PG8_STAGE(PG8_SA(1, 0), a3, voffA);
;             PG8_WAIT_V(8); PG8_WAIT_L(0); PG8_BAR; PG8_MMA(1, 0, At, B0); PG8_MMA(1, 1, At, B1); PG8_BAR; PG8_SCHED;
;     ...
;         if constexpr (ALIGN_EPI) { if (wr == 0) PG8_BAR; }
	s_add_i32 s30, s60, s37
	v_lshl_add_u64 v[212:213], v[212:213], 0, s[78:79]
	s_mov_b32 m0, s30
	ds_read_b128 v[152:155], v241 offset:49152
	ds_read_b128 v[164:167], v241 offset:50176
	ds_read_b128 v[168:171], v241 offset:51200
	ds_read_b128 v[172:175], v241 offset:52224
	ds_read_b128 v[176:179], v241 offset:53248
	ds_read_b128 v[180:183], v241 offset:54272
	ds_read_b128 v[184:187], v241 offset:55296
	ds_read_b128 v[208:211], v241 offset:56320
	global_load_lds_dwordx4 v[212:213], off
	s_add_i32 m0, s30, 0x2000
	s_add_u32 s28, s28, 0x200080
	v_lshl_add_u64 v[212:213], v[214:215], 0, s[78:79]
	s_addc_u32 s29, s29, 0
	s_add_i32 s30, s61, s37
	global_load_lds_dwordx4 v[212:213], off
	v_lshl_add_u64 v[212:213], s[28:29], 0, v[188:189]
	s_mov_b32 m0, s30
	s_nop 0
	global_load_lds_dwordx4 v[212:213], off
	v_lshl_add_u64 v[212:213], s[28:29], 0, v[198:199]
	s_add_i32 m0, s30, 0x2000
	s_nop 0
	global_load_lds_dwordx4 v[212:213], off
	v_lshl_add_u64 v[212:213], v[216:217], 0, s[78:79]
	s_mov_b32 m0, s44
	s_nop 0
	global_load_lds_dwordx4 v[212:213], off
	v_lshl_add_u64 v[212:213], v[218:219], 0, s[78:79]
	s_mov_b32 m0, s45
	s_nop 0
	global_load_lds_dwordx4 v[212:213], off
	s_waitcnt vmcnt(8)
	s_waitcnt lgkmcnt(0)
	s_barrier
	v_mfma_f32_16x16x32_bf16 v[60:63], v[112:115], v[152:155], v[60:63]
	v_mfma_f32_16x16x32_bf16 v[56:59], v[120:123], v[152:155], v[56:59]
	v_mfma_f32_16x16x32_bf16 v[44:47], v[112:115], v[168:171], v[44:47]
	v_mfma_f32_16x16x32_bf16 v[40:43], v[120:123], v[168:171], v[40:43]
	v_mfma_f32_16x16x32_bf16 v[28:31], v[112:115], v[176:179], v[28:31]
	v_mfma_f32_16x16x32_bf16 v[24:27], v[120:123], v[176:179], v[24:27]
	v_mfma_f32_16x16x32_bf16 v[12:15], v[112:115], v[184:187], v[12:15]
	v_mfma_f32_16x16x32_bf16 v[8:11], v[120:123], v[184:187], v[8:11]
	v_mfma_f32_16x16x32_bf16 v[60:63], v[116:119], v[164:167], v[60:63]
	v_mfma_f32_16x16x32_bf16 v[56:59], v[124:127], v[164:167], v[56:59]
	v_mfma_f32_16x16x32_bf16 v[44:47], v[116:119], v[172:175], v[44:47]
	v_mfma_f32_16x16x32_bf16 v[40:43], v[124:127], v[172:175], v[40:43]
	v_mfma_f32_16x16x32_bf16 v[28:31], v[116:119], v[180:183], v[28:31]
	v_mfma_f32_16x16x32_bf16 v[24:27], v[124:127], v[180:183], v[24:27]
	v_mfma_f32_16x16x32_bf16 v[12:15], v[116:119], v[208:211], v[12:15]
	v_mfma_f32_16x16x32_bf16 v[8:11], v[124:127], v[208:211], v[8:11]
	v_mfma_f32_16x16x32_bf16 v[52:55], v[132:135], v[152:155], v[52:55]
	v_mfma_f32_16x16x32_bf16 v[48:51], v[144:147], v[152:155], v[48:51]
	v_mfma_f32_16x16x32_bf16 v[36:39], v[132:135], v[168:171], v[36:39]
	v_mfma_f32_16x16x32_bf16 v[32:35], v[144:147], v[168:171], v[32:35]
	v_mfma_f32_16x16x32_bf16 v[20:23], v[132:135], v[176:179], v[20:23]
	v_mfma_f32_16x16x32_bf16 v[16:19], v[144:147], v[176:179], v[16:19]
	v_mfma_f32_16x16x32_bf16 v[4:7], v[132:135], v[184:187], v[4:7]
	v_mfma_f32_16x16x32_bf16 v[0:3], v[144:147], v[184:187], v[0:3]
	v_mfma_f32_16x16x32_bf16 v[52:55], v[140:143], v[164:167], v[52:55]
	v_mfma_f32_16x16x32_bf16 v[48:51], v[148:151], v[164:167], v[48:51]
	v_mfma_f32_16x16x32_bf16 v[36:39], v[140:143], v[172:175], v[36:39]
	v_mfma_f32_16x16x32_bf16 v[32:35], v[148:151], v[172:175], v[32:35]
	v_mfma_f32_16x16x32_bf16 v[20:23], v[140:143], v[180:183], v[20:23]
	v_mfma_f32_16x16x32_bf16 v[16:19], v[148:151], v[180:183], v[16:19]
	v_mfma_f32_16x16x32_bf16 v[4:7], v[140:143], v[208:211], v[4:7]
	v_mfma_f32_16x16x32_bf16 v[0:3], v[148:151], v[208:211], v[0:3]
	s_barrier
	s_add_i32 s72, s72, 2
	s_add_u32 s26, s26, 0x100
	s_addc_u32 s27, s27, 0
	s_add_u32 s67, s67, 0x100
	s_addc_u32 s68, s68, 0
	s_cmpk_gt_u32 s72, 0x7d
	s_cbranch_scc0 .LBB0_757
	s_and_b64 vcc, exec, s[16:17]
	s_cbranch_vccz .LBB0_760
	s_barrier

; #define PG8_STAGE(bufoff, gbase, voff) do { _Pragma("unroll") for (int _i = 0; _i < 2; ++_i) \
;         __builtin_amdgcn_global_load_lds((const unsigned*)((const char*)(gbase) + (voff)[_i]), (PG8_LAS unsigned*)(lds + (bufoff) + ldsw + _i * 8192), 16, 0, 0); } while (0)
; #define PG8_LDA(dst, b, h) do { _Pragma("unroll") for (int m = 0; m < 4; ++m) _Pragma("unroll") for (int k = 0; k < 2; ++k) dst[m][k] = *(const PG8_LAS bf16x8*)(lds + PG8_SA(b, h) + aoff + m * 2048 + k * 1024); } while (0)
; #define PG8_LDB(dst, b, h) do { _Pragma("unroll") for (int n = 0; n < 2; ++n) _Pragma("unroll") for (int k = 0; k < 2; ++k) dst[n][k] = *(const PG8_LAS bf16x8*)(lds + PG8_SB(b, h) + boff + n * 2048 + k * 1024); } while (0)
; #define PG8_MMA(ai, bj, At, Bt) do { __builtin_amdgcn_s_setprio(1); _Pragma("unroll") for (int m = 0; m < 4; ++m) _Pragma("unroll") for (int n = 0; n < 2; ++n) _Pragma("unroll") for (int k = 0; k < 2; ++k) \
;         acc[ai][bj][m][n] = __builtin_amdgcn_mfma_f32_16x16x32_bf16(Bt[n][k], At[m][k], acc[ai][bj][m][n], 0, 0, 0); __builtin_amdgcn_s_setprio(0); } while (0)
; #define PG8_WAIT_V(n) asm volatile("s_waitcnt vmcnt(" #n ")" ::: "memory")
; #define PG8_WAIT_L(n) asm volatile("s_waitcnt lgkmcnt(" #n ")" ::: "memory")
; template <class Epi, class Sched, bool ALIGN_EPI = false, bool SP2 = false>
; __device__ __forceinline__ void gemm_phase(PG8_LAS unsigned char* lds, const Gemm g, const Sched& S, const Epi& E) {
;     ...
;             const bool last = (t == nt - 2);
;             const char* a1 = cA + (size_t)(t + 1) * kstep;
;             const char* a2 = last ? nA : cA + (size_t)(t + 2) * kstep; const char* b2 = last ? nB : cB + (size_t)(t + 2) * kstep;
;             const char* a3 = a2 + kstep; const char* b3 = b2 + kstep;
;             if (last && has_next) S.a_ready(nxt);
;             if constexpr (SP2) {
;             PG8_LDB(B0, 0, 0); PG8_LDB(B1, 0, 1); PG8_SCHED; PG8_LDA(At, 0, 0); PG8_STAGE(PG8_SA(1, 1), a1 + hstep, voffA);
;             PG8_WAIT_V(8); PG8_WAIT_L(0); PG8_BAR; PG8_MMA(0, 0, At, B0); PG8_MMA(0, 1, At, B1); PG8_BAR; PG8_SCHED;
;             PG8_LDA(At, 0, 1); PG8_STAGE(PG8_SB(0, 0), b2, voffB); PG8_STAGE(PG8_SB(0, 1), b2 + hstep, voffB); PG8_STAGE(PG8_SA(0, 0), a2, voffA);
;             PG8_WAIT_V(8); PG8_WAIT_L(0); PG8_BAR; PG8_MMA(1, 0, At, B0); PG8_MMA(1, 1, At, B1); PG8_BAR; PG8_SCHED;
.LBB0_851:
	s_add_i32 s63, s24, 2
	s_add_u32 s60, s22, 0x80
	s_addc_u32 s25, s23, 0
	s_add_i32 s66, 0, 0x10000
	s_cmp_eq_u32 s39, s24
	s_cselect_b32 s25, s7, s25
	s_cselect_b32 s24, s6, s60
	s_cselect_b32 s61, s21, s62
	s_cselect_b32 s60, s20, s58
	s_add_i32 s67, 0, 0x14000
	v_add_u32_e32 v154, s66, v139
	v_add_u32_e32 v170, s67, v139
	ds_read_b128 v[142:145], v154
	ds_read_b128 v[146:149], v154 offset:1024
	ds_read_b128 v[150:153], v154 offset:2048
	ds_read_b128 v[154:157], v154 offset:3072
	ds_read_b128 v[158:161], v170
	ds_read_b128 v[162:165], v170 offset:1024
	ds_read_b128 v[166:169], v170 offset:2048
	ds_read_b128 v[170:173], v170 offset:3072
	v_lshl_add_u64 v[186:187], s[22:23], 0, v[134:135]
	s_add_i32 m0, s30, 0xc000
	ds_read_b128 v[174:177], v141
	ds_read_b128 v[178:181], v141 offset:1024
	ds_read_b128 v[182:185], v141 offset:2048
	ds_read_b128 v[198:201], v141 offset:3072
	ds_read_b128 v[202:205], v141 offset:4096
	ds_read_b128 v[206:209], v141 offset:5120
	ds_read_b128 v[210:213], v141 offset:6144
	ds_read_b128 v[214:217], v141 offset:7168
	global_load_lds_dwordx4 v[186:187], off
	v_lshl_add_u64 v[186:187], s[22:23], 0, v[136:137]
	s_add_i32 m0, s30, 0xe000
	s_nop 0
	global_load_lds_dwordx4 v[186:187], off
	s_waitcnt vmcnt(8)
	s_waitcnt lgkmcnt(0)
	s_barrier
	v_mfma_f32_16x16x32_bf16 v[120:123], v[142:145], v[174:177], v[120:123]
	v_mfma_f32_16x16x32_bf16 v[124:127], v[150:153], v[174:177], v[124:127]
	v_mfma_f32_16x16x32_bf16 v[108:111], v[142:145], v[182:185], v[108:111]
	v_mfma_f32_16x16x32_bf16 v[104:107], v[150:153], v[182:185], v[104:107]
	v_mfma_f32_16x16x32_bf16 v[92:95], v[142:145], v[202:205], v[92:95]
	v_mfma_f32_16x16x32_bf16 v[88:91], v[150:153], v[202:205], v[88:91]
	v_mfma_f32_16x16x32_bf16 v[76:79], v[142:145], v[210:213], v[76:79]
	v_mfma_f32_16x16x32_bf16 v[72:75], v[150:153], v[210:213], v[72:75]
	v_mfma_f32_16x16x32_bf16 v[120:123], v[146:149], v[178:181], v[120:123]
	v_mfma_f32_16x16x32_bf16 v[124:127], v[154:157], v[178:181], v[124:127]
	v_mfma_f32_16x16x32_bf16 v[108:111], v[146:149], v[198:201], v[108:111]
	v_mfma_f32_16x16x32_bf16 v[104:107], v[154:157], v[198:201], v[104:107]
	v_mfma_f32_16x16x32_bf16 v[92:95], v[146:149], v[206:209], v[92:95]
	v_mfma_f32_16x16x32_bf16 v[88:91], v[154:157], v[206:209], v[88:91]
	v_mfma_f32_16x16x32_bf16 v[76:79], v[146:149], v[214:217], v[76:79]
	v_mfma_f32_16x16x32_bf16 v[72:75], v[154:157], v[214:217], v[72:75]
	v_mfma_f32_16x16x32_bf16 v[116:119], v[158:161], v[174:177], v[116:119]
	v_mfma_f32_16x16x32_bf16 v[112:115], v[166:169], v[174:177], v[112:115]
	v_mfma_f32_16x16x32_bf16 v[100:103], v[158:161], v[182:185], v[100:103]
	v_mfma_f32_16x16x32_bf16 v[96:99], v[166:169], v[182:185], v[96:99]
	v_mfma_f32_16x16x32_bf16 v[84:87], v[158:161], v[202:205], v[84:87]
	v_mfma_f32_16x16x32_bf16 v[80:83], v[166:169], v[202:205], v[80:83]
	v_mfma_f32_16x16x32_bf16 v[68:71], v[158:161], v[210:213], v[68:71]
	v_mfma_f32_16x16x32_bf16 v[64:67], v[166:169], v[210:213], v[64:67]
	v_mfma_f32_16x16x32_bf16 v[116:119], v[162:165], v[178:181], v[116:119]
	v_mfma_f32_16x16x32_bf16 v[112:115], v[170:173], v[178:181], v[112:115]
	v_mfma_f32_16x16x32_bf16 v[100:103], v[162:165], v[198:201], v[100:103]
	v_mfma_f32_16x16x32_bf16 v[96:99], v[170:173], v[198:201], v[96:99]
	v_mfma_f32_16x16x32_bf16 v[84:87], v[162:165], v[206:209], v[84:87]
	v_mfma_f32_16x16x32_bf16 v[80:83], v[170:173], v[206:209], v[80:83]
	v_mfma_f32_16x16x32_bf16 v[68:71], v[162:165], v[214:217], v[68:71]
	v_mfma_f32_16x16x32_bf16 v[64:67], v[170:173], v[214:217], v[64:67]
	s_barrier
	s_add_i32 s66, s66, s29
	v_lshl_add_u64 v[186:187], s[60:61], 0, v[188:189]
	s_mov_b32 m0, s66
	ds_read_b128 v[174:177], v141 offset:16384
	ds_read_b128 v[178:181], v141 offset:17408
	ds_read_b128 v[182:185], v141 offset:18432
	ds_read_b128 v[198:201], v141 offset:19456
	ds_read_b128 v[202:205], v141 offset:20480
	ds_read_b128 v[206:209], v141 offset:21504
	ds_read_b128 v[210:213], v141 offset:22528
	ds_read_b128 v[214:217], v141 offset:23552
	global_load_lds_dwordx4 v[186:187], off
	s_add_i32 m0, s66, 0x2000
	v_lshl_add_u64 v[218:219], s[60:61], 0, v[128:129]
	s_add_u32 s60, s60, s0
	s_addc_u32 s61, s61, s1
	s_add_i32 s66, s67, s29
	global_load_lds_dwordx4 v[218:219], off
	v_lshl_add_u64 v[220:221], s[60:61], 0, v[188:189]
	s_mov_b32 m0, s66
	v_lshl_add_u64 v[222:223], s[60:61], 0, v[128:129]
	global_load_lds_dwordx4 v[220:221], off
	s_add_i32 m0, s66, 0x2000
	v_lshl_add_u64 v[224:225], s[24:25], 0, v[132:133]
	global_load_lds_dwordx4 v[222:223], off
	s_mov_b32 m0, s30
	v_lshl_add_u64 v[226:227], s[24:25], 0, v[130:131]
	global_load_lds_dwordx4 v[224:225], off
	s_mov_b32 m0, s31
	s_nop 0
	global_load_lds_dwordx4 v[226:227], off
	s_waitcnt vmcnt(8)
	s_waitcnt lgkmcnt(0)
	s_barrier
; #define PG8_STAGE(bufoff, gbase, voff) do { _Pragma("unroll") for (int _i = 0; _i < 2; ++_i) \
;         __builtin_amdgcn_global_load_lds((const unsigned*)((const char*)(gbase) + (voff)[_i]), (PG8_LAS unsigned*)(lds + (bufoff) + ldsw + _i * 8192), 16, 0, 0); } while (0)
; #define PG8_LDA(dst, b, h) do { _Pragma("unroll") for (int m = 0; m < 4; ++m) _Pragma("unroll") for (int k = 0; k < 2; ++k) dst[m][k] = *(const PG8_LAS bf16x8*)(lds + PG8_SA(b, h) + aoff + m * 2048 + k * 1024); } while (0)
; #define PG8_LDB(dst, b, h) do { _Pragma("unroll") for (int n = 0; n < 2; ++n) _Pragma("unroll") for (int k = 0; k < 2; ++k) dst[n][k] = *(const PG8_LAS bf16x8*)(lds + PG8_SB(b, h) + boff + n * 2048 + k * 1024); } while (0)
; #define PG8_MMA(ai, bj, At, Bt) do { __builtin_amdgcn_s_setprio(1); _Pragma("unroll") for (int m = 0; m < 4; ++m) _Pragma("unroll") for (int n = 0; n < 2; ++n) _Pragma("unroll") for (int k = 0; k < 2; ++k) \
;         acc[ai][bj][m][n] = __builtin_amdgcn_mfma_f32_16x16x32_bf16(Bt[n][k], At[m][k], acc[ai][bj][m][n], 0, 0, 0); __builtin_amdgcn_s_setprio(0); } while (0)
; #define PG8_WAIT_V(n) asm volatile("s_waitcnt vmcnt(" #n ")" ::: "memory")
; #define PG8_WAIT_L(n) asm volatile("s_waitcnt lgkmcnt(" #n ")" ::: "memory")
; #define PG8_BAR __builtin_amdgcn_s_barrier()
; #define PG8_SCHED __builtin_amdgcn_sched_barrier(0)
; template <class Epi, class Sched, bool ALIGN_EPI = false, bool SP2 = false>
; __device__ __forceinline__ void gemm_phase(PG8_LAS unsigned char* lds, const Gemm g, const Sched& S, const Epi& E) {
;     ...
;             PG8_WAIT_V(8); PG8_WAIT_L(0); PG8_BAR; PG8_MMA(1, 0, At, B0); PG8_MMA(1, 1, At, B1); PG8_BAR; PG8_SCHED;
;             PG8_LDB(B0, 1, 0); PG8_LDB(B1, 1, 1); PG8_SCHED; PG8_LDA(At, 1, 0); PG8_STAGE(PG8_SA(0, 1), a2 + hstep, voffA);
;             PG8_WAIT_V(8); PG8_WAIT_L(0); PG8_BAR; PG8_MMA(0, 0, At, B0); PG8_MMA(0, 1, At, B1); PG8_BAR; PG8_SCHED;
	v_mfma_f32_16x16x32_bf16 v[60:63], v[142:145], v[174:177], v[60:63]
	v_mfma_f32_16x16x32_bf16 v[56:59], v[150:153], v[174:177], v[56:59]
	v_mfma_f32_16x16x32_bf16 v[44:47], v[142:145], v[182:185], v[44:47]
	v_mfma_f32_16x16x32_bf16 v[40:43], v[150:153], v[182:185], v[40:43]
	v_mfma_f32_16x16x32_bf16 v[28:31], v[142:145], v[202:205], v[28:31]
	v_mfma_f32_16x16x32_bf16 v[24:27], v[150:153], v[202:205], v[24:27]
	v_mfma_f32_16x16x32_bf16 v[12:15], v[142:145], v[210:213], v[12:15]
	v_mfma_f32_16x16x32_bf16 v[8:11], v[150:153], v[210:213], v[8:11]
	v_mfma_f32_16x16x32_bf16 v[60:63], v[146:149], v[178:181], v[60:63]
	v_mfma_f32_16x16x32_bf16 v[56:59], v[154:157], v[178:181], v[56:59]
	v_mfma_f32_16x16x32_bf16 v[44:47], v[146:149], v[198:201], v[44:47]
	v_mfma_f32_16x16x32_bf16 v[40:43], v[154:157], v[198:201], v[40:43]
	v_mfma_f32_16x16x32_bf16 v[28:31], v[146:149], v[206:209], v[28:31]
	v_mfma_f32_16x16x32_bf16 v[24:27], v[154:157], v[206:209], v[24:27]
	v_mfma_f32_16x16x32_bf16 v[12:15], v[146:149], v[214:217], v[12:15]
	v_mfma_f32_16x16x32_bf16 v[8:11], v[154:157], v[214:217], v[8:11]
	v_mfma_f32_16x16x32_bf16 v[52:55], v[158:161], v[174:177], v[52:55]
	v_mfma_f32_16x16x32_bf16 v[48:51], v[166:169], v[174:177], v[48:51]
	v_mfma_f32_16x16x32_bf16 v[36:39], v[158:161], v[182:185], v[36:39]
	v_mfma_f32_16x16x32_bf16 v[32:35], v[166:169], v[182:185], v[32:35]
	v_mfma_f32_16x16x32_bf16 v[20:23], v[158:161], v[202:205], v[20:23]
	v_mfma_f32_16x16x32_bf16 v[16:19], v[166:169], v[202:205], v[16:19]
	v_mfma_f32_16x16x32_bf16 v[4:7], v[158:161], v[210:213], v[4:7]
	v_mfma_f32_16x16x32_bf16 v[0:3], v[166:169], v[210:213], v[0:3]
	v_mfma_f32_16x16x32_bf16 v[52:55], v[162:165], v[178:181], v[52:55]
	v_mfma_f32_16x16x32_bf16 v[48:51], v[170:173], v[178:181], v[48:51]
	v_mfma_f32_16x16x32_bf16 v[36:39], v[162:165], v[198:201], v[36:39]
	v_mfma_f32_16x16x32_bf16 v[32:35], v[170:173], v[198:201], v[32:35]
	v_mfma_f32_16x16x32_bf16 v[20:23], v[162:165], v[206:209], v[20:23]
	v_mfma_f32_16x16x32_bf16 v[16:19], v[170:173], v[206:209], v[16:19]
	v_mfma_f32_16x16x32_bf16 v[4:7], v[162:165], v[214:217], v[4:7]
	v_mfma_f32_16x16x32_bf16 v[0:3], v[170:173], v[214:217], v[0:3]
	s_barrier
	s_add_i32 s60, 0, 0x18000
	s_add_i32 s61, 0, 0x1c000
	v_add_u32_e32 v154, s60, v139
	v_add_u32_e32 v170, s61, v139
	ds_read_b128 v[142:145], v154
	ds_read_b128 v[146:149], v154 offset:1024
	ds_read_b128 v[150:153], v154 offset:2048
	ds_read_b128 v[154:157], v154 offset:3072
	ds_read_b128 v[158:161], v170
	ds_read_b128 v[162:165], v170 offset:1024
	ds_read_b128 v[166:169], v170 offset:2048
	ds_read_b128 v[170:173], v170 offset:3072
	s_add_u32 s24, s24, s0
	s_addc_u32 s25, s25, s1
	s_mov_b32 m0, s34
	v_lshl_add_u64 v[228:229], s[24:25], 0, v[132:133]
	ds_read_b128 v[174:177], v141 offset:32768
	ds_read_b128 v[178:181], v141 offset:33792
	ds_read_b128 v[182:185], v141 offset:34816
	ds_read_b128 v[198:201], v141 offset:35840
	ds_read_b128 v[202:205], v141 offset:36864
	ds_read_b128 v[206:209], v141 offset:37888
	ds_read_b128 v[210:213], v141 offset:38912
	ds_read_b128 v[214:217], v141 offset:39936
	global_load_lds_dwordx4 v[228:229], off
	v_lshl_add_u64 v[228:229], s[24:25], 0, v[130:131]
	s_mov_b32 m0, s35
	s_nop 0
	global_load_lds_dwordx4 v[228:229], off
	s_waitcnt vmcnt(8)
	s_waitcnt lgkmcnt(0)
	s_barrier
	v_mfma_f32_16x16x32_bf16 v[120:123], v[142:145], v[174:177], v[120:123]
	v_mfma_f32_16x16x32_bf16 v[124:127], v[150:153], v[174:177], v[124:127]
	v_mfma_f32_16x16x32_bf16 v[108:111], v[142:145], v[182:185], v[108:111]
	v_mfma_f32_16x16x32_bf16 v[104:107], v[150:153], v[182:185], v[104:107]
	v_mfma_f32_16x16x32_bf16 v[92:95], v[142:145], v[202:205], v[92:95]
	v_mfma_f32_16x16x32_bf16 v[88:91], v[150:153], v[202:205], v[88:91]
	v_mfma_f32_16x16x32_bf16 v[76:79], v[142:145], v[210:213], v[76:79]
	v_mfma_f32_16x16x32_bf16 v[72:75], v[150:153], v[210:213], v[72:75]
	v_mfma_f32_16x16x32_bf16 v[120:123], v[146:149], v[178:181], v[120:123]
	v_mfma_f32_16x16x32_bf16 v[124:127], v[154:157], v[178:181], v[124:127]
	v_mfma_f32_16x16x32_bf16 v[108:111], v[146:149], v[198:201], v[108:111]
	v_mfma_f32_16x16x32_bf16 v[104:107], v[154:157], v[198:201], v[104:107]
	v_mfma_f32_16x16x32_bf16 v[92:95], v[146:149], v[206:209], v[92:95]
	v_mfma_f32_16x16x32_bf16 v[88:91], v[154:157], v[206:209], v[88:91]
	v_mfma_f32_16x16x32_bf16 v[76:79], v[146:149], v[214:217], v[76:79]
	v_mfma_f32_16x16x32_bf16 v[72:75], v[154:157], v[214:217], v[72:75]
	v_mfma_f32_16x16x32_bf16 v[116:119], v[158:161], v[174:177], v[116:119]
	v_mfma_f32_16x16x32_bf16 v[112:115], v[166:169], v[174:177], v[112:115]
	v_mfma_f32_16x16x32_bf16 v[100:103], v[158:161], v[182:185], v[100:103]
	v_mfma_f32_16x16x32_bf16 v[96:99], v[166:169], v[182:185], v[96:99]
	v_mfma_f32_16x16x32_bf16 v[84:87], v[158:161], v[202:205], v[84:87]
	v_mfma_f32_16x16x32_bf16 v[80:83], v[166:169], v[202:205], v[80:83]
	v_mfma_f32_16x16x32_bf16 v[68:71], v[158:161], v[210:213], v[68:71]
	v_mfma_f32_16x16x32_bf16 v[64:67], v[166:169], v[210:213], v[64:67]
	v_mfma_f32_16x16x32_bf16 v[116:119], v[162:165], v[178:181], v[116:119]
	v_mfma_f32_16x16x32_bf16 v[112:115], v[170:173], v[178:181], v[112:115]
	v_mfma_f32_16x16x32_bf16 v[100:103], v[162:165], v[198:201], v[100:103]
	v_mfma_f32_16x16x32_bf16 v[96:99], v[170:173], v[198:201], v[96:99]
	v_mfma_f32_16x16x32_bf16 v[84:87], v[162:165], v[206:209], v[84:87]
	v_mfma_f32_16x16x32_bf16 v[80:83], v[170:173], v[206:209], v[80:83]
	v_mfma_f32_16x16x32_bf16 v[68:71], v[162:165], v[214:217], v[68:71]
	v_mfma_f32_16x16x32_bf16 v[64:67], v[170:173], v[214:217], v[64:67]
	s_barrier
; #define PG8_STAGE(bufoff, gbase, voff) do { _Pragma("unroll") for (int _i = 0; _i < 2; ++_i) \
;         __builtin_amdgcn_global_load_lds((const unsigned*)((const char*)(gbase) + (voff)[_i]), (PG8_LAS unsigned*)(lds + (bufoff) + ldsw + _i * 8192), 16, 0, 0); } while (0)
; #define PG8_LDA(dst, b, h) do { _Pragma("unroll") for (int m = 0; m < 4; ++m) _Pragma("unroll") for (int k = 0; k < 2; ++k) dst[m][k] = *(const PG8_LAS bf16x8*)(lds + PG8_SA(b, h) + aoff + m * 2048 + k * 1024); } while (0)
; #define PG8_MMA(ai, bj, At, Bt) do { __builtin_amdgcn_s_setprio(1); _Pragma("unroll") for (int m = 0; m < 4; ++m) _Pragma("unroll") for (int n = 0; n < 2; ++n) _Pragma("unroll") for (int k = 0; k < 2; ++k) \
;         acc[ai][bj][m][n] = __builtin_amdgcn_mfma_f32_16x16x32_bf16(Bt[n][k], At[m][k], acc[ai][bj][m][n], 0, 0, 0); __builtin_amdgcn_s_setprio(0); } while (0)
; #define PG8_WAIT_V(n) asm volatile("s_waitcnt vmcnt(" #n ")" ::: "memory")
; #define PG8_WAIT_L(n) asm volatile("s_waitcnt lgkmcnt(" #n ")" ::: "memory")
; #define PG8_BAR __builtin_amdgcn_s_barrier()
; #define PG8_SCHED __builtin_amdgcn_sched_barrier(0)
; template <class Epi, class Sched, bool ALIGN_EPI = false, bool SP2 = false>
; __device__ __forceinline__ void gemm_phase(PG8_LAS unsigned char* lds, const Gemm g, const Sched& S, const Epi& E) {
;     ...
;         for (int t = 0; t < nt; t += 2) {
;     ...
;             PG8_LDA(At, 1, 1); PG8_STAGE(PG8_SB(1, 0), b3, voffB); PG8_STAGE(PG8_SB(1, 1), b3 + hstep, voffB); PG8_STAGE(PG8_SA(1, 0), a3, voffA);
;             PG8_WAIT_V(8); PG8_WAIT_L(0); PG8_BAR; PG8_MMA(1, 0, At, B0); PG8_MMA(1, 1, At, B1); PG8_BAR; PG8_SCHED;
	s_add_i32 s24, s60, s29
	v_lshl_add_u64 v[186:187], v[186:187], 0, s[78:79]
	s_mov_b32 m0, s24
	ds_read_b128 v[174:177], v141 offset:49152
	ds_read_b128 v[178:181], v141 offset:50176
	ds_read_b128 v[182:185], v141 offset:51200
	ds_read_b128 v[198:201], v141 offset:52224
	ds_read_b128 v[202:205], v141 offset:53248
	ds_read_b128 v[206:209], v141 offset:54272
	ds_read_b128 v[210:213], v141 offset:55296
	ds_read_b128 v[214:217], v141 offset:56320
	global_load_lds_dwordx4 v[186:187], off
	v_lshl_add_u64 v[186:187], v[218:219], 0, s[78:79]
	s_add_i32 m0, s24, 0x2000
	s_add_i32 s24, s61, s29
	global_load_lds_dwordx4 v[186:187], off
	v_lshl_add_u64 v[186:187], v[220:221], 0, s[78:79]
	s_mov_b32 m0, s24
	s_nop 0
	global_load_lds_dwordx4 v[186:187], off
	v_lshl_add_u64 v[186:187], v[222:223], 0, s[78:79]
	s_add_i32 m0, s24, 0x2000
	s_nop 0
	global_load_lds_dwordx4 v[186:187], off
	v_lshl_add_u64 v[186:187], v[224:225], 0, s[78:79]
	s_mov_b32 m0, s37
	s_nop 0
	global_load_lds_dwordx4 v[186:187], off
	v_lshl_add_u64 v[186:187], v[226:227], 0, s[78:79]
	s_mov_b32 m0, s38
	s_nop 0
	global_load_lds_dwordx4 v[186:187], off
	s_waitcnt vmcnt(8)
	s_waitcnt lgkmcnt(0)
	s_barrier
	v_mfma_f32_16x16x32_bf16 v[60:63], v[142:145], v[174:177], v[60:63]
	v_mfma_f32_16x16x32_bf16 v[56:59], v[150:153], v[174:177], v[56:59]
	v_mfma_f32_16x16x32_bf16 v[44:47], v[142:145], v[182:185], v[44:47]
	v_mfma_f32_16x16x32_bf16 v[40:43], v[150:153], v[182:185], v[40:43]
	v_mfma_f32_16x16x32_bf16 v[28:31], v[142:145], v[202:205], v[28:31]
	v_mfma_f32_16x16x32_bf16 v[24:27], v[150:153], v[202:205], v[24:27]
	v_mfma_f32_16x16x32_bf16 v[12:15], v[142:145], v[210:213], v[12:15]
	v_mfma_f32_16x16x32_bf16 v[8:11], v[150:153], v[210:213], v[8:11]
	v_mfma_f32_16x16x32_bf16 v[60:63], v[146:149], v[178:181], v[60:63]
	v_mfma_f32_16x16x32_bf16 v[56:59], v[154:157], v[178:181], v[56:59]
	v_mfma_f32_16x16x32_bf16 v[44:47], v[146:149], v[198:201], v[44:47]
	v_mfma_f32_16x16x32_bf16 v[40:43], v[154:157], v[198:201], v[40:43]
	v_mfma_f32_16x16x32_bf16 v[28:31], v[146:149], v[206:209], v[28:31]
	v_mfma_f32_16x16x32_bf16 v[24:27], v[154:157], v[206:209], v[24:27]
	v_mfma_f32_16x16x32_bf16 v[12:15], v[146:149], v[214:217], v[12:15]
	v_mfma_f32_16x16x32_bf16 v[8:11], v[154:157], v[214:217], v[8:11]
	v_mfma_f32_16x16x32_bf16 v[52:55], v[158:161], v[174:177], v[52:55]
	v_mfma_f32_16x16x32_bf16 v[48:51], v[166:169], v[174:177], v[48:51]
	v_mfma_f32_16x16x32_bf16 v[36:39], v[158:161], v[182:185], v[36:39]
	v_mfma_f32_16x16x32_bf16 v[32:35], v[166:169], v[182:185], v[32:35]
	v_mfma_f32_16x16x32_bf16 v[20:23], v[158:161], v[202:205], v[20:23]
	v_mfma_f32_16x16x32_bf16 v[16:19], v[166:169], v[202:205], v[16:19]
	v_mfma_f32_16x16x32_bf16 v[4:7], v[158:161], v[210:213], v[4:7]
	v_mfma_f32_16x16x32_bf16 v[0:3], v[166:169], v[210:213], v[0:3]
	v_mfma_f32_16x16x32_bf16 v[52:55], v[162:165], v[178:181], v[52:55]
	v_mfma_f32_16x16x32_bf16 v[48:51], v[170:173], v[178:181], v[48:51]
	v_mfma_f32_16x16x32_bf16 v[36:39], v[162:165], v[198:201], v[36:39]
	v_mfma_f32_16x16x32_bf16 v[32:35], v[170:173], v[198:201], v[32:35]
	v_mfma_f32_16x16x32_bf16 v[20:23], v[162:165], v[206:209], v[20:23]
	v_mfma_f32_16x16x32_bf16 v[16:19], v[170:173], v[206:209], v[16:19]
	v_mfma_f32_16x16x32_bf16 v[4:7], v[162:165], v[214:217], v[4:7]
	v_mfma_f32_16x16x32_bf16 v[0:3], v[170:173], v[214:217], v[0:3]
	s_barrier
	s_add_u32 s22, s22, 0x100
	s_addc_u32 s23, s23, 0
	s_add_u32 s58, s58, 0x100
	s_addc_u32 s62, s62, 0
	s_cmp_ge_i32 s63, s36
	s_mov_b32 s24, s63
	s_cbranch_scc0 .LBB0_851
	s_mov_b32 s67, 0x20000
	s_mov_b32 s66, 0x30000

; #define PG8_STAGE(bufoff, gbase, voff) do { _Pragma("unroll") for (int _i = 0; _i < 2; ++_i) \
;         __builtin_amdgcn_global_load_lds((const unsigned*)((const char*)(gbase) + (voff)[_i]), (PG8_LAS unsigned*)(lds + (bufoff) + ldsw + _i * 8192), 16, 0, 0); } while (0)
; #define PG8_LDA(dst, b, h) do { _Pragma("unroll") for (int m = 0; m < 4; ++m) _Pragma("unroll") for (int k = 0; k < 2; ++k) dst[m][k] = *(const PG8_LAS bf16x8*)(lds + PG8_SA(b, h) + aoff + m * 2048 + k * 1024); } while (0)
; #define PG8_LDB(dst, b, h) do { _Pragma("unroll") for (int n = 0; n < 2; ++n) _Pragma("unroll") for (int k = 0; k < 2; ++k) dst[n][k] = *(const PG8_LAS bf16x8*)(lds + PG8_SB(b, h) + boff + n * 2048 + k * 1024); } while (0)
; #define PG8_MMA(ai, bj, At, Bt) do { __builtin_amdgcn_s_setprio(1); _Pragma("unroll") for (int m = 0; m < 4; ++m) _Pragma("unroll") for (int n = 0; n < 2; ++n) _Pragma("unroll") for (int k = 0; k < 2; ++k) \
;         acc[ai][bj][m][n] = __builtin_amdgcn_mfma_f32_16x16x32_bf16(Bt[n][k], At[m][k], acc[ai][bj][m][n], 0, 0, 0); __builtin_amdgcn_s_setprio(0); } while (0)
; #define PG8_WAIT_V(n) asm volatile("s_waitcnt vmcnt(" #n ")" ::: "memory")
; #define PG8_WAIT_L(n) asm volatile("s_waitcnt lgkmcnt(" #n ")" ::: "memory")
; template <class Epi, class Sched, bool ALIGN_EPI = false, bool SP2 = false>
; __device__ __forceinline__ void gemm_phase(PG8_LAS unsigned char* lds, const Gemm g, const Sched& S, const Epi& E) {
;     ...
;             const bool last = (t == nt - 2);
;             const char* a1 = cA + (size_t)(t + 1) * kstep;
;             const char* a2 = last ? nA : cA + (size_t)(t + 2) * kstep; const char* b2 = last ? nB : cB + (size_t)(t + 2) * kstep;
;             const char* a3 = a2 + kstep; const char* b3 = b2 + kstep;
;             if (last && has_next) S.a_ready(nxt);
;             if constexpr (SP2) {
;             PG8_LDB(B0, 0, 0); PG8_LDB(B1, 0, 1); PG8_SCHED; PG8_LDA(At, 0, 0); PG8_STAGE(PG8_SA(1, 1), a1 + hstep, voffA);
;             PG8_WAIT_V(8); PG8_WAIT_L(0); PG8_BAR; PG8_MMA(0, 0, At, B0); PG8_MMA(0, 1, At, B1); PG8_BAR; PG8_SCHED;
;             PG8_LDA(At, 0, 1); PG8_STAGE(PG8_SB(0, 0), b2, voffB); PG8_STAGE(PG8_SB(0, 1), b2 + hstep, voffB); PG8_STAGE(PG8_SA(0, 0), a2, voffA);
;             PG8_WAIT_V(8); PG8_WAIT_L(0); PG8_BAR; PG8_MMA(1, 0, At, B0); PG8_MMA(1, 1, At, B1); PG8_BAR; PG8_SCHED;
.LBB0_872:
	s_add_u32 s36, s34, 0xfff80080
	s_addc_u32 s37, s35, -1
	s_add_i32 s60, 0, 0x10000
	s_cmp_eq_u32 s72, 28
	s_cselect_b32 s39, s23, s37
	s_cselect_b32 s38, s29, s36
	s_cselect_b32 s37, s21, s68
	s_cselect_b32 s36, s66, s67
	s_add_i32 s73, 0, 0x14000
	v_add_u32_e32 v132, s60, v225
	v_add_u32_e32 v156, s73, v225
	ds_read_b128 v[112:115], v132
	ds_read_b128 v[116:119], v132 offset:1024
	ds_read_b128 v[120:123], v132 offset:2048
	ds_read_b128 v[132:135], v132 offset:3072
	ds_read_b128 v[140:143], v156
	ds_read_b128 v[148:151], v156 offset:1024
	ds_read_b128 v[152:155], v156 offset:2048
	ds_read_b128 v[156:159], v156 offset:3072
	v_lshl_add_u64 v[212:213], s[34:35], 0, v[186:187]
	s_add_i32 m0, s2, 0xc000
	ds_read_b128 v[160:163], v227
	ds_read_b128 v[164:167], v227 offset:1024
	ds_read_b128 v[168:171], v227 offset:2048
	ds_read_b128 v[172:175], v227 offset:3072
	ds_read_b128 v[176:179], v227 offset:4096
	ds_read_b128 v[200:203], v227 offset:5120
	ds_read_b128 v[204:207], v227 offset:6144
	ds_read_b128 v[208:211], v227 offset:7168
	global_load_lds_dwordx4 v[212:213], off
	v_lshl_add_u64 v[212:213], s[34:35], 0, v[198:199]
	s_add_i32 m0, s2, 0xe000
	s_nop 0
	global_load_lds_dwordx4 v[212:213], off
	s_waitcnt vmcnt(8)
	s_waitcnt lgkmcnt(0)
	s_barrier
	v_mfma_f32_16x16x32_bf16 v[144:147], v[112:115], v[160:163], v[144:147]
	v_mfma_f32_16x16x32_bf16 v[136:139], v[120:123], v[160:163], v[136:139]
	v_mfma_f32_16x16x32_bf16 v[108:111], v[112:115], v[168:171], v[108:111]
	v_mfma_f32_16x16x32_bf16 v[104:107], v[120:123], v[168:171], v[104:107]
	v_mfma_f32_16x16x32_bf16 v[92:95], v[112:115], v[176:179], v[92:95]
	v_mfma_f32_16x16x32_bf16 v[88:91], v[120:123], v[176:179], v[88:91]
	v_mfma_f32_16x16x32_bf16 v[76:79], v[112:115], v[204:207], v[76:79]
	v_mfma_f32_16x16x32_bf16 v[72:75], v[120:123], v[204:207], v[72:75]
	v_mfma_f32_16x16x32_bf16 v[144:147], v[116:119], v[164:167], v[144:147]
	v_mfma_f32_16x16x32_bf16 v[136:139], v[132:135], v[164:167], v[136:139]
	v_mfma_f32_16x16x32_bf16 v[108:111], v[116:119], v[172:175], v[108:111]
	v_mfma_f32_16x16x32_bf16 v[104:107], v[132:135], v[172:175], v[104:107]
	v_mfma_f32_16x16x32_bf16 v[92:95], v[116:119], v[200:203], v[92:95]
	v_mfma_f32_16x16x32_bf16 v[88:91], v[132:135], v[200:203], v[88:91]
	v_mfma_f32_16x16x32_bf16 v[76:79], v[116:119], v[208:211], v[76:79]
	v_mfma_f32_16x16x32_bf16 v[72:75], v[132:135], v[208:211], v[72:75]
	v_mfma_f32_16x16x32_bf16 v[128:131], v[140:143], v[160:163], v[128:131]
	v_mfma_f32_16x16x32_bf16 v[124:127], v[152:155], v[160:163], v[124:127]
	v_mfma_f32_16x16x32_bf16 v[100:103], v[140:143], v[168:171], v[100:103]
	v_mfma_f32_16x16x32_bf16 v[96:99], v[152:155], v[168:171], v[96:99]
	v_mfma_f32_16x16x32_bf16 v[84:87], v[140:143], v[176:179], v[84:87]
	v_mfma_f32_16x16x32_bf16 v[80:83], v[152:155], v[176:179], v[80:83]
	v_mfma_f32_16x16x32_bf16 v[68:71], v[140:143], v[204:207], v[68:71]
	v_mfma_f32_16x16x32_bf16 v[64:67], v[152:155], v[204:207], v[64:67]
	v_mfma_f32_16x16x32_bf16 v[128:131], v[148:151], v[164:167], v[128:131]
	v_mfma_f32_16x16x32_bf16 v[124:127], v[156:159], v[164:167], v[124:127]
	v_mfma_f32_16x16x32_bf16 v[100:103], v[148:151], v[172:175], v[100:103]
	v_mfma_f32_16x16x32_bf16 v[96:99], v[156:159], v[172:175], v[96:99]
	v_mfma_f32_16x16x32_bf16 v[84:87], v[148:151], v[200:203], v[84:87]
	v_mfma_f32_16x16x32_bf16 v[80:83], v[156:159], v[200:203], v[80:83]
	v_mfma_f32_16x16x32_bf16 v[68:71], v[148:151], v[208:211], v[68:71]
	v_mfma_f32_16x16x32_bf16 v[64:67], v[156:159], v[208:211], v[64:67]
	s_barrier
	s_add_i32 s60, s60, s44
	v_lshl_add_u64 v[212:213], s[36:37], 0, v[188:189]
	s_mov_b32 m0, s60
	ds_read_b128 v[160:163], v227 offset:16384
	ds_read_b128 v[164:167], v227 offset:17408
	ds_read_b128 v[168:171], v227 offset:18432
	ds_read_b128 v[172:175], v227 offset:19456
	ds_read_b128 v[176:179], v227 offset:20480
	ds_read_b128 v[200:203], v227 offset:21504
	ds_read_b128 v[204:207], v227 offset:22528
	ds_read_b128 v[208:211], v227 offset:23552
	global_load_lds_dwordx4 v[212:213], off
	s_add_i32 m0, s60, 0x2000
	s_add_u32 s60, s36, 0x80000
	v_lshl_add_u64 v[214:215], s[36:37], 0, v[180:181]
	s_addc_u32 s61, s37, 0
	s_add_i32 s73, s73, s44
	global_load_lds_dwordx4 v[214:215], off
	v_lshl_add_u64 v[216:217], s[60:61], 0, v[188:189]
	s_mov_b32 m0, s73
	v_lshl_add_u64 v[218:219], s[38:39], 0, v[182:183]
	global_load_lds_dwordx4 v[216:217], off
	v_lshl_add_u64 v[216:217], s[60:61], 0, v[180:181]
	s_add_i32 m0, s73, 0x2000
	s_nop 0
	global_load_lds_dwordx4 v[216:217], off
	v_lshl_add_u64 v[216:217], s[38:39], 0, v[184:185]
	s_mov_b32 m0, s2
	s_nop 0
	global_load_lds_dwordx4 v[216:217], off
	s_mov_b32 m0, s31
	s_nop 0
	global_load_lds_dwordx4 v[218:219], off
	s_waitcnt vmcnt(8)
	s_waitcnt lgkmcnt(0)
	s_barrier
; #define PG8_STAGE(bufoff, gbase, voff) do { _Pragma("unroll") for (int _i = 0; _i < 2; ++_i) \
;         __builtin_amdgcn_global_load_lds((const unsigned*)((const char*)(gbase) + (voff)[_i]), (PG8_LAS unsigned*)(lds + (bufoff) + ldsw + _i * 8192), 16, 0, 0); } while (0)
; #define PG8_LDA(dst, b, h) do { _Pragma("unroll") for (int m = 0; m < 4; ++m) _Pragma("unroll") for (int k = 0; k < 2; ++k) dst[m][k] = *(const PG8_LAS bf16x8*)(lds + PG8_SA(b, h) + aoff + m * 2048 + k * 1024); } while (0)
; #define PG8_LDB(dst, b, h) do { _Pragma("unroll") for (int n = 0; n < 2; ++n) _Pragma("unroll") for (int k = 0; k < 2; ++k) dst[n][k] = *(const PG8_LAS bf16x8*)(lds + PG8_SB(b, h) + boff + n * 2048 + k * 1024); } while (0)
; #define PG8_MMA(ai, bj, At, Bt) do { __builtin_amdgcn_s_setprio(1); _Pragma("unroll") for (int m = 0; m < 4; ++m) _Pragma("unroll") for (int n = 0; n < 2; ++n) _Pragma("unroll") for (int k = 0; k < 2; ++k) \
;         acc[ai][bj][m][n] = __builtin_amdgcn_mfma_f32_16x16x32_bf16(Bt[n][k], At[m][k], acc[ai][bj][m][n], 0, 0, 0); __builtin_amdgcn_s_setprio(0); } while (0)
; #define PG8_WAIT_V(n) asm volatile("s_waitcnt vmcnt(" #n ")" ::: "memory")
; #define PG8_WAIT_L(n) asm volatile("s_waitcnt lgkmcnt(" #n ")" ::: "memory")
; #define PG8_BAR __builtin_amdgcn_s_barrier()
; #define PG8_SCHED __builtin_amdgcn_sched_barrier(0)
; template <class Epi, class Sched, bool ALIGN_EPI = false, bool SP2 = false>
; __device__ __forceinline__ void gemm_phase(PG8_LAS unsigned char* lds, const Gemm g, const Sched& S, const Epi& E) {
;     ...
;             PG8_WAIT_V(8); PG8_WAIT_L(0); PG8_BAR; PG8_MMA(1, 0, At, B0); PG8_MMA(1, 1, At, B1); PG8_BAR; PG8_SCHED;
;             PG8_LDB(B0, 1, 0); PG8_LDB(B1, 1, 1); PG8_SCHED; PG8_LDA(At, 1, 0); PG8_STAGE(PG8_SA(0, 1), a2 + hstep, voffA);
;             PG8_WAIT_V(8); PG8_WAIT_L(0); PG8_BAR; PG8_MMA(0, 0, At, B0); PG8_MMA(0, 1, At, B1); PG8_BAR; PG8_SCHED;
	v_mfma_f32_16x16x32_bf16 v[60:63], v[112:115], v[160:163], v[60:63]
	v_mfma_f32_16x16x32_bf16 v[56:59], v[120:123], v[160:163], v[56:59]
	v_mfma_f32_16x16x32_bf16 v[44:47], v[112:115], v[168:171], v[44:47]
	v_mfma_f32_16x16x32_bf16 v[40:43], v[120:123], v[168:171], v[40:43]
	v_mfma_f32_16x16x32_bf16 v[28:31], v[112:115], v[176:179], v[28:31]
	v_mfma_f32_16x16x32_bf16 v[24:27], v[120:123], v[176:179], v[24:27]
	v_mfma_f32_16x16x32_bf16 v[12:15], v[112:115], v[204:207], v[12:15]
	v_mfma_f32_16x16x32_bf16 v[8:11], v[120:123], v[204:207], v[8:11]
	v_mfma_f32_16x16x32_bf16 v[60:63], v[116:119], v[164:167], v[60:63]
	v_mfma_f32_16x16x32_bf16 v[56:59], v[132:135], v[164:167], v[56:59]
	v_mfma_f32_16x16x32_bf16 v[44:47], v[116:119], v[172:175], v[44:47]
	v_mfma_f32_16x16x32_bf16 v[40:43], v[132:135], v[172:175], v[40:43]
	v_mfma_f32_16x16x32_bf16 v[28:31], v[116:119], v[200:203], v[28:31]
	v_mfma_f32_16x16x32_bf16 v[24:27], v[132:135], v[200:203], v[24:27]
	v_mfma_f32_16x16x32_bf16 v[12:15], v[116:119], v[208:211], v[12:15]
	v_mfma_f32_16x16x32_bf16 v[8:11], v[132:135], v[208:211], v[8:11]
	v_mfma_f32_16x16x32_bf16 v[52:55], v[140:143], v[160:163], v[52:55]
	v_mfma_f32_16x16x32_bf16 v[48:51], v[152:155], v[160:163], v[48:51]
	v_mfma_f32_16x16x32_bf16 v[36:39], v[140:143], v[168:171], v[36:39]
	v_mfma_f32_16x16x32_bf16 v[32:35], v[152:155], v[168:171], v[32:35]
	v_mfma_f32_16x16x32_bf16 v[20:23], v[140:143], v[176:179], v[20:23]
	v_mfma_f32_16x16x32_bf16 v[16:19], v[152:155], v[176:179], v[16:19]
	v_mfma_f32_16x16x32_bf16 v[4:7], v[140:143], v[204:207], v[4:7]
	v_mfma_f32_16x16x32_bf16 v[0:3], v[152:155], v[204:207], v[0:3]
	v_mfma_f32_16x16x32_bf16 v[52:55], v[148:151], v[164:167], v[52:55]
	v_mfma_f32_16x16x32_bf16 v[48:51], v[156:159], v[164:167], v[48:51]
	v_mfma_f32_16x16x32_bf16 v[36:39], v[148:151], v[172:175], v[36:39]
	v_mfma_f32_16x16x32_bf16 v[32:35], v[156:159], v[172:175], v[32:35]
	v_mfma_f32_16x16x32_bf16 v[20:23], v[148:151], v[200:203], v[20:23]
	v_mfma_f32_16x16x32_bf16 v[16:19], v[156:159], v[200:203], v[16:19]
	v_mfma_f32_16x16x32_bf16 v[4:7], v[148:151], v[208:211], v[4:7]
	v_mfma_f32_16x16x32_bf16 v[0:3], v[156:159], v[208:211], v[0:3]
	s_barrier
	s_add_i32 s60, 0, 0x18000
	s_add_i32 s61, 0, 0x1c000
	v_add_u32_e32 v132, s60, v225
	v_add_u32_e32 v156, s61, v225
	ds_read_b128 v[112:115], v132
	ds_read_b128 v[116:119], v132 offset:1024
	ds_read_b128 v[120:123], v132 offset:2048
	ds_read_b128 v[132:135], v132 offset:3072
	ds_read_b128 v[140:143], v156
	ds_read_b128 v[148:151], v156 offset:1024
	ds_read_b128 v[152:155], v156 offset:2048
	ds_read_b128 v[156:159], v156 offset:3072
	s_add_u32 s38, s38, 0x80000
	s_addc_u32 s39, s39, 0
	s_mov_b32 m0, s45
	v_lshl_add_u64 v[220:221], s[38:39], 0, v[184:185]
	ds_read_b128 v[160:163], v227 offset:32768
	ds_read_b128 v[164:167], v227 offset:33792
	ds_read_b128 v[168:171], v227 offset:34816
	ds_read_b128 v[172:175], v227 offset:35840
	ds_read_b128 v[176:179], v227 offset:36864
	ds_read_b128 v[200:203], v227 offset:37888
	ds_read_b128 v[204:207], v227 offset:38912
	ds_read_b128 v[208:211], v227 offset:39936
	global_load_lds_dwordx4 v[220:221], off
	v_lshl_add_u64 v[220:221], s[38:39], 0, v[182:183]
	s_mov_b32 m0, s52
	s_nop 0
	global_load_lds_dwordx4 v[220:221], off
	s_waitcnt vmcnt(8)
	s_waitcnt lgkmcnt(0)
	s_barrier
	v_mfma_f32_16x16x32_bf16 v[144:147], v[112:115], v[160:163], v[144:147]
	v_mfma_f32_16x16x32_bf16 v[136:139], v[120:123], v[160:163], v[136:139]
	v_mfma_f32_16x16x32_bf16 v[108:111], v[112:115], v[168:171], v[108:111]
	v_mfma_f32_16x16x32_bf16 v[104:107], v[120:123], v[168:171], v[104:107]
	v_mfma_f32_16x16x32_bf16 v[92:95], v[112:115], v[176:179], v[92:95]
	v_mfma_f32_16x16x32_bf16 v[88:91], v[120:123], v[176:179], v[88:91]
	v_mfma_f32_16x16x32_bf16 v[76:79], v[112:115], v[204:207], v[76:79]
	v_mfma_f32_16x16x32_bf16 v[72:75], v[120:123], v[204:207], v[72:75]
	v_mfma_f32_16x16x32_bf16 v[144:147], v[116:119], v[164:167], v[144:147]
	v_mfma_f32_16x16x32_bf16 v[136:139], v[132:135], v[164:167], v[136:139]
	v_mfma_f32_16x16x32_bf16 v[108:111], v[116:119], v[172:175], v[108:111]
	v_mfma_f32_16x16x32_bf16 v[104:107], v[132:135], v[172:175], v[104:107]
	v_mfma_f32_16x16x32_bf16 v[92:95], v[116:119], v[200:203], v[92:95]
	v_mfma_f32_16x16x32_bf16 v[88:91], v[132:135], v[200:203], v[88:91]
	v_mfma_f32_16x16x32_bf16 v[76:79], v[116:119], v[208:211], v[76:79]
	v_mfma_f32_16x16x32_bf16 v[72:75], v[132:135], v[208:211], v[72:75]
	v_mfma_f32_16x16x32_bf16 v[128:131], v[140:143], v[160:163], v[128:131]
	v_mfma_f32_16x16x32_bf16 v[124:127], v[152:155], v[160:163], v[124:127]
	v_mfma_f32_16x16x32_bf16 v[100:103], v[140:143], v[168:171], v[100:103]
	v_mfma_f32_16x16x32_bf16 v[96:99], v[152:155], v[168:171], v[96:99]
	v_mfma_f32_16x16x32_bf16 v[84:87], v[140:143], v[176:179], v[84:87]
	v_mfma_f32_16x16x32_bf16 v[80:83], v[152:155], v[176:179], v[80:83]
	v_mfma_f32_16x16x32_bf16 v[68:71], v[140:143], v[204:207], v[68:71]
	v_mfma_f32_16x16x32_bf16 v[64:67], v[152:155], v[204:207], v[64:67]
	v_mfma_f32_16x16x32_bf16 v[128:131], v[148:151], v[164:167], v[128:131]
	v_mfma_f32_16x16x32_bf16 v[124:127], v[156:159], v[164:167], v[124:127]
	v_mfma_f32_16x16x32_bf16 v[100:103], v[148:151], v[172:175], v[100:103]
	v_mfma_f32_16x16x32_bf16 v[96:99], v[156:159], v[172:175], v[96:99]
	v_mfma_f32_16x16x32_bf16 v[84:87], v[148:151], v[200:203], v[84:87]
	v_mfma_f32_16x16x32_bf16 v[80:83], v[156:159], v[200:203], v[80:83]
	v_mfma_f32_16x16x32_bf16 v[68:71], v[148:151], v[208:211], v[68:71]
	v_mfma_f32_16x16x32_bf16 v[64:67], v[156:159], v[208:211], v[64:67]
	s_barrier
; #define PG8_STAGE(bufoff, gbase, voff) do { _Pragma("unroll") for (int _i = 0; _i < 2; ++_i) \
;         __builtin_amdgcn_global_load_lds((const unsigned*)((const char*)(gbase) + (voff)[_i]), (PG8_LAS unsigned*)(lds + (bufoff) + ldsw + _i * 8192), 16, 0, 0); } while (0)
; #define PG8_LDA(dst, b, h) do { _Pragma("unroll") for (int m = 0; m < 4; ++m) _Pragma("unroll") for (int k = 0; k < 2; ++k) dst[m][k] = *(const PG8_LAS bf16x8*)(lds + PG8_SA(b, h) + aoff + m * 2048 + k * 1024); } while (0)
; #define PG8_MMA(ai, bj, At, Bt) do { __builtin_amdgcn_s_setprio(1); _Pragma("unroll") for (int m = 0; m < 4; ++m) _Pragma("unroll") for (int n = 0; n < 2; ++n) _Pragma("unroll") for (int k = 0; k < 2; ++k) \
;         acc[ai][bj][m][n] = __builtin_amdgcn_mfma_f32_16x16x32_bf16(Bt[n][k], At[m][k], acc[ai][bj][m][n], 0, 0, 0); __builtin_amdgcn_s_setprio(0); } while (0)
; #define PG8_WAIT_V(n) asm volatile("s_waitcnt vmcnt(" #n ")" ::: "memory")
; #define PG8_WAIT_L(n) asm volatile("s_waitcnt lgkmcnt(" #n ")" ::: "memory")
; #define PG8_BAR __builtin_amdgcn_s_barrier()
; #define PG8_SCHED __builtin_amdgcn_sched_barrier(0)
; template <class Epi, class Sched, bool ALIGN_EPI = false, bool SP2 = false>
; __device__ __forceinline__ void gemm_phase(PG8_LAS unsigned char* lds, const Gemm g, const Sched& S, const Epi& E) {
;     ...
;             PG8_LDA(At, 1, 1); PG8_STAGE(PG8_SB(1, 0), b3, voffB); PG8_STAGE(PG8_SB(1, 1), b3 + hstep, voffB); PG8_STAGE(PG8_SA(1, 0), a3, voffA);
;             PG8_WAIT_V(8); PG8_WAIT_L(0); PG8_BAR; PG8_MMA(1, 0, At, B0); PG8_MMA(1, 1, At, B1); PG8_BAR; PG8_SCHED;
;     ...
;         if constexpr (ALIGN_EPI) { if (wr == 0) PG8_BAR; }
	s_add_i32 s38, s60, s44
	v_lshl_add_u64 v[212:213], v[212:213], 0, s[78:79]
	s_mov_b32 m0, s38
	ds_read_b128 v[160:163], v227 offset:49152
	ds_read_b128 v[164:167], v227 offset:50176
	ds_read_b128 v[168:171], v227 offset:51200
	ds_read_b128 v[172:175], v227 offset:52224
	ds_read_b128 v[176:179], v227 offset:53248
	ds_read_b128 v[200:203], v227 offset:54272
	ds_read_b128 v[204:207], v227 offset:55296
	ds_read_b128 v[208:211], v227 offset:56320
	global_load_lds_dwordx4 v[212:213], off
	s_add_i32 m0, s38, 0x2000
	s_add_u32 s36, s36, 0x80080
	v_lshl_add_u64 v[212:213], v[214:215], 0, s[78:79]
	s_addc_u32 s37, s37, 0
	s_add_i32 s38, s61, s44
	global_load_lds_dwordx4 v[212:213], off
	v_lshl_add_u64 v[212:213], s[36:37], 0, v[188:189]
	s_mov_b32 m0, s38
	s_nop 0
	global_load_lds_dwordx4 v[212:213], off
	v_lshl_add_u64 v[212:213], s[36:37], 0, v[180:181]
	s_add_i32 m0, s38, 0x2000
	s_nop 0
	global_load_lds_dwordx4 v[212:213], off
	v_lshl_add_u64 v[212:213], v[216:217], 0, s[78:79]
	s_mov_b32 m0, s58
	s_nop 0
	global_load_lds_dwordx4 v[212:213], off
	v_lshl_add_u64 v[212:213], v[218:219], 0, s[78:79]
	s_mov_b32 m0, s62
	s_nop 0
	global_load_lds_dwordx4 v[212:213], off
	s_waitcnt vmcnt(8)
	s_waitcnt lgkmcnt(0)
	s_barrier
	v_mfma_f32_16x16x32_bf16 v[60:63], v[112:115], v[160:163], v[60:63]
	v_mfma_f32_16x16x32_bf16 v[56:59], v[120:123], v[160:163], v[56:59]
	v_mfma_f32_16x16x32_bf16 v[44:47], v[112:115], v[168:171], v[44:47]
	v_mfma_f32_16x16x32_bf16 v[40:43], v[120:123], v[168:171], v[40:43]
	v_mfma_f32_16x16x32_bf16 v[28:31], v[112:115], v[176:179], v[28:31]
	v_mfma_f32_16x16x32_bf16 v[24:27], v[120:123], v[176:179], v[24:27]
	v_mfma_f32_16x16x32_bf16 v[12:15], v[112:115], v[204:207], v[12:15]
	v_mfma_f32_16x16x32_bf16 v[8:11], v[120:123], v[204:207], v[8:11]
	v_mfma_f32_16x16x32_bf16 v[60:63], v[116:119], v[164:167], v[60:63]
	v_mfma_f32_16x16x32_bf16 v[56:59], v[132:135], v[164:167], v[56:59]
	v_mfma_f32_16x16x32_bf16 v[44:47], v[116:119], v[172:175], v[44:47]
	v_mfma_f32_16x16x32_bf16 v[40:43], v[132:135], v[172:175], v[40:43]
	v_mfma_f32_16x16x32_bf16 v[28:31], v[116:119], v[200:203], v[28:31]
	v_mfma_f32_16x16x32_bf16 v[24:27], v[132:135], v[200:203], v[24:27]
	v_mfma_f32_16x16x32_bf16 v[12:15], v[116:119], v[208:211], v[12:15]
	v_mfma_f32_16x16x32_bf16 v[8:11], v[132:135], v[208:211], v[8:11]
	v_mfma_f32_16x16x32_bf16 v[52:55], v[140:143], v[160:163], v[52:55]
	v_mfma_f32_16x16x32_bf16 v[48:51], v[152:155], v[160:163], v[48:51]
	v_mfma_f32_16x16x32_bf16 v[36:39], v[140:143], v[168:171], v[36:39]
	v_mfma_f32_16x16x32_bf16 v[32:35], v[152:155], v[168:171], v[32:35]
	v_mfma_f32_16x16x32_bf16 v[20:23], v[140:143], v[176:179], v[20:23]
	v_mfma_f32_16x16x32_bf16 v[16:19], v[152:155], v[176:179], v[16:19]
	v_mfma_f32_16x16x32_bf16 v[4:7], v[140:143], v[204:207], v[4:7]
	v_mfma_f32_16x16x32_bf16 v[0:3], v[152:155], v[204:207], v[0:3]
	v_mfma_f32_16x16x32_bf16 v[52:55], v[148:151], v[164:167], v[52:55]
	v_mfma_f32_16x16x32_bf16 v[48:51], v[156:159], v[164:167], v[48:51]
	v_mfma_f32_16x16x32_bf16 v[36:39], v[148:151], v[172:175], v[36:39]
	v_mfma_f32_16x16x32_bf16 v[32:35], v[156:159], v[172:175], v[32:35]
	v_mfma_f32_16x16x32_bf16 v[20:23], v[148:151], v[200:203], v[20:23]
	v_mfma_f32_16x16x32_bf16 v[16:19], v[156:159], v[200:203], v[16:19]
	v_mfma_f32_16x16x32_bf16 v[4:7], v[148:151], v[208:211], v[4:7]
	v_mfma_f32_16x16x32_bf16 v[0:3], v[156:159], v[208:211], v[0:3]
	s_barrier
	s_add_i32 s72, s72, 2
	s_add_u32 s34, s34, 0x100
	s_addc_u32 s35, s35, 0
	s_add_u32 s67, s67, 0x100
	s_addc_u32 s68, s68, 0
	s_cmp_gt_u32 s72, 29
	s_cbranch_scc0 .LBB0_872
	v_mov_b32_e32 v196, 0x2000
	s_and_b64 vcc, exec, s[18:19]
	s_cbranch_vccz .LBB0_875
	s_barrier
